# accumulator zeroing folded into the first K-iteration: peeled loop copy whose first MFMA per accumulator tile takes C=0 (all five K-loops), 64 VALU zeroing ops per unit removed
# baseline (speedup 1.0000x reference)
; template <class Epi, class Sched, bool ALIGN_EPI = false, bool SP2 = false, bool F8 = false>
; __device__ __forceinline__ void gemm_phase(PG8_LAS unsigned char* lds, const Gemm g, const Sched& S, const Epi& E) {
;     ...
;         const char* nA = has_next ? PG8_ABASE(nxt.pm) : cA; const char* nB = has_next ? (const char*)g.Bt + (size_t)nxt.pn * tstep : cB;
;     ...
; #pragma unroll
;         for (int a = 0; a < 2; ++a)
; #pragma unroll
;             for (int b = 0; b < 2; ++b)
; #pragma unroll
;                 for (int m = 0; m < 4; ++m)
; #pragma unroll
;                     for (int n = 0; n < 2; ++n) acc[a][b][m][n] = (f32x4){0.f, 0.f, 0.f, 0.f};
;         cur = nxt; cA = nA; cB = nB; ++ui;
.LBB0_254:
	s_ashr_i32 s79, s78, 31
	s_lshl_b64 s[54:55], s[78:79], 20
	s_add_u32 s80, s30, s54
	s_addc_u32 s81, s31, s55
	s_and_b64 s[54:55], s[10:11], exec
	s_cselect_b32 s13, s81, s85
	s_cselect_b32 s53, s80, s84
	s_ashr_i32 s77, s76, 31
	s_lshl_b64 s[54:55], s[76:77], 20
	s_add_u32 s82, s58, s54
	s_addc_u32 s83, s59, s55
	s_and_b64 s[54:55], s[10:11], exec
	s_cselect_b32 s77, s83, s87
	s_cselect_b32 s79, s82, s86
	s_add_u32 s84, s84, 0x80080
	s_addc_u32 s85, s85, 0
	s_add_u32 vcc_lo, s86, 0x100
	s_addc_u32 vcc_hi, s87, 0
	s_mov_b32 s54, -2
	s_cmp_lg_u64 s[64:65], 0
	s_cbranch_scc1 .Lk0_Yz
	s_branch .Lk0_Xz

; #define PG8_STAGE(bufoff, gbase, voff) do { _Pragma("unroll") for (int _i = 0; _i < 2; ++_i) \
;         __builtin_amdgcn_global_load_lds((const unsigned*)((const char*)(gbase) + (voff)[_i]), (PG8_LAS unsigned*)(lds + (bufoff) + ldsw + _i * 8192), 16, 0, 0); } while (0)
; #define PG8_LDA(dst, b, h) do { _Pragma("unroll") for (int m = 0; m < 4; ++m) _Pragma("unroll") for (int k = 0; k < 2; ++k) dst[m][k] = *(const PG8_LAS bf16x8*)(lds + PG8_SA(b, h) + aoff + m * 2048 + k * 1024); } while (0)
; #define PG8_LDB(dst, b, h) do { _Pragma("unroll") for (int n = 0; n < 2; ++n) _Pragma("unroll") for (int k = 0; k < 2; ++k) dst[n][k] = *(const PG8_LAS bf16x8*)(lds + PG8_SB(b, h) + boff + n * 2048 + k * 1024); } while (0)
; #define PG8_WAIT_V(n) asm volatile("s_waitcnt vmcnt(" #n ")" ::: "memory")
; #define PG8_WAIT_L(n) asm volatile("s_waitcnt lgkmcnt(" #n ")" ::: "memory")
; #define PG8_BAR __builtin_amdgcn_s_barrier()
; #define PG8_SCHED __builtin_amdgcn_sched_barrier(0)
; template <class Epi, class Sched, bool ALIGN_EPI = false, bool SP2 = false, bool F8 = false>
; __device__ __forceinline__ void gemm_phase(PG8_LAS unsigned char* lds, const Gemm g, const Sched& S, const Epi& E) {
;     ...
;             const bool last = (t == nt - 2);
;             const char* a1 = cA + (size_t)(t + 1) * kstep;
;             const char* a2 = last ? nA : cA + (size_t)(t + 2) * kstep; const char* b2 = last ? nB : cB + (size_t)(t + 2) * kstep;
;             const char* a3 = a2 + kstep; const char* b3 = b2 + kstep;
;             if (last && has_next) S.a_ready(nxt);
;             if constexpr (SP2) {
;             PG8_LDB(B0, 0, 0); PG8_LDB(B1, 0, 1); PG8_SCHED; PG8_LDA(At, 0, 0); PG8_STAGE(PG8_SA(1, 1), a1 + hstepA, voffA);
;             PG8_WAIT_V(8); PG8_WAIT_L(0); PG8_BAR; PG8_MMA(0, 0, At, B0); PG8_MMA(0, 1, At, B1); PG8_BAR; PG8_SCHED;
.Lk0_Y:
	ds_read_b128 v[130:133], v225
	ds_read_b128 v[134:137], v225 offset:1024
	ds_read_b128 v[138:141], v225 offset:2048
	ds_read_b128 v[142:145], v225 offset:3072
	ds_read_b128 v[146:149], v226
	ds_read_b128 v[150:153], v226 offset:1024
	ds_read_b128 v[154:157], v226 offset:2048
	ds_read_b128 v[158:161], v226 offset:3072
	s_add_u32 s24, s84, 0xfff80080
	s_addc_u32 s25, s85, -1
	s_cmp_eq_u32 s54, 28
	s_cselect_b32 s89, s13, s25
	s_cselect_b32 s88, s53, s24
	s_cselect_b32 s87, s77, vcc_hi
	s_cselect_b32 s86, s79, vcc_lo
	s_add_i32 m0, s95, 0xc000
	ds_read_b128 v[192:195], v227
	ds_read_b128 v[196:199], v227 offset:1024
	ds_read_b128 v[200:203], v227 offset:2048
	ds_read_b128 v[204:207], v227 offset:3072
	ds_read_b128 v[230:233], v227 offset:4096
	ds_read_b128 v[234:237], v227 offset:5120
	ds_read_b128 v[238:241], v227 offset:6144
	ds_read_b128 v[242:245], v227 offset:7168
	global_load_lds_dwordx4 v186, s[84:85]
	s_add_i32 m0, s95, 0xe000
	s_nop 0
	global_load_lds_dwordx4 v188, s[84:85]
	s_waitcnt vmcnt(8)
	s_waitcnt lgkmcnt(0)
	s_barrier
	s_setprio 3
	s_waitcnt lgkmcnt(0)
	v_mfma_f32_16x16x32_bf16 v[126:129], v[130:133], v[192:195], v[126:129]
	v_mfma_f32_16x16x32_bf16 v[122:125], v[138:141], v[192:195], v[122:125]
	v_mfma_f32_16x16x32_bf16 v[110:113], v[130:133], v[200:203], v[110:113]
	v_mfma_f32_16x16x32_bf16 v[106:109], v[138:141], v[200:203], v[106:109]
	v_mfma_f32_16x16x32_bf16 v[94:97], v[130:133], v[230:233], v[94:97]
	v_mfma_f32_16x16x32_bf16 v[90:93], v[138:141], v[230:233], v[90:93]
	v_mfma_f32_16x16x32_bf16 v[78:81], v[130:133], v[238:241], v[78:81]
	v_mfma_f32_16x16x32_bf16 v[74:77], v[138:141], v[238:241], v[74:77]
	v_mfma_f32_16x16x32_bf16 v[126:129], v[134:137], v[196:199], v[126:129]
	v_mfma_f32_16x16x32_bf16 v[122:125], v[142:145], v[196:199], v[122:125]
	v_mfma_f32_16x16x32_bf16 v[110:113], v[134:137], v[204:207], v[110:113]
	v_mfma_f32_16x16x32_bf16 v[106:109], v[142:145], v[204:207], v[106:109]
	v_mfma_f32_16x16x32_bf16 v[94:97], v[134:137], v[234:237], v[94:97]
	v_mfma_f32_16x16x32_bf16 v[90:93], v[142:145], v[234:237], v[90:93]
	v_mfma_f32_16x16x32_bf16 v[78:81], v[134:137], v[242:245], v[78:81]
	v_mfma_f32_16x16x32_bf16 v[74:77], v[142:145], v[242:245], v[74:77]


; #define PG8_STAGE(bufoff, gbase, voff) do { _Pragma("unroll") for (int _i = 0; _i < 2; ++_i) \
;         __builtin_amdgcn_global_load_lds((const unsigned*)((const char*)(gbase) + (voff)[_i]), (PG8_LAS unsigned*)(lds + (bufoff) + ldsw + _i * 8192), 16, 0, 0); } while (0)
; #define PG8_LDA(dst, b, h) do { _Pragma("unroll") for (int m = 0; m < 4; ++m) _Pragma("unroll") for (int k = 0; k < 2; ++k) dst[m][k] = *(const PG8_LAS bf16x8*)(lds + PG8_SA(b, h) + aoff + m * 2048 + k * 1024); } while (0)
; #define PG8_WAIT_V(n) asm volatile("s_waitcnt vmcnt(" #n ")" ::: "memory")
; #define PG8_WAIT_L(n) asm volatile("s_waitcnt lgkmcnt(" #n ")" ::: "memory")
; #define PG8_BAR __builtin_amdgcn_s_barrier()
; #define PG8_SCHED __builtin_amdgcn_sched_barrier(0)
; template <class Epi, class Sched, bool ALIGN_EPI = false, bool SP2 = false, bool F8 = false>
; __device__ __forceinline__ void gemm_phase(PG8_LAS unsigned char* lds, const Gemm g, const Sched& S, const Epi& E) {
;     ...
;             PG8_WAIT_V(8); PG8_WAIT_L(0); PG8_BAR; PG8_MMA(0, 0, At, B0); PG8_MMA(0, 1, At, B1); PG8_BAR; PG8_SCHED;
;             PG8_LDA(At, 0, 1); PG8_STAGE(PG8_SB(0, 0), b2, voffB); PG8_STAGE(PG8_SB(0, 1), b2 + hstep, voffB); PG8_STAGE(PG8_SA(0, 0), a2, voffA);
;             PG8_WAIT_V(8); PG8_WAIT_L(0); PG8_BAR; PG8_MMA(1, 0, At, B0); PG8_MMA(1, 1, At, B1); PG8_BAR; PG8_SCHED;
	v_mfma_f32_16x16x32_bf16 v[118:121], v[146:149], v[192:195], v[118:121]
	v_mfma_f32_16x16x32_bf16 v[114:117], v[154:157], v[192:195], v[114:117]
	v_mfma_f32_16x16x32_bf16 v[102:105], v[146:149], v[200:203], v[102:105]
	v_mfma_f32_16x16x32_bf16 v[98:101], v[154:157], v[200:203], v[98:101]
	v_mfma_f32_16x16x32_bf16 v[86:89], v[146:149], v[230:233], v[86:89]
	v_mfma_f32_16x16x32_bf16 v[82:85], v[154:157], v[230:233], v[82:85]
	v_mfma_f32_16x16x32_bf16 v[70:73], v[146:149], v[238:241], v[70:73]
	v_mfma_f32_16x16x32_bf16 v[66:69], v[154:157], v[238:241], v[66:69]
	v_mfma_f32_16x16x32_bf16 v[118:121], v[150:153], v[196:199], v[118:121]
	v_mfma_f32_16x16x32_bf16 v[114:117], v[158:161], v[196:199], v[114:117]
	v_mfma_f32_16x16x32_bf16 v[102:105], v[150:153], v[204:207], v[102:105]
	v_mfma_f32_16x16x32_bf16 v[98:101], v[158:161], v[204:207], v[98:101]
	v_mfma_f32_16x16x32_bf16 v[86:89], v[150:153], v[234:237], v[86:89]
	v_mfma_f32_16x16x32_bf16 v[82:85], v[158:161], v[234:237], v[82:85]
	v_mfma_f32_16x16x32_bf16 v[70:73], v[150:153], v[242:245], v[70:73]
	v_mfma_f32_16x16x32_bf16 v[66:69], v[158:161], v[242:245], v[66:69]
	s_setprio 0
	s_add_i32 s24, s45, s23
	s_mov_b32 m0, s24
	ds_read_b128 v[192:195], v227 offset:16384
	ds_read_b128 v[196:199], v227 offset:17408
	ds_read_b128 v[200:203], v227 offset:18432
	ds_read_b128 v[204:207], v227 offset:19456
	ds_read_b128 v[230:233], v227 offset:20480
	ds_read_b128 v[234:237], v227 offset:21504
	ds_read_b128 v[238:241], v227 offset:22528
	ds_read_b128 v[242:245], v227 offset:23552
	global_load_lds_dwordx4 v168, s[86:87]
	s_add_i32 m0, s24, 0x2000
	s_add_u32 s24, s86, 0x80000
	s_addc_u32 s25, s87, 0
	s_add_i32 s55, s33, s23
	global_load_lds_dwordx4 v164, s[86:87]
	s_mov_b32 m0, s55
	s_nop 0
	global_load_lds_dwordx4 v168, s[24:25]
	s_add_i32 m0, s55, 0x2000
	s_nop 0
	global_load_lds_dwordx4 v164, s[24:25]
	s_mov_b32 m0, s95
	s_nop 0
	global_load_lds_dwordx4 v170, s[88:89]
	s_mov_b32 m0, s96
	s_nop 0
	global_load_lds_dwordx4 v166, s[88:89]
	s_waitcnt vmcnt(8)
	s_waitcnt lgkmcnt(0)
	s_barrier
	s_setprio 3
	s_waitcnt lgkmcnt(0)
	v_mfma_f32_16x16x32_bf16 v[62:65], v[130:133], v[192:195], v[62:65]
	v_mfma_f32_16x16x32_bf16 v[58:61], v[138:141], v[192:195], v[58:61]
	v_mfma_f32_16x16x32_bf16 v[46:49], v[130:133], v[200:203], v[46:49]
	v_mfma_f32_16x16x32_bf16 v[42:45], v[138:141], v[200:203], v[42:45]
	v_mfma_f32_16x16x32_bf16 v[30:33], v[130:133], v[230:233], v[30:33]
	v_mfma_f32_16x16x32_bf16 v[26:29], v[138:141], v[230:233], v[26:29]
	v_mfma_f32_16x16x32_bf16 v[14:17], v[130:133], v[238:241], v[14:17]
	v_mfma_f32_16x16x32_bf16 v[10:13], v[138:141], v[238:241], v[10:13]
	v_mfma_f32_16x16x32_bf16 v[62:65], v[134:137], v[196:199], v[62:65]
	v_mfma_f32_16x16x32_bf16 v[58:61], v[142:145], v[196:199], v[58:61]
	v_mfma_f32_16x16x32_bf16 v[46:49], v[134:137], v[204:207], v[46:49]
	v_mfma_f32_16x16x32_bf16 v[42:45], v[142:145], v[204:207], v[42:45]
	v_mfma_f32_16x16x32_bf16 v[30:33], v[134:137], v[234:237], v[30:33]
	v_mfma_f32_16x16x32_bf16 v[26:29], v[142:145], v[234:237], v[26:29]
	v_mfma_f32_16x16x32_bf16 v[14:17], v[134:137], v[242:245], v[14:17]
	v_mfma_f32_16x16x32_bf16 v[10:13], v[142:145], v[242:245], v[10:13]


; #define PG8_STAGE(bufoff, gbase, voff) do { _Pragma("unroll") for (int _i = 0; _i < 2; ++_i) \
;         __builtin_amdgcn_global_load_lds((const unsigned*)((const char*)(gbase) + (voff)[_i]), (PG8_LAS unsigned*)(lds + (bufoff) + ldsw + _i * 8192), 16, 0, 0); } while (0)
; #define PG8_LDA(dst, b, h) do { _Pragma("unroll") for (int m = 0; m < 4; ++m) _Pragma("unroll") for (int k = 0; k < 2; ++k) dst[m][k] = *(const PG8_LAS bf16x8*)(lds + PG8_SA(b, h) + aoff + m * 2048 + k * 1024); } while (0)
; #define PG8_LDB(dst, b, h) do { _Pragma("unroll") for (int n = 0; n < 2; ++n) _Pragma("unroll") for (int k = 0; k < 2; ++k) dst[n][k] = *(const PG8_LAS bf16x8*)(lds + PG8_SB(b, h) + boff + n * 2048 + k * 1024); } while (0)
; #define PG8_WAIT_V(n) asm volatile("s_waitcnt vmcnt(" #n ")" ::: "memory")
; #define PG8_WAIT_L(n) asm volatile("s_waitcnt lgkmcnt(" #n ")" ::: "memory")
; #define PG8_BAR __builtin_amdgcn_s_barrier()
; #define PG8_SCHED __builtin_amdgcn_sched_barrier(0)
; template <class Epi, class Sched, bool ALIGN_EPI = false, bool SP2 = false, bool F8 = false>
; __device__ __forceinline__ void gemm_phase(PG8_LAS unsigned char* lds, const Gemm g, const Sched& S, const Epi& E) {
;     ...
;             PG8_WAIT_V(8); PG8_WAIT_L(0); PG8_BAR; PG8_MMA(1, 0, At, B0); PG8_MMA(1, 1, At, B1); PG8_BAR; PG8_SCHED;
;             PG8_LDB(B0, 1, 0); PG8_LDB(B1, 1, 1); PG8_SCHED; PG8_LDA(At, 1, 0); PG8_STAGE(PG8_SA(0, 1), a2 + hstepA, voffA);
;             PG8_WAIT_V(8); PG8_WAIT_L(0); PG8_BAR; PG8_MMA(0, 0, At, B0); PG8_MMA(0, 1, At, B1); PG8_BAR; PG8_SCHED;
	v_mfma_f32_16x16x32_bf16 v[54:57], v[146:149], v[192:195], v[54:57]
	v_mfma_f32_16x16x32_bf16 v[50:53], v[154:157], v[192:195], v[50:53]
	v_mfma_f32_16x16x32_bf16 v[38:41], v[146:149], v[200:203], v[38:41]
	v_mfma_f32_16x16x32_bf16 v[34:37], v[154:157], v[200:203], v[34:37]
	v_mfma_f32_16x16x32_bf16 v[22:25], v[146:149], v[230:233], v[22:25]
	v_mfma_f32_16x16x32_bf16 v[18:21], v[154:157], v[230:233], v[18:21]
	v_mfma_f32_16x16x32_bf16 v[6:9], v[146:149], v[238:241], v[6:9]
	v_mfma_f32_16x16x32_bf16 v[2:5], v[154:157], v[238:241], v[2:5]
	v_mfma_f32_16x16x32_bf16 v[54:57], v[150:153], v[196:199], v[54:57]
	v_mfma_f32_16x16x32_bf16 v[50:53], v[158:161], v[196:199], v[50:53]
	v_mfma_f32_16x16x32_bf16 v[38:41], v[150:153], v[204:207], v[38:41]
	v_mfma_f32_16x16x32_bf16 v[34:37], v[158:161], v[204:207], v[34:37]
	v_mfma_f32_16x16x32_bf16 v[22:25], v[150:153], v[234:237], v[22:25]
	v_mfma_f32_16x16x32_bf16 v[18:21], v[158:161], v[234:237], v[18:21]
	v_mfma_f32_16x16x32_bf16 v[6:9], v[150:153], v[242:245], v[6:9]
	v_mfma_f32_16x16x32_bf16 v[2:5], v[158:161], v[242:245], v[2:5]
	s_setprio 0
	s_add_i32 s55, 0, 0x18000
	s_add_i32 s36, 0, 0x1c000
	v_add_u32_e32 v142, s55, v222
	v_add_u32_e32 v158, s36, v222
	ds_read_b128 v[130:133], v142
	ds_read_b128 v[134:137], v142 offset:1024
	ds_read_b128 v[138:141], v142 offset:2048
	ds_read_b128 v[142:145], v142 offset:3072
	ds_read_b128 v[146:149], v158
	ds_read_b128 v[150:153], v158 offset:1024
	ds_read_b128 v[154:157], v158 offset:2048
	ds_read_b128 v[158:161], v158 offset:3072
	s_add_u32 s24, s88, 0x80000
	s_addc_u32 s25, s89, 0
	s_mov_b32 m0, s97
	ds_read_b128 v[192:195], v227 offset:32768
	ds_read_b128 v[196:199], v227 offset:33792
	ds_read_b128 v[200:203], v227 offset:34816
	ds_read_b128 v[204:207], v227 offset:35840
	ds_read_b128 v[230:233], v227 offset:36864
	ds_read_b128 v[234:237], v227 offset:37888
	ds_read_b128 v[238:241], v227 offset:38912
	ds_read_b128 v[242:245], v227 offset:39936
	global_load_lds_dwordx4 v170, s[24:25]
	s_mov_b32 m0, s28
	s_nop 0
	global_load_lds_dwordx4 v166, s[24:25]
	s_waitcnt vmcnt(8)
	s_waitcnt lgkmcnt(0)
	s_barrier
	s_setprio 3
	s_waitcnt lgkmcnt(0)
	v_mfma_f32_16x16x32_bf16 v[126:129], v[130:133], v[192:195], v[126:129]
	v_mfma_f32_16x16x32_bf16 v[122:125], v[138:141], v[192:195], v[122:125]
	v_mfma_f32_16x16x32_bf16 v[110:113], v[130:133], v[200:203], v[110:113]
	v_mfma_f32_16x16x32_bf16 v[106:109], v[138:141], v[200:203], v[106:109]
	v_mfma_f32_16x16x32_bf16 v[94:97], v[130:133], v[230:233], v[94:97]
	v_mfma_f32_16x16x32_bf16 v[90:93], v[138:141], v[230:233], v[90:93]
	v_mfma_f32_16x16x32_bf16 v[78:81], v[130:133], v[238:241], v[78:81]
	v_mfma_f32_16x16x32_bf16 v[74:77], v[138:141], v[238:241], v[74:77]
	v_mfma_f32_16x16x32_bf16 v[126:129], v[134:137], v[196:199], v[126:129]
	v_mfma_f32_16x16x32_bf16 v[122:125], v[142:145], v[196:199], v[122:125]
	v_mfma_f32_16x16x32_bf16 v[110:113], v[134:137], v[204:207], v[110:113]
	v_mfma_f32_16x16x32_bf16 v[106:109], v[142:145], v[204:207], v[106:109]
	v_mfma_f32_16x16x32_bf16 v[94:97], v[134:137], v[234:237], v[94:97]
	v_mfma_f32_16x16x32_bf16 v[90:93], v[142:145], v[234:237], v[90:93]
	v_mfma_f32_16x16x32_bf16 v[78:81], v[134:137], v[242:245], v[78:81]
	v_mfma_f32_16x16x32_bf16 v[74:77], v[142:145], v[242:245], v[74:77]


; #define PG8_STAGE(bufoff, gbase, voff) do { _Pragma("unroll") for (int _i = 0; _i < 2; ++_i) \
;         __builtin_amdgcn_global_load_lds((const unsigned*)((const char*)(gbase) + (voff)[_i]), (PG8_LAS unsigned*)(lds + (bufoff) + ldsw + _i * 8192), 16, 0, 0); } while (0)
; #define PG8_LDA(dst, b, h) do { _Pragma("unroll") for (int m = 0; m < 4; ++m) _Pragma("unroll") for (int k = 0; k < 2; ++k) dst[m][k] = *(const PG8_LAS bf16x8*)(lds + PG8_SA(b, h) + aoff + m * 2048 + k * 1024); } while (0)
; #define PG8_WAIT_V(n) asm volatile("s_waitcnt vmcnt(" #n ")" ::: "memory")
; #define PG8_WAIT_L(n) asm volatile("s_waitcnt lgkmcnt(" #n ")" ::: "memory")
; #define PG8_BAR __builtin_amdgcn_s_barrier()
; #define PG8_SCHED __builtin_amdgcn_sched_barrier(0)
; template <class Epi, class Sched, bool ALIGN_EPI = false, bool SP2 = false, bool F8 = false>
; __device__ __forceinline__ void gemm_phase(PG8_LAS unsigned char* lds, const Gemm g, const Sched& S, const Epi& E) {
;     ...
;             PG8_WAIT_V(8); PG8_WAIT_L(0); PG8_BAR; PG8_MMA(0, 0, At, B0); PG8_MMA(0, 1, At, B1); PG8_BAR; PG8_SCHED;
;             PG8_LDA(At, 1, 1); PG8_STAGE(PG8_SB(1, 0), b3, voffB); PG8_STAGE(PG8_SB(1, 1), b3 + hstep, voffB); PG8_STAGE(PG8_SA(1, 0), a3, voffA);
;             PG8_WAIT_V(8); PG8_WAIT_L(0); PG8_BAR; PG8_MMA(1, 0, At, B0); PG8_MMA(1, 1, At, B1); PG8_BAR; PG8_SCHED;
	v_mfma_f32_16x16x32_bf16 v[118:121], v[146:149], v[192:195], v[118:121]
	v_mfma_f32_16x16x32_bf16 v[114:117], v[154:157], v[192:195], v[114:117]
	v_mfma_f32_16x16x32_bf16 v[102:105], v[146:149], v[200:203], v[102:105]
	v_mfma_f32_16x16x32_bf16 v[98:101], v[154:157], v[200:203], v[98:101]
	v_mfma_f32_16x16x32_bf16 v[86:89], v[146:149], v[230:233], v[86:89]
	v_mfma_f32_16x16x32_bf16 v[82:85], v[154:157], v[230:233], v[82:85]
	v_mfma_f32_16x16x32_bf16 v[70:73], v[146:149], v[238:241], v[70:73]
	v_mfma_f32_16x16x32_bf16 v[66:69], v[154:157], v[238:241], v[66:69]
	v_mfma_f32_16x16x32_bf16 v[118:121], v[150:153], v[196:199], v[118:121]
	v_mfma_f32_16x16x32_bf16 v[114:117], v[158:161], v[196:199], v[114:117]
	v_mfma_f32_16x16x32_bf16 v[102:105], v[150:153], v[204:207], v[102:105]
	v_mfma_f32_16x16x32_bf16 v[98:101], v[158:161], v[204:207], v[98:101]
	v_mfma_f32_16x16x32_bf16 v[86:89], v[150:153], v[234:237], v[86:89]
	v_mfma_f32_16x16x32_bf16 v[82:85], v[158:161], v[234:237], v[82:85]
	v_mfma_f32_16x16x32_bf16 v[70:73], v[150:153], v[242:245], v[70:73]
	v_mfma_f32_16x16x32_bf16 v[66:69], v[158:161], v[242:245], v[66:69]
	s_setprio 0
	s_add_i32 s24, s55, s23
	s_mov_b32 m0, s24
	ds_read_b128 v[192:195], v227 offset:49152
	ds_read_b128 v[196:199], v227 offset:50176
	ds_read_b128 v[200:203], v227 offset:51200
	ds_read_b128 v[204:207], v227 offset:52224
	ds_read_b128 v[230:233], v227 offset:53248
	ds_read_b128 v[234:237], v227 offset:54272
	ds_read_b128 v[238:241], v227 offset:55296
	ds_read_b128 v[242:245], v227 offset:56320
	s_add_u32 s98, s86, 0x80
	s_addc_u32 s99, s87, 0
	global_load_lds_dwordx4 v168, s[98:99]
	s_add_i32 m0, s24, 0x2000
	s_add_u32 s24, s86, 0x80080
	s_addc_u32 s25, s87, 0
	s_add_i32 s36, s36, s23
	s_add_u32 s100, s86, 0x80
	s_addc_u32 s101, s87, 0
	global_load_lds_dwordx4 v164, s[100:101]
	s_mov_b32 m0, s36
	s_nop 0
	global_load_lds_dwordx4 v168, s[24:25]
	s_add_i32 m0, s36, 0x2000
	s_nop 0
	global_load_lds_dwordx4 v164, s[24:25]
	s_mov_b32 m0, s15
	s_nop 0
	s_add_u32 s98, s88, 0x80
	s_addc_u32 s99, s89, 0
	global_load_lds_dwordx4 v170, s[98:99]
	s_mov_b32 m0, s26
	s_nop 0
	s_add_u32 s100, s88, 0x80
	s_addc_u32 s101, s89, 0
	global_load_lds_dwordx4 v166, s[100:101]
	s_waitcnt vmcnt(8)
	s_waitcnt lgkmcnt(0)
	s_barrier
	s_setprio 3
	s_waitcnt lgkmcnt(0)
	v_mfma_f32_16x16x32_bf16 v[62:65], v[130:133], v[192:195], v[62:65]
	v_mfma_f32_16x16x32_bf16 v[58:61], v[138:141], v[192:195], v[58:61]
	v_mfma_f32_16x16x32_bf16 v[46:49], v[130:133], v[200:203], v[46:49]
	v_mfma_f32_16x16x32_bf16 v[42:45], v[138:141], v[200:203], v[42:45]
	v_mfma_f32_16x16x32_bf16 v[30:33], v[130:133], v[230:233], v[30:33]
	v_mfma_f32_16x16x32_bf16 v[26:29], v[138:141], v[230:233], v[26:29]
	v_mfma_f32_16x16x32_bf16 v[14:17], v[130:133], v[238:241], v[14:17]
	v_mfma_f32_16x16x32_bf16 v[10:13], v[138:141], v[238:241], v[10:13]
	v_mfma_f32_16x16x32_bf16 v[62:65], v[134:137], v[196:199], v[62:65]
	v_mfma_f32_16x16x32_bf16 v[58:61], v[142:145], v[196:199], v[58:61]
	v_mfma_f32_16x16x32_bf16 v[46:49], v[134:137], v[204:207], v[46:49]
	v_mfma_f32_16x16x32_bf16 v[42:45], v[142:145], v[204:207], v[42:45]
	v_mfma_f32_16x16x32_bf16 v[30:33], v[134:137], v[234:237], v[30:33]
	v_mfma_f32_16x16x32_bf16 v[26:29], v[142:145], v[234:237], v[26:29]
	v_mfma_f32_16x16x32_bf16 v[14:17], v[134:137], v[242:245], v[14:17]
	v_mfma_f32_16x16x32_bf16 v[10:13], v[142:145], v[242:245], v[10:13]


; #define PG8_STAGE(bufoff, gbase, voff) do { _Pragma("unroll") for (int _i = 0; _i < 2; ++_i) \
;         __builtin_amdgcn_global_load_lds((const unsigned*)((const char*)(gbase) + (voff)[_i]), (PG8_LAS unsigned*)(lds + (bufoff) + ldsw + _i * 8192), 16, 0, 0); } while (0)
; #define PG8_LDA(dst, b, h) do { _Pragma("unroll") for (int m = 0; m < 4; ++m) _Pragma("unroll") for (int k = 0; k < 2; ++k) dst[m][k] = *(const PG8_LAS bf16x8*)(lds + PG8_SA(b, h) + aoff + m * 2048 + k * 1024); } while (0)
; #define PG8_LDB(dst, b, h) do { _Pragma("unroll") for (int n = 0; n < 2; ++n) _Pragma("unroll") for (int k = 0; k < 2; ++k) dst[n][k] = *(const PG8_LAS bf16x8*)(lds + PG8_SB(b, h) + boff + n * 2048 + k * 1024); } while (0)
; #define PG8_WAIT_V(n) asm volatile("s_waitcnt vmcnt(" #n ")" ::: "memory")
; #define PG8_WAIT_L(n) asm volatile("s_waitcnt lgkmcnt(" #n ")" ::: "memory")
; #define PG8_BAR __builtin_amdgcn_s_barrier()
; #define PG8_SCHED __builtin_amdgcn_sched_barrier(0)
; template <class Epi, class Sched, bool ALIGN_EPI = false, bool SP2 = false, bool F8 = false>
; __device__ __forceinline__ void gemm_phase(PG8_LAS unsigned char* lds, const Gemm g, const Sched& S, const Epi& E) {
;     ...
;         for (int t = 0; t < nt; t += 2) {
;             const bool last = (t == nt - 2);
;             const char* a1 = cA + (size_t)(t + 1) * kstep;
;             const char* a2 = last ? nA : cA + (size_t)(t + 2) * kstep; const char* b2 = last ? nB : cB + (size_t)(t + 2) * kstep;
;             const char* a3 = a2 + kstep; const char* b3 = b2 + kstep;
;             if (last && has_next) S.a_ready(nxt);
;             if constexpr (SP2) {
;             PG8_LDB(B0, 0, 0); PG8_LDB(B1, 0, 1); PG8_SCHED; PG8_LDA(At, 0, 0); PG8_STAGE(PG8_SA(1, 1), a1 + hstepA, voffA);
;             PG8_WAIT_V(8); PG8_WAIT_L(0); PG8_BAR; PG8_MMA(0, 0, At, B0); PG8_MMA(0, 1, At, B1); PG8_BAR; PG8_SCHED;
	v_mfma_f32_16x16x32_bf16 v[54:57], v[146:149], v[192:195], v[54:57]
	v_mfma_f32_16x16x32_bf16 v[50:53], v[154:157], v[192:195], v[50:53]
	v_mfma_f32_16x16x32_bf16 v[38:41], v[146:149], v[200:203], v[38:41]
	v_mfma_f32_16x16x32_bf16 v[34:37], v[154:157], v[200:203], v[34:37]
	v_mfma_f32_16x16x32_bf16 v[22:25], v[146:149], v[230:233], v[22:25]
	v_mfma_f32_16x16x32_bf16 v[18:21], v[154:157], v[230:233], v[18:21]
	v_mfma_f32_16x16x32_bf16 v[6:9], v[146:149], v[238:241], v[6:9]
	v_mfma_f32_16x16x32_bf16 v[2:5], v[154:157], v[238:241], v[2:5]
	v_mfma_f32_16x16x32_bf16 v[54:57], v[150:153], v[196:199], v[54:57]
	v_mfma_f32_16x16x32_bf16 v[50:53], v[158:161], v[196:199], v[50:53]
	v_mfma_f32_16x16x32_bf16 v[38:41], v[150:153], v[204:207], v[38:41]
	v_mfma_f32_16x16x32_bf16 v[34:37], v[158:161], v[204:207], v[34:37]
	v_mfma_f32_16x16x32_bf16 v[22:25], v[150:153], v[234:237], v[22:25]
	v_mfma_f32_16x16x32_bf16 v[18:21], v[158:161], v[234:237], v[18:21]
	v_mfma_f32_16x16x32_bf16 v[6:9], v[150:153], v[242:245], v[6:9]
	v_mfma_f32_16x16x32_bf16 v[2:5], v[158:161], v[242:245], v[2:5]
	s_setprio 0
	s_add_i32 s54, s54, 2
	s_add_u32 s84, s84, 0x100
	s_addc_u32 s85, s85, 0
	s_add_u32 vcc_lo, vcc_lo, 0x100
	s_addc_u32 vcc_hi, vcc_hi, 0
	s_cmp_gt_u32 s54, 29
	s_cbranch_scc0 .Lk0_Y
	s_branch .Lk0_exit
.Lk0_Xz:
	ds_read_b128 v[130:133], v225
	ds_read_b128 v[134:137], v225 offset:1024
	ds_read_b128 v[138:141], v225 offset:2048
	ds_read_b128 v[142:145], v225 offset:3072
	ds_read_b128 v[146:149], v226
	ds_read_b128 v[150:153], v226 offset:1024
	ds_read_b128 v[154:157], v226 offset:2048
	ds_read_b128 v[158:161], v226 offset:3072
	s_add_u32 s24, s84, 0xfff80080
	s_addc_u32 s25, s85, -1
	s_cmp_eq_u32 s54, 28
	s_cselect_b32 s89, s13, s25
	s_cselect_b32 s88, s53, s24
	s_cselect_b32 s87, s77, vcc_hi
	s_cselect_b32 s86, s79, vcc_lo
	s_add_i32 m0, s95, 0xc000
	ds_read_b128 v[192:195], v227
	ds_read_b128 v[196:199], v227 offset:1024
	ds_read_b128 v[200:203], v227 offset:2048
	ds_read_b128 v[204:207], v227 offset:3072
	ds_read_b128 v[230:233], v227 offset:4096
	ds_read_b128 v[234:237], v227 offset:5120
	ds_read_b128 v[238:241], v227 offset:6144
	ds_read_b128 v[242:245], v227 offset:7168
	global_load_lds_dwordx4 v186, s[84:85]
	s_add_i32 m0, s95, 0xe000
	s_nop 0
	global_load_lds_dwordx4 v188, s[84:85]
	s_waitcnt vmcnt(8)
	s_waitcnt lgkmcnt(0)
	s_setprio 1
	s_waitcnt lgkmcnt(0)
	v_mfma_f32_16x16x32_bf16 v[126:129], v[130:133], v[192:195], 0
	v_mfma_f32_16x16x32_bf16 v[122:125], v[138:141], v[192:195], 0
	v_mfma_f32_16x16x32_bf16 v[110:113], v[130:133], v[200:203], 0
	v_mfma_f32_16x16x32_bf16 v[106:109], v[138:141], v[200:203], 0
	v_mfma_f32_16x16x32_bf16 v[94:97], v[130:133], v[230:233], 0
	v_mfma_f32_16x16x32_bf16 v[90:93], v[138:141], v[230:233], 0
	v_mfma_f32_16x16x32_bf16 v[78:81], v[130:133], v[238:241], 0
	v_mfma_f32_16x16x32_bf16 v[74:77], v[138:141], v[238:241], 0
	v_mfma_f32_16x16x32_bf16 v[126:129], v[134:137], v[196:199], v[126:129]
	v_mfma_f32_16x16x32_bf16 v[122:125], v[142:145], v[196:199], v[122:125]
	v_mfma_f32_16x16x32_bf16 v[110:113], v[134:137], v[204:207], v[110:113]
	v_mfma_f32_16x16x32_bf16 v[106:109], v[142:145], v[204:207], v[106:109]
	v_mfma_f32_16x16x32_bf16 v[94:97], v[134:137], v[234:237], v[94:97]
	v_mfma_f32_16x16x32_bf16 v[90:93], v[142:145], v[234:237], v[90:93]
	v_mfma_f32_16x16x32_bf16 v[78:81], v[134:137], v[242:245], v[78:81]
	v_mfma_f32_16x16x32_bf16 v[74:77], v[142:145], v[242:245], v[74:77]
	s_setprio 0
	s_setprio 1
	v_mfma_f32_16x16x32_bf16 v[118:121], v[146:149], v[192:195], 0
	v_mfma_f32_16x16x32_bf16 v[114:117], v[154:157], v[192:195], 0
	v_mfma_f32_16x16x32_bf16 v[102:105], v[146:149], v[200:203], 0
	v_mfma_f32_16x16x32_bf16 v[98:101], v[154:157], v[200:203], 0
	v_mfma_f32_16x16x32_bf16 v[86:89], v[146:149], v[230:233], 0
	v_mfma_f32_16x16x32_bf16 v[82:85], v[154:157], v[230:233], 0
	v_mfma_f32_16x16x32_bf16 v[70:73], v[146:149], v[238:241], 0
	v_mfma_f32_16x16x32_bf16 v[66:69], v[154:157], v[238:241], 0
	v_mfma_f32_16x16x32_bf16 v[118:121], v[150:153], v[196:199], v[118:121]
	v_mfma_f32_16x16x32_bf16 v[114:117], v[158:161], v[196:199], v[114:117]
	v_mfma_f32_16x16x32_bf16 v[102:105], v[150:153], v[204:207], v[102:105]
	v_mfma_f32_16x16x32_bf16 v[98:101], v[158:161], v[204:207], v[98:101]
	v_mfma_f32_16x16x32_bf16 v[86:89], v[150:153], v[234:237], v[86:89]
	v_mfma_f32_16x16x32_bf16 v[82:85], v[158:161], v[234:237], v[82:85]
	v_mfma_f32_16x16x32_bf16 v[70:73], v[150:153], v[242:245], v[70:73]
	v_mfma_f32_16x16x32_bf16 v[66:69], v[158:161], v[242:245], v[66:69]
	s_setprio 0
	s_barrier
; #define PG8_STAGE(bufoff, gbase, voff) do { _Pragma("unroll") for (int _i = 0; _i < 2; ++_i) \
;         __builtin_amdgcn_global_load_lds((const unsigned*)((const char*)(gbase) + (voff)[_i]), (PG8_LAS unsigned*)(lds + (bufoff) + ldsw + _i * 8192), 16, 0, 0); } while (0)
; #define PG8_LDA(dst, b, h) do { _Pragma("unroll") for (int m = 0; m < 4; ++m) _Pragma("unroll") for (int k = 0; k < 2; ++k) dst[m][k] = *(const PG8_LAS bf16x8*)(lds + PG8_SA(b, h) + aoff + m * 2048 + k * 1024); } while (0)
; #define PG8_LDB(dst, b, h) do { _Pragma("unroll") for (int n = 0; n < 2; ++n) _Pragma("unroll") for (int k = 0; k < 2; ++k) dst[n][k] = *(const PG8_LAS bf16x8*)(lds + PG8_SB(b, h) + boff + n * 2048 + k * 1024); } while (0)
; #define PG8_WAIT_V(n) asm volatile("s_waitcnt vmcnt(" #n ")" ::: "memory")
; #define PG8_WAIT_L(n) asm volatile("s_waitcnt lgkmcnt(" #n ")" ::: "memory")
; #define PG8_BAR __builtin_amdgcn_s_barrier()
; #define PG8_SCHED __builtin_amdgcn_sched_barrier(0)
; template <class Epi, class Sched, bool ALIGN_EPI = false, bool SP2 = false, bool F8 = false>
; __device__ __forceinline__ void gemm_phase(PG8_LAS unsigned char* lds, const Gemm g, const Sched& S, const Epi& E) {
;     ...
;             PG8_LDA(At, 0, 1); PG8_STAGE(PG8_SB(0, 0), b2, voffB); PG8_STAGE(PG8_SB(0, 1), b2 + hstep, voffB); PG8_STAGE(PG8_SA(0, 0), a2, voffA);
;             PG8_WAIT_V(8); PG8_WAIT_L(0); PG8_BAR; PG8_MMA(1, 0, At, B0); PG8_MMA(1, 1, At, B1); PG8_BAR; PG8_SCHED;
;             PG8_LDB(B0, 1, 0); PG8_LDB(B1, 1, 1); PG8_SCHED; PG8_LDA(At, 1, 0); PG8_STAGE(PG8_SA(0, 1), a2 + hstepA, voffA);
;             PG8_WAIT_V(8); PG8_WAIT_L(0); PG8_BAR; PG8_MMA(0, 0, At, B0); PG8_MMA(0, 1, At, B1); PG8_BAR; PG8_SCHED;
	s_add_i32 s24, s45, s23
	s_mov_b32 m0, s24
	ds_read_b128 v[192:195], v227 offset:16384
	ds_read_b128 v[196:199], v227 offset:17408
	ds_read_b128 v[200:203], v227 offset:18432
	ds_read_b128 v[204:207], v227 offset:19456
	ds_read_b128 v[230:233], v227 offset:20480
	ds_read_b128 v[234:237], v227 offset:21504
	ds_read_b128 v[238:241], v227 offset:22528
	ds_read_b128 v[242:245], v227 offset:23552
	global_load_lds_dwordx4 v168, s[86:87]
	s_add_i32 m0, s24, 0x2000
	s_add_u32 s24, s86, 0x80000
	s_addc_u32 s25, s87, 0
	s_add_i32 s55, s33, s23
	global_load_lds_dwordx4 v164, s[86:87]
	s_mov_b32 m0, s55
	s_nop 0
	global_load_lds_dwordx4 v168, s[24:25]
	s_add_i32 m0, s55, 0x2000
	s_nop 0
	global_load_lds_dwordx4 v164, s[24:25]
	s_mov_b32 m0, s95
	s_nop 0
	global_load_lds_dwordx4 v170, s[88:89]
	s_mov_b32 m0, s96
	s_nop 0
	global_load_lds_dwordx4 v166, s[88:89]
	s_waitcnt vmcnt(8)
	s_waitcnt lgkmcnt(0)
	s_setprio 1
	s_waitcnt lgkmcnt(0)
	v_mfma_f32_16x16x32_bf16 v[62:65], v[130:133], v[192:195], 0
	v_mfma_f32_16x16x32_bf16 v[58:61], v[138:141], v[192:195], 0
	v_mfma_f32_16x16x32_bf16 v[46:49], v[130:133], v[200:203], 0
	v_mfma_f32_16x16x32_bf16 v[42:45], v[138:141], v[200:203], 0
	v_mfma_f32_16x16x32_bf16 v[30:33], v[130:133], v[230:233], 0
	v_mfma_f32_16x16x32_bf16 v[26:29], v[138:141], v[230:233], 0
	v_mfma_f32_16x16x32_bf16 v[14:17], v[130:133], v[238:241], 0
	v_mfma_f32_16x16x32_bf16 v[10:13], v[138:141], v[238:241], 0
	v_mfma_f32_16x16x32_bf16 v[62:65], v[134:137], v[196:199], v[62:65]
	v_mfma_f32_16x16x32_bf16 v[58:61], v[142:145], v[196:199], v[58:61]
	v_mfma_f32_16x16x32_bf16 v[46:49], v[134:137], v[204:207], v[46:49]
	v_mfma_f32_16x16x32_bf16 v[42:45], v[142:145], v[204:207], v[42:45]
	v_mfma_f32_16x16x32_bf16 v[30:33], v[134:137], v[234:237], v[30:33]
	v_mfma_f32_16x16x32_bf16 v[26:29], v[142:145], v[234:237], v[26:29]
	v_mfma_f32_16x16x32_bf16 v[14:17], v[134:137], v[242:245], v[14:17]
	v_mfma_f32_16x16x32_bf16 v[10:13], v[142:145], v[242:245], v[10:13]
	s_setprio 0
	s_setprio 1
	v_mfma_f32_16x16x32_bf16 v[54:57], v[146:149], v[192:195], 0
	v_mfma_f32_16x16x32_bf16 v[50:53], v[154:157], v[192:195], 0
	v_mfma_f32_16x16x32_bf16 v[38:41], v[146:149], v[200:203], 0
	v_mfma_f32_16x16x32_bf16 v[34:37], v[154:157], v[200:203], 0
	v_mfma_f32_16x16x32_bf16 v[22:25], v[146:149], v[230:233], 0
	v_mfma_f32_16x16x32_bf16 v[18:21], v[154:157], v[230:233], 0
	v_mfma_f32_16x16x32_bf16 v[6:9], v[146:149], v[238:241], 0
	v_mfma_f32_16x16x32_bf16 v[2:5], v[154:157], v[238:241], 0
	v_mfma_f32_16x16x32_bf16 v[54:57], v[150:153], v[196:199], v[54:57]
	v_mfma_f32_16x16x32_bf16 v[50:53], v[158:161], v[196:199], v[50:53]
	v_mfma_f32_16x16x32_bf16 v[38:41], v[150:153], v[204:207], v[38:41]
	v_mfma_f32_16x16x32_bf16 v[34:37], v[158:161], v[204:207], v[34:37]
	v_mfma_f32_16x16x32_bf16 v[22:25], v[150:153], v[234:237], v[22:25]
	v_mfma_f32_16x16x32_bf16 v[18:21], v[158:161], v[234:237], v[18:21]
	v_mfma_f32_16x16x32_bf16 v[6:9], v[150:153], v[242:245], v[6:9]
	v_mfma_f32_16x16x32_bf16 v[2:5], v[158:161], v[242:245], v[2:5]
	s_setprio 0
	s_barrier
	s_add_i32 s55, 0, 0x18000
	s_add_i32 s36, 0, 0x1c000
	v_add_u32_e32 v142, s55, v222
	v_add_u32_e32 v158, s36, v222
	ds_read_b128 v[130:133], v142
	ds_read_b128 v[134:137], v142 offset:1024
	ds_read_b128 v[138:141], v142 offset:2048
	ds_read_b128 v[142:145], v142 offset:3072
	ds_read_b128 v[146:149], v158
	ds_read_b128 v[150:153], v158 offset:1024
	ds_read_b128 v[154:157], v158 offset:2048
	ds_read_b128 v[158:161], v158 offset:3072
	s_add_u32 s24, s88, 0x80000
	s_addc_u32 s25, s89, 0
	s_mov_b32 m0, s97
	ds_read_b128 v[192:195], v227 offset:32768
	ds_read_b128 v[196:199], v227 offset:33792
	ds_read_b128 v[200:203], v227 offset:34816
	ds_read_b128 v[204:207], v227 offset:35840
	ds_read_b128 v[230:233], v227 offset:36864
	ds_read_b128 v[234:237], v227 offset:37888
	ds_read_b128 v[238:241], v227 offset:38912
	ds_read_b128 v[242:245], v227 offset:39936
	global_load_lds_dwordx4 v170, s[24:25]
	s_mov_b32 m0, s28
	s_nop 0
	global_load_lds_dwordx4 v166, s[24:25]
	s_waitcnt vmcnt(8)
	s_waitcnt lgkmcnt(0)
	s_setprio 1
	s_waitcnt lgkmcnt(0)
	v_mfma_f32_16x16x32_bf16 v[126:129], v[130:133], v[192:195], v[126:129]
	v_mfma_f32_16x16x32_bf16 v[122:125], v[138:141], v[192:195], v[122:125]
	v_mfma_f32_16x16x32_bf16 v[110:113], v[130:133], v[200:203], v[110:113]
	v_mfma_f32_16x16x32_bf16 v[106:109], v[138:141], v[200:203], v[106:109]
	v_mfma_f32_16x16x32_bf16 v[94:97], v[130:133], v[230:233], v[94:97]
	v_mfma_f32_16x16x32_bf16 v[90:93], v[138:141], v[230:233], v[90:93]
	v_mfma_f32_16x16x32_bf16 v[78:81], v[130:133], v[238:241], v[78:81]
	v_mfma_f32_16x16x32_bf16 v[74:77], v[138:141], v[238:241], v[74:77]
	v_mfma_f32_16x16x32_bf16 v[126:129], v[134:137], v[196:199], v[126:129]
	v_mfma_f32_16x16x32_bf16 v[122:125], v[142:145], v[196:199], v[122:125]
	v_mfma_f32_16x16x32_bf16 v[110:113], v[134:137], v[204:207], v[110:113]
	v_mfma_f32_16x16x32_bf16 v[106:109], v[142:145], v[204:207], v[106:109]
	v_mfma_f32_16x16x32_bf16 v[94:97], v[134:137], v[234:237], v[94:97]
	v_mfma_f32_16x16x32_bf16 v[90:93], v[142:145], v[234:237], v[90:93]
	v_mfma_f32_16x16x32_bf16 v[78:81], v[134:137], v[242:245], v[78:81]
	v_mfma_f32_16x16x32_bf16 v[74:77], v[142:145], v[242:245], v[74:77]
	s_setprio 0
	s_setprio 1
	v_mfma_f32_16x16x32_bf16 v[118:121], v[146:149], v[192:195], v[118:121]
	v_mfma_f32_16x16x32_bf16 v[114:117], v[154:157], v[192:195], v[114:117]
	v_mfma_f32_16x16x32_bf16 v[102:105], v[146:149], v[200:203], v[102:105]
	v_mfma_f32_16x16x32_bf16 v[98:101], v[154:157], v[200:203], v[98:101]
	v_mfma_f32_16x16x32_bf16 v[86:89], v[146:149], v[230:233], v[86:89]
	v_mfma_f32_16x16x32_bf16 v[82:85], v[154:157], v[230:233], v[82:85]
	v_mfma_f32_16x16x32_bf16 v[70:73], v[146:149], v[238:241], v[70:73]
	v_mfma_f32_16x16x32_bf16 v[66:69], v[154:157], v[238:241], v[66:69]
	v_mfma_f32_16x16x32_bf16 v[118:121], v[150:153], v[196:199], v[118:121]
	v_mfma_f32_16x16x32_bf16 v[114:117], v[158:161], v[196:199], v[114:117]
	v_mfma_f32_16x16x32_bf16 v[102:105], v[150:153], v[204:207], v[102:105]
	v_mfma_f32_16x16x32_bf16 v[98:101], v[158:161], v[204:207], v[98:101]
	v_mfma_f32_16x16x32_bf16 v[86:89], v[150:153], v[234:237], v[86:89]
	v_mfma_f32_16x16x32_bf16 v[82:85], v[158:161], v[234:237], v[82:85]
	v_mfma_f32_16x16x32_bf16 v[70:73], v[150:153], v[242:245], v[70:73]
	v_mfma_f32_16x16x32_bf16 v[66:69], v[158:161], v[242:245], v[66:69]
	s_setprio 0
	s_barrier
; #define PG8_STAGE(bufoff, gbase, voff) do { _Pragma("unroll") for (int _i = 0; _i < 2; ++_i) \
;         __builtin_amdgcn_global_load_lds((const unsigned*)((const char*)(gbase) + (voff)[_i]), (PG8_LAS unsigned*)(lds + (bufoff) + ldsw + _i * 8192), 16, 0, 0); } while (0)
; #define PG8_LDA(dst, b, h) do { _Pragma("unroll") for (int m = 0; m < 4; ++m) _Pragma("unroll") for (int k = 0; k < 2; ++k) dst[m][k] = *(const PG8_LAS bf16x8*)(lds + PG8_SA(b, h) + aoff + m * 2048 + k * 1024); } while (0)
; #define PG8_LDB(dst, b, h) do { _Pragma("unroll") for (int n = 0; n < 2; ++n) _Pragma("unroll") for (int k = 0; k < 2; ++k) dst[n][k] = *(const PG8_LAS bf16x8*)(lds + PG8_SB(b, h) + boff + n * 2048 + k * 1024); } while (0)
; #define PG8_WAIT_V(n) asm volatile("s_waitcnt vmcnt(" #n ")" ::: "memory")
; #define PG8_WAIT_L(n) asm volatile("s_waitcnt lgkmcnt(" #n ")" ::: "memory")
; #define PG8_BAR __builtin_amdgcn_s_barrier()
; #define PG8_SCHED __builtin_amdgcn_sched_barrier(0)
; template <class Epi, class Sched, bool ALIGN_EPI = false, bool SP2 = false, bool F8 = false>
; __device__ __forceinline__ void gemm_phase(PG8_LAS unsigned char* lds, const Gemm g, const Sched& S, const Epi& E) {
;     ...
;             PG8_LDB(B0, 0, 0); PG8_LDB(B1, 0, 1); PG8_SCHED; PG8_LDA(At, 0, 0); PG8_STAGE(PG8_SA(1, 1), a1 + hstepA, voffA);
;             PG8_WAIT_V(8); PG8_WAIT_L(0); PG8_BAR; PG8_MMA(0, 0, At, B0); PG8_MMA(0, 1, At, B1); PG8_BAR; PG8_SCHED;
;     ...
;             PG8_LDA(At, 1, 1); PG8_STAGE(PG8_SB(1, 0), b3, voffB); PG8_STAGE(PG8_SB(1, 1), b3 + hstep, voffB); PG8_STAGE(PG8_SA(1, 0), a3, voffA);
;             PG8_WAIT_V(8); PG8_WAIT_L(0); PG8_BAR; PG8_MMA(1, 0, At, B0); PG8_MMA(1, 1, At, B1); PG8_BAR; PG8_SCHED;
	s_add_i32 s24, s55, s23
	s_mov_b32 m0, s24
	ds_read_b128 v[192:195], v227 offset:49152
	ds_read_b128 v[196:199], v227 offset:50176
	ds_read_b128 v[200:203], v227 offset:51200
	ds_read_b128 v[204:207], v227 offset:52224
	ds_read_b128 v[230:233], v227 offset:53248
	ds_read_b128 v[234:237], v227 offset:54272
	ds_read_b128 v[238:241], v227 offset:55296
	ds_read_b128 v[242:245], v227 offset:56320
	s_add_u32 s98, s86, 0x80
	s_addc_u32 s99, s87, 0
	global_load_lds_dwordx4 v168, s[98:99]
	s_add_i32 m0, s24, 0x2000
	s_add_u32 s24, s86, 0x80080
	s_addc_u32 s25, s87, 0
	s_add_i32 s36, s36, s23
	s_add_u32 s100, s86, 0x80
	s_addc_u32 s101, s87, 0
	global_load_lds_dwordx4 v164, s[100:101]
	s_mov_b32 m0, s36
	s_nop 0
	global_load_lds_dwordx4 v168, s[24:25]
	s_add_i32 m0, s36, 0x2000
	s_nop 0
	global_load_lds_dwordx4 v164, s[24:25]
	s_mov_b32 m0, s15
	s_nop 0
	s_add_u32 s98, s88, 0x80
	s_addc_u32 s99, s89, 0
	global_load_lds_dwordx4 v170, s[98:99]
	s_mov_b32 m0, s26
	s_nop 0
	s_add_u32 s100, s88, 0x80
	s_addc_u32 s101, s89, 0
	global_load_lds_dwordx4 v166, s[100:101]
	s_waitcnt vmcnt(8)
	s_waitcnt lgkmcnt(0)
	s_setprio 1
	s_waitcnt lgkmcnt(0)
	v_mfma_f32_16x16x32_bf16 v[62:65], v[130:133], v[192:195], v[62:65]
	v_mfma_f32_16x16x32_bf16 v[58:61], v[138:141], v[192:195], v[58:61]
	v_mfma_f32_16x16x32_bf16 v[46:49], v[130:133], v[200:203], v[46:49]
	v_mfma_f32_16x16x32_bf16 v[42:45], v[138:141], v[200:203], v[42:45]
	v_mfma_f32_16x16x32_bf16 v[30:33], v[130:133], v[230:233], v[30:33]
	v_mfma_f32_16x16x32_bf16 v[26:29], v[138:141], v[230:233], v[26:29]
	v_mfma_f32_16x16x32_bf16 v[14:17], v[130:133], v[238:241], v[14:17]
	v_mfma_f32_16x16x32_bf16 v[10:13], v[138:141], v[238:241], v[10:13]
	v_mfma_f32_16x16x32_bf16 v[62:65], v[134:137], v[196:199], v[62:65]
	v_mfma_f32_16x16x32_bf16 v[58:61], v[142:145], v[196:199], v[58:61]
	v_mfma_f32_16x16x32_bf16 v[46:49], v[134:137], v[204:207], v[46:49]
	v_mfma_f32_16x16x32_bf16 v[42:45], v[142:145], v[204:207], v[42:45]
	v_mfma_f32_16x16x32_bf16 v[30:33], v[134:137], v[234:237], v[30:33]
	v_mfma_f32_16x16x32_bf16 v[26:29], v[142:145], v[234:237], v[26:29]
	v_mfma_f32_16x16x32_bf16 v[14:17], v[134:137], v[242:245], v[14:17]
	v_mfma_f32_16x16x32_bf16 v[10:13], v[142:145], v[242:245], v[10:13]
	s_setprio 0
	s_setprio 1
	v_mfma_f32_16x16x32_bf16 v[54:57], v[146:149], v[192:195], v[54:57]
	v_mfma_f32_16x16x32_bf16 v[50:53], v[154:157], v[192:195], v[50:53]
	v_mfma_f32_16x16x32_bf16 v[38:41], v[146:149], v[200:203], v[38:41]
	v_mfma_f32_16x16x32_bf16 v[34:37], v[154:157], v[200:203], v[34:37]
	v_mfma_f32_16x16x32_bf16 v[22:25], v[146:149], v[230:233], v[22:25]
	v_mfma_f32_16x16x32_bf16 v[18:21], v[154:157], v[230:233], v[18:21]
	v_mfma_f32_16x16x32_bf16 v[6:9], v[146:149], v[238:241], v[6:9]
	v_mfma_f32_16x16x32_bf16 v[2:5], v[154:157], v[238:241], v[2:5]
	v_mfma_f32_16x16x32_bf16 v[54:57], v[150:153], v[196:199], v[54:57]
	v_mfma_f32_16x16x32_bf16 v[50:53], v[158:161], v[196:199], v[50:53]
	v_mfma_f32_16x16x32_bf16 v[38:41], v[150:153], v[204:207], v[38:41]
	v_mfma_f32_16x16x32_bf16 v[34:37], v[158:161], v[204:207], v[34:37]
	v_mfma_f32_16x16x32_bf16 v[22:25], v[150:153], v[234:237], v[22:25]
	v_mfma_f32_16x16x32_bf16 v[18:21], v[158:161], v[234:237], v[18:21]
	v_mfma_f32_16x16x32_bf16 v[6:9], v[150:153], v[242:245], v[6:9]
	v_mfma_f32_16x16x32_bf16 v[2:5], v[158:161], v[242:245], v[2:5]
	s_setprio 0
	s_barrier
	s_add_i32 s54, s54, 2
	s_add_u32 s84, s84, 0x100
	s_addc_u32 s85, s85, 0
	s_add_u32 vcc_lo, vcc_lo, 0x100
	s_addc_u32 vcc_hi, vcc_hi, 0
	s_cmp_gt_u32 s54, 29
	s_branch .LBB0_255
.Lk0_Yz:
	ds_read_b128 v[130:133], v225
	ds_read_b128 v[134:137], v225 offset:1024
	ds_read_b128 v[138:141], v225 offset:2048
	ds_read_b128 v[142:145], v225 offset:3072
	ds_read_b128 v[146:149], v226
	ds_read_b128 v[150:153], v226 offset:1024
	ds_read_b128 v[154:157], v226 offset:2048
	ds_read_b128 v[158:161], v226 offset:3072
	s_add_u32 s24, s84, 0xfff80080
	s_addc_u32 s25, s85, -1
	s_cmp_eq_u32 s54, 28
	s_cselect_b32 s89, s13, s25
	s_cselect_b32 s88, s53, s24
	s_cselect_b32 s87, s77, vcc_hi
	s_cselect_b32 s86, s79, vcc_lo
	s_add_i32 m0, s95, 0xc000
	ds_read_b128 v[192:195], v227
	ds_read_b128 v[196:199], v227 offset:1024
	ds_read_b128 v[200:203], v227 offset:2048
	ds_read_b128 v[204:207], v227 offset:3072
	ds_read_b128 v[230:233], v227 offset:4096
	ds_read_b128 v[234:237], v227 offset:5120
	ds_read_b128 v[238:241], v227 offset:6144
	ds_read_b128 v[242:245], v227 offset:7168
	global_load_lds_dwordx4 v186, s[84:85]
	s_add_i32 m0, s95, 0xe000
	s_nop 0
	global_load_lds_dwordx4 v188, s[84:85]
	s_waitcnt vmcnt(8)
	s_waitcnt lgkmcnt(0)
	s_barrier
	s_setprio 3
	s_waitcnt lgkmcnt(0)
	v_mfma_f32_16x16x32_bf16 v[126:129], v[130:133], v[192:195], 0
	v_mfma_f32_16x16x32_bf16 v[122:125], v[138:141], v[192:195], 0
	v_mfma_f32_16x16x32_bf16 v[110:113], v[130:133], v[200:203], 0
	v_mfma_f32_16x16x32_bf16 v[106:109], v[138:141], v[200:203], 0
	v_mfma_f32_16x16x32_bf16 v[94:97], v[130:133], v[230:233], 0
	v_mfma_f32_16x16x32_bf16 v[90:93], v[138:141], v[230:233], 0
	v_mfma_f32_16x16x32_bf16 v[78:81], v[130:133], v[238:241], 0
	v_mfma_f32_16x16x32_bf16 v[74:77], v[138:141], v[238:241], 0
	v_mfma_f32_16x16x32_bf16 v[126:129], v[134:137], v[196:199], v[126:129]
	v_mfma_f32_16x16x32_bf16 v[122:125], v[142:145], v[196:199], v[122:125]
	v_mfma_f32_16x16x32_bf16 v[110:113], v[134:137], v[204:207], v[110:113]
	v_mfma_f32_16x16x32_bf16 v[106:109], v[142:145], v[204:207], v[106:109]
	v_mfma_f32_16x16x32_bf16 v[94:97], v[134:137], v[234:237], v[94:97]
	v_mfma_f32_16x16x32_bf16 v[90:93], v[142:145], v[234:237], v[90:93]
	v_mfma_f32_16x16x32_bf16 v[78:81], v[134:137], v[242:245], v[78:81]
	v_mfma_f32_16x16x32_bf16 v[74:77], v[142:145], v[242:245], v[74:77]


; #define PG8_STAGE(bufoff, gbase, voff) do { _Pragma("unroll") for (int _i = 0; _i < 2; ++_i) \
;         __builtin_amdgcn_global_load_lds((const unsigned*)((const char*)(gbase) + (voff)[_i]), (PG8_LAS unsigned*)(lds + (bufoff) + ldsw + _i * 8192), 16, 0, 0); } while (0)
; #define PG8_LDA(dst, b, h) do { _Pragma("unroll") for (int m = 0; m < 4; ++m) _Pragma("unroll") for (int k = 0; k < 2; ++k) dst[m][k] = *(const PG8_LAS bf16x8*)(lds + PG8_SA(b, h) + aoff + m * 2048 + k * 1024); } while (0)
; #define PG8_WAIT_V(n) asm volatile("s_waitcnt vmcnt(" #n ")" ::: "memory")
; #define PG8_WAIT_L(n) asm volatile("s_waitcnt lgkmcnt(" #n ")" ::: "memory")
; #define PG8_BAR __builtin_amdgcn_s_barrier()
; #define PG8_SCHED __builtin_amdgcn_sched_barrier(0)
; template <class Epi, class Sched, bool ALIGN_EPI = false, bool SP2 = false, bool F8 = false>
; __device__ __forceinline__ void gemm_phase(PG8_LAS unsigned char* lds, const Gemm g, const Sched& S, const Epi& E) {
;     ...
;             PG8_WAIT_V(8); PG8_WAIT_L(0); PG8_BAR; PG8_MMA(0, 0, At, B0); PG8_MMA(0, 1, At, B1); PG8_BAR; PG8_SCHED;
;             PG8_LDA(At, 0, 1); PG8_STAGE(PG8_SB(0, 0), b2, voffB); PG8_STAGE(PG8_SB(0, 1), b2 + hstep, voffB); PG8_STAGE(PG8_SA(0, 0), a2, voffA);
;             PG8_WAIT_V(8); PG8_WAIT_L(0); PG8_BAR; PG8_MMA(1, 0, At, B0); PG8_MMA(1, 1, At, B1); PG8_BAR; PG8_SCHED;
	v_mfma_f32_16x16x32_bf16 v[118:121], v[146:149], v[192:195], 0
	v_mfma_f32_16x16x32_bf16 v[114:117], v[154:157], v[192:195], 0
	v_mfma_f32_16x16x32_bf16 v[102:105], v[146:149], v[200:203], 0
	v_mfma_f32_16x16x32_bf16 v[98:101], v[154:157], v[200:203], 0
	v_mfma_f32_16x16x32_bf16 v[86:89], v[146:149], v[230:233], 0
	v_mfma_f32_16x16x32_bf16 v[82:85], v[154:157], v[230:233], 0
	v_mfma_f32_16x16x32_bf16 v[70:73], v[146:149], v[238:241], 0
	v_mfma_f32_16x16x32_bf16 v[66:69], v[154:157], v[238:241], 0
	v_mfma_f32_16x16x32_bf16 v[118:121], v[150:153], v[196:199], v[118:121]
	v_mfma_f32_16x16x32_bf16 v[114:117], v[158:161], v[196:199], v[114:117]
	v_mfma_f32_16x16x32_bf16 v[102:105], v[150:153], v[204:207], v[102:105]
	v_mfma_f32_16x16x32_bf16 v[98:101], v[158:161], v[204:207], v[98:101]
	v_mfma_f32_16x16x32_bf16 v[86:89], v[150:153], v[234:237], v[86:89]
	v_mfma_f32_16x16x32_bf16 v[82:85], v[158:161], v[234:237], v[82:85]
	v_mfma_f32_16x16x32_bf16 v[70:73], v[150:153], v[242:245], v[70:73]
	v_mfma_f32_16x16x32_bf16 v[66:69], v[158:161], v[242:245], v[66:69]
	s_setprio 0
	s_add_i32 s24, s45, s23
	s_mov_b32 m0, s24
	ds_read_b128 v[192:195], v227 offset:16384
	ds_read_b128 v[196:199], v227 offset:17408
	ds_read_b128 v[200:203], v227 offset:18432
	ds_read_b128 v[204:207], v227 offset:19456
	ds_read_b128 v[230:233], v227 offset:20480
	ds_read_b128 v[234:237], v227 offset:21504
	ds_read_b128 v[238:241], v227 offset:22528
	ds_read_b128 v[242:245], v227 offset:23552
	global_load_lds_dwordx4 v168, s[86:87]
	s_add_i32 m0, s24, 0x2000
	s_add_u32 s24, s86, 0x80000
	s_addc_u32 s25, s87, 0
	s_add_i32 s55, s33, s23
	global_load_lds_dwordx4 v164, s[86:87]
	s_mov_b32 m0, s55
	s_nop 0
	global_load_lds_dwordx4 v168, s[24:25]
	s_add_i32 m0, s55, 0x2000
	s_nop 0
	global_load_lds_dwordx4 v164, s[24:25]
	s_mov_b32 m0, s95
	s_nop 0
	global_load_lds_dwordx4 v170, s[88:89]
	s_mov_b32 m0, s96
	s_nop 0
	global_load_lds_dwordx4 v166, s[88:89]
	s_waitcnt vmcnt(8)
	s_waitcnt lgkmcnt(0)
	s_barrier
	s_setprio 3
	s_waitcnt lgkmcnt(0)
	v_mfma_f32_16x16x32_bf16 v[62:65], v[130:133], v[192:195], 0
	v_mfma_f32_16x16x32_bf16 v[58:61], v[138:141], v[192:195], 0
	v_mfma_f32_16x16x32_bf16 v[46:49], v[130:133], v[200:203], 0
	v_mfma_f32_16x16x32_bf16 v[42:45], v[138:141], v[200:203], 0
	v_mfma_f32_16x16x32_bf16 v[30:33], v[130:133], v[230:233], 0
	v_mfma_f32_16x16x32_bf16 v[26:29], v[138:141], v[230:233], 0
	v_mfma_f32_16x16x32_bf16 v[14:17], v[130:133], v[238:241], 0
	v_mfma_f32_16x16x32_bf16 v[10:13], v[138:141], v[238:241], 0
	v_mfma_f32_16x16x32_bf16 v[62:65], v[134:137], v[196:199], v[62:65]
	v_mfma_f32_16x16x32_bf16 v[58:61], v[142:145], v[196:199], v[58:61]
	v_mfma_f32_16x16x32_bf16 v[46:49], v[134:137], v[204:207], v[46:49]
	v_mfma_f32_16x16x32_bf16 v[42:45], v[142:145], v[204:207], v[42:45]
	v_mfma_f32_16x16x32_bf16 v[30:33], v[134:137], v[234:237], v[30:33]
	v_mfma_f32_16x16x32_bf16 v[26:29], v[142:145], v[234:237], v[26:29]
	v_mfma_f32_16x16x32_bf16 v[14:17], v[134:137], v[242:245], v[14:17]
	v_mfma_f32_16x16x32_bf16 v[10:13], v[142:145], v[242:245], v[10:13]


; #define PG8_STAGE(bufoff, gbase, voff) do { _Pragma("unroll") for (int _i = 0; _i < 2; ++_i) \
;         __builtin_amdgcn_global_load_lds((const unsigned*)((const char*)(gbase) + (voff)[_i]), (PG8_LAS unsigned*)(lds + (bufoff) + ldsw + _i * 8192), 16, 0, 0); } while (0)
; #define PG8_LDA(dst, b, h) do { _Pragma("unroll") for (int m = 0; m < 4; ++m) _Pragma("unroll") for (int k = 0; k < 2; ++k) dst[m][k] = *(const PG8_LAS bf16x8*)(lds + PG8_SA(b, h) + aoff + m * 2048 + k * 1024); } while (0)
; #define PG8_LDB(dst, b, h) do { _Pragma("unroll") for (int n = 0; n < 2; ++n) _Pragma("unroll") for (int k = 0; k < 2; ++k) dst[n][k] = *(const PG8_LAS bf16x8*)(lds + PG8_SB(b, h) + boff + n * 2048 + k * 1024); } while (0)
; #define PG8_WAIT_V(n) asm volatile("s_waitcnt vmcnt(" #n ")" ::: "memory")
; #define PG8_WAIT_L(n) asm volatile("s_waitcnt lgkmcnt(" #n ")" ::: "memory")
; #define PG8_BAR __builtin_amdgcn_s_barrier()
; #define PG8_SCHED __builtin_amdgcn_sched_barrier(0)
; template <class Epi, class Sched, bool ALIGN_EPI = false, bool SP2 = false, bool F8 = false>
; __device__ __forceinline__ void gemm_phase(PG8_LAS unsigned char* lds, const Gemm g, const Sched& S, const Epi& E) {
;     ...
;             PG8_WAIT_V(8); PG8_WAIT_L(0); PG8_BAR; PG8_MMA(1, 0, At, B0); PG8_MMA(1, 1, At, B1); PG8_BAR; PG8_SCHED;
;             PG8_LDB(B0, 1, 0); PG8_LDB(B1, 1, 1); PG8_SCHED; PG8_LDA(At, 1, 0); PG8_STAGE(PG8_SA(0, 1), a2 + hstepA, voffA);
;             PG8_WAIT_V(8); PG8_WAIT_L(0); PG8_BAR; PG8_MMA(0, 0, At, B0); PG8_MMA(0, 1, At, B1); PG8_BAR; PG8_SCHED;
	v_mfma_f32_16x16x32_bf16 v[54:57], v[146:149], v[192:195], 0
	v_mfma_f32_16x16x32_bf16 v[50:53], v[154:157], v[192:195], 0
	v_mfma_f32_16x16x32_bf16 v[38:41], v[146:149], v[200:203], 0
	v_mfma_f32_16x16x32_bf16 v[34:37], v[154:157], v[200:203], 0
	v_mfma_f32_16x16x32_bf16 v[22:25], v[146:149], v[230:233], 0
	v_mfma_f32_16x16x32_bf16 v[18:21], v[154:157], v[230:233], 0
	v_mfma_f32_16x16x32_bf16 v[6:9], v[146:149], v[238:241], 0
	v_mfma_f32_16x16x32_bf16 v[2:5], v[154:157], v[238:241], 0
	v_mfma_f32_16x16x32_bf16 v[54:57], v[150:153], v[196:199], v[54:57]
	v_mfma_f32_16x16x32_bf16 v[50:53], v[158:161], v[196:199], v[50:53]
	v_mfma_f32_16x16x32_bf16 v[38:41], v[150:153], v[204:207], v[38:41]
	v_mfma_f32_16x16x32_bf16 v[34:37], v[158:161], v[204:207], v[34:37]
	v_mfma_f32_16x16x32_bf16 v[22:25], v[150:153], v[234:237], v[22:25]
	v_mfma_f32_16x16x32_bf16 v[18:21], v[158:161], v[234:237], v[18:21]
	v_mfma_f32_16x16x32_bf16 v[6:9], v[150:153], v[242:245], v[6:9]
	v_mfma_f32_16x16x32_bf16 v[2:5], v[158:161], v[242:245], v[2:5]
	s_setprio 0
	s_add_i32 s55, 0, 0x18000
	s_add_i32 s36, 0, 0x1c000
	v_add_u32_e32 v142, s55, v222
	v_add_u32_e32 v158, s36, v222
	ds_read_b128 v[130:133], v142
	ds_read_b128 v[134:137], v142 offset:1024
	ds_read_b128 v[138:141], v142 offset:2048
	ds_read_b128 v[142:145], v142 offset:3072
	ds_read_b128 v[146:149], v158
	ds_read_b128 v[150:153], v158 offset:1024
	ds_read_b128 v[154:157], v158 offset:2048
	ds_read_b128 v[158:161], v158 offset:3072
	s_add_u32 s24, s88, 0x80000
	s_addc_u32 s25, s89, 0
	s_mov_b32 m0, s97
	ds_read_b128 v[192:195], v227 offset:32768
	ds_read_b128 v[196:199], v227 offset:33792
	ds_read_b128 v[200:203], v227 offset:34816
	ds_read_b128 v[204:207], v227 offset:35840
	ds_read_b128 v[230:233], v227 offset:36864
	ds_read_b128 v[234:237], v227 offset:37888
	ds_read_b128 v[238:241], v227 offset:38912
	ds_read_b128 v[242:245], v227 offset:39936
	global_load_lds_dwordx4 v170, s[24:25]
	s_mov_b32 m0, s28
	s_nop 0
	global_load_lds_dwordx4 v166, s[24:25]
	s_waitcnt vmcnt(8)
	s_waitcnt lgkmcnt(0)
	s_barrier
	s_setprio 3
	s_waitcnt lgkmcnt(0)
	v_mfma_f32_16x16x32_bf16 v[126:129], v[130:133], v[192:195], v[126:129]
	v_mfma_f32_16x16x32_bf16 v[122:125], v[138:141], v[192:195], v[122:125]
	v_mfma_f32_16x16x32_bf16 v[110:113], v[130:133], v[200:203], v[110:113]
	v_mfma_f32_16x16x32_bf16 v[106:109], v[138:141], v[200:203], v[106:109]
	v_mfma_f32_16x16x32_bf16 v[94:97], v[130:133], v[230:233], v[94:97]
	v_mfma_f32_16x16x32_bf16 v[90:93], v[138:141], v[230:233], v[90:93]
	v_mfma_f32_16x16x32_bf16 v[78:81], v[130:133], v[238:241], v[78:81]
	v_mfma_f32_16x16x32_bf16 v[74:77], v[138:141], v[238:241], v[74:77]
	v_mfma_f32_16x16x32_bf16 v[126:129], v[134:137], v[196:199], v[126:129]
	v_mfma_f32_16x16x32_bf16 v[122:125], v[142:145], v[196:199], v[122:125]
	v_mfma_f32_16x16x32_bf16 v[110:113], v[134:137], v[204:207], v[110:113]
	v_mfma_f32_16x16x32_bf16 v[106:109], v[142:145], v[204:207], v[106:109]
	v_mfma_f32_16x16x32_bf16 v[94:97], v[134:137], v[234:237], v[94:97]
	v_mfma_f32_16x16x32_bf16 v[90:93], v[142:145], v[234:237], v[90:93]
	v_mfma_f32_16x16x32_bf16 v[78:81], v[134:137], v[242:245], v[78:81]
	v_mfma_f32_16x16x32_bf16 v[74:77], v[142:145], v[242:245], v[74:77]


; #define PG8_STAGE(bufoff, gbase, voff) do { _Pragma("unroll") for (int _i = 0; _i < 2; ++_i) \
;         __builtin_amdgcn_global_load_lds((const unsigned*)((const char*)(gbase) + (voff)[_i]), (PG8_LAS unsigned*)(lds + (bufoff) + ldsw + _i * 8192), 16, 0, 0); } while (0)
; #define PG8_LDA(dst, b, h) do { _Pragma("unroll") for (int m = 0; m < 4; ++m) _Pragma("unroll") for (int k = 0; k < 2; ++k) dst[m][k] = *(const PG8_LAS bf16x8*)(lds + PG8_SA(b, h) + aoff + m * 2048 + k * 1024); } while (0)
; #define PG8_WAIT_V(n) asm volatile("s_waitcnt vmcnt(" #n ")" ::: "memory")
; #define PG8_WAIT_L(n) asm volatile("s_waitcnt lgkmcnt(" #n ")" ::: "memory")
; #define PG8_BAR __builtin_amdgcn_s_barrier()
; #define PG8_SCHED __builtin_amdgcn_sched_barrier(0)
; template <class Epi, class Sched, bool ALIGN_EPI = false, bool SP2 = false, bool F8 = false>
; __device__ __forceinline__ void gemm_phase(PG8_LAS unsigned char* lds, const Gemm g, const Sched& S, const Epi& E) {
;     ...
;             PG8_WAIT_V(8); PG8_WAIT_L(0); PG8_BAR; PG8_MMA(0, 0, At, B0); PG8_MMA(0, 1, At, B1); PG8_BAR; PG8_SCHED;
;             PG8_LDA(At, 1, 1); PG8_STAGE(PG8_SB(1, 0), b3, voffB); PG8_STAGE(PG8_SB(1, 1), b3 + hstep, voffB); PG8_STAGE(PG8_SA(1, 0), a3, voffA);
;             PG8_WAIT_V(8); PG8_WAIT_L(0); PG8_BAR; PG8_MMA(1, 0, At, B0); PG8_MMA(1, 1, At, B1); PG8_BAR; PG8_SCHED;
	v_mfma_f32_16x16x32_bf16 v[118:121], v[146:149], v[192:195], v[118:121]
	v_mfma_f32_16x16x32_bf16 v[114:117], v[154:157], v[192:195], v[114:117]
	v_mfma_f32_16x16x32_bf16 v[102:105], v[146:149], v[200:203], v[102:105]
	v_mfma_f32_16x16x32_bf16 v[98:101], v[154:157], v[200:203], v[98:101]
	v_mfma_f32_16x16x32_bf16 v[86:89], v[146:149], v[230:233], v[86:89]
	v_mfma_f32_16x16x32_bf16 v[82:85], v[154:157], v[230:233], v[82:85]
	v_mfma_f32_16x16x32_bf16 v[70:73], v[146:149], v[238:241], v[70:73]
	v_mfma_f32_16x16x32_bf16 v[66:69], v[154:157], v[238:241], v[66:69]
	v_mfma_f32_16x16x32_bf16 v[118:121], v[150:153], v[196:199], v[118:121]
	v_mfma_f32_16x16x32_bf16 v[114:117], v[158:161], v[196:199], v[114:117]
	v_mfma_f32_16x16x32_bf16 v[102:105], v[150:153], v[204:207], v[102:105]
	v_mfma_f32_16x16x32_bf16 v[98:101], v[158:161], v[204:207], v[98:101]
	v_mfma_f32_16x16x32_bf16 v[86:89], v[150:153], v[234:237], v[86:89]
	v_mfma_f32_16x16x32_bf16 v[82:85], v[158:161], v[234:237], v[82:85]
	v_mfma_f32_16x16x32_bf16 v[70:73], v[150:153], v[242:245], v[70:73]
	v_mfma_f32_16x16x32_bf16 v[66:69], v[158:161], v[242:245], v[66:69]
	s_setprio 0
	s_add_i32 s24, s55, s23
	s_mov_b32 m0, s24
	ds_read_b128 v[192:195], v227 offset:49152
	ds_read_b128 v[196:199], v227 offset:50176
	ds_read_b128 v[200:203], v227 offset:51200
	ds_read_b128 v[204:207], v227 offset:52224
	ds_read_b128 v[230:233], v227 offset:53248
	ds_read_b128 v[234:237], v227 offset:54272
	ds_read_b128 v[238:241], v227 offset:55296
	ds_read_b128 v[242:245], v227 offset:56320
	s_add_u32 s98, s86, 0x80
	s_addc_u32 s99, s87, 0
	global_load_lds_dwordx4 v168, s[98:99]
	s_add_i32 m0, s24, 0x2000
	s_add_u32 s24, s86, 0x80080
	s_addc_u32 s25, s87, 0
	s_add_i32 s36, s36, s23
	s_add_u32 s100, s86, 0x80
	s_addc_u32 s101, s87, 0
	global_load_lds_dwordx4 v164, s[100:101]
	s_mov_b32 m0, s36
	s_nop 0
	global_load_lds_dwordx4 v168, s[24:25]
	s_add_i32 m0, s36, 0x2000
	s_nop 0
	global_load_lds_dwordx4 v164, s[24:25]
	s_mov_b32 m0, s15
	s_nop 0
	s_add_u32 s98, s88, 0x80
	s_addc_u32 s99, s89, 0
	global_load_lds_dwordx4 v170, s[98:99]
	s_mov_b32 m0, s26
	s_nop 0
	s_add_u32 s100, s88, 0x80
	s_addc_u32 s101, s89, 0
	global_load_lds_dwordx4 v166, s[100:101]
	s_waitcnt vmcnt(8)
	s_waitcnt lgkmcnt(0)
	s_barrier
	s_setprio 3
	s_waitcnt lgkmcnt(0)
	v_mfma_f32_16x16x32_bf16 v[62:65], v[130:133], v[192:195], v[62:65]
	v_mfma_f32_16x16x32_bf16 v[58:61], v[138:141], v[192:195], v[58:61]
	v_mfma_f32_16x16x32_bf16 v[46:49], v[130:133], v[200:203], v[46:49]
	v_mfma_f32_16x16x32_bf16 v[42:45], v[138:141], v[200:203], v[42:45]
	v_mfma_f32_16x16x32_bf16 v[30:33], v[130:133], v[230:233], v[30:33]
	v_mfma_f32_16x16x32_bf16 v[26:29], v[138:141], v[230:233], v[26:29]
	v_mfma_f32_16x16x32_bf16 v[14:17], v[130:133], v[238:241], v[14:17]
	v_mfma_f32_16x16x32_bf16 v[10:13], v[138:141], v[238:241], v[10:13]
	v_mfma_f32_16x16x32_bf16 v[62:65], v[134:137], v[196:199], v[62:65]
	v_mfma_f32_16x16x32_bf16 v[58:61], v[142:145], v[196:199], v[58:61]
	v_mfma_f32_16x16x32_bf16 v[46:49], v[134:137], v[204:207], v[46:49]
	v_mfma_f32_16x16x32_bf16 v[42:45], v[142:145], v[204:207], v[42:45]
	v_mfma_f32_16x16x32_bf16 v[30:33], v[134:137], v[234:237], v[30:33]
	v_mfma_f32_16x16x32_bf16 v[26:29], v[142:145], v[234:237], v[26:29]
	v_mfma_f32_16x16x32_bf16 v[14:17], v[134:137], v[242:245], v[14:17]
	v_mfma_f32_16x16x32_bf16 v[10:13], v[142:145], v[242:245], v[10:13]


; #define PG8_WAIT_V(n) asm volatile("s_waitcnt vmcnt(" #n ")" ::: "memory")
; #define PG8_WAIT_L(n) asm volatile("s_waitcnt lgkmcnt(" #n ")" ::: "memory")
; #define PG8_BAR __builtin_amdgcn_s_barrier()
; #define PG8_SCHED __builtin_amdgcn_sched_barrier(0)
; template <class Epi, class Sched, bool ALIGN_EPI = false, bool SP2 = false, bool F8 = false>
; __device__ __forceinline__ void gemm_phase(PG8_LAS unsigned char* lds, const Gemm g, const Sched& S, const Epi& E) {
;     ...
;         for (int t = 0; t < nt; t += 2) {
;     ...
;             PG8_WAIT_V(8); PG8_WAIT_L(0); PG8_BAR; PG8_MMA(1, 0, At, B0); PG8_MMA(1, 1, At, B1); PG8_BAR; PG8_SCHED;
	v_mfma_f32_16x16x32_bf16 v[54:57], v[146:149], v[192:195], v[54:57]
	v_mfma_f32_16x16x32_bf16 v[50:53], v[154:157], v[192:195], v[50:53]
	v_mfma_f32_16x16x32_bf16 v[38:41], v[146:149], v[200:203], v[38:41]
	v_mfma_f32_16x16x32_bf16 v[34:37], v[154:157], v[200:203], v[34:37]
	v_mfma_f32_16x16x32_bf16 v[22:25], v[146:149], v[230:233], v[22:25]
	v_mfma_f32_16x16x32_bf16 v[18:21], v[154:157], v[230:233], v[18:21]
	v_mfma_f32_16x16x32_bf16 v[6:9], v[146:149], v[238:241], v[6:9]
	v_mfma_f32_16x16x32_bf16 v[2:5], v[154:157], v[238:241], v[2:5]
	v_mfma_f32_16x16x32_bf16 v[54:57], v[150:153], v[196:199], v[54:57]
	v_mfma_f32_16x16x32_bf16 v[50:53], v[158:161], v[196:199], v[50:53]
	v_mfma_f32_16x16x32_bf16 v[38:41], v[150:153], v[204:207], v[38:41]
	v_mfma_f32_16x16x32_bf16 v[34:37], v[158:161], v[204:207], v[34:37]
	v_mfma_f32_16x16x32_bf16 v[22:25], v[150:153], v[234:237], v[22:25]
	v_mfma_f32_16x16x32_bf16 v[18:21], v[158:161], v[234:237], v[18:21]
	v_mfma_f32_16x16x32_bf16 v[6:9], v[150:153], v[242:245], v[6:9]
	v_mfma_f32_16x16x32_bf16 v[2:5], v[158:161], v[242:245], v[2:5]
	s_setprio 0
	s_add_i32 s54, s54, 2
	s_add_u32 s84, s84, 0x100
	s_addc_u32 s85, s85, 0
	s_add_u32 vcc_lo, vcc_lo, 0x100
	s_addc_u32 vcc_hi, vcc_hi, 0
	s_cmp_gt_u32 s54, 29
	s_branch .Lk0_Y

; template <class Epi, class Sched, bool ALIGN_EPI = false, bool SP2 = false, bool F8 = false>
; __device__ __forceinline__ void gemm_phase(PG8_LAS unsigned char* lds, const Gemm g, const Sched& S, const Epi& E) {
;     ...
;         const char* nA = has_next ? PG8_ABASE(nxt.pm) : cA; const char* nB = has_next ? (const char*)g.Bt + (size_t)nxt.pn * tstep : cB;
;     ...
; #pragma unroll
;         for (int a = 0; a < 2; ++a)
; #pragma unroll
;             for (int b = 0; b < 2; ++b)
; #pragma unroll
;                 for (int m = 0; m < 4; ++m)
; #pragma unroll
;                     for (int n = 0; n < 2; ++n) acc[a][b][m][n] = (f32x4){0.f, 0.f, 0.f, 0.f};
;         cur = nxt; cA = nA; cB = nB; ++ui;
.LBB0_290:
	s_ashr_i32 s65, s64, 31
	s_lshl_b64 s[24:25], s[64:65], 19
	s_add_u32 s66, s15, s24
	s_addc_u32 s67, s23, s25
	s_and_b64 s[24:25], s[54:55], exec
	s_cselect_b32 s7, s67, s73
	s_cselect_b32 s65, s66, s72
	s_ashr_i32 s63, s62, 31
	s_lshl_b64 s[24:25], s[62:63], 19
	s_add_u32 s68, s50, s24
	s_addc_u32 s69, s51, s25
	s_and_b64 s[24:25], s[54:55], exec
	s_cselect_b32 s63, s69, s75
	s_cselect_b32 s71, s68, s74
	s_add_u32 s72, s72, 0x40080
	s_addc_u32 s73, s73, 0
	s_add_u32 s85, s74, 0x100
	s_addc_u32 s86, s75, 0
	s_mov_b32 s87, -2
	s_cmp_lg_u64 s[8:9], 0
	s_cbranch_scc1 .Lk1_Yz
	s_branch .Lk1_Xz

; #define PG8_STAGE(bufoff, gbase, voff) do { _Pragma("unroll") for (int _i = 0; _i < 2; ++_i) \
;         __builtin_amdgcn_global_load_lds((const unsigned*)((const char*)(gbase) + (voff)[_i]), (PG8_LAS unsigned*)(lds + (bufoff) + ldsw + _i * 8192), 16, 0, 0); } while (0)
; #define PG8_LDA(dst, b, h) do { _Pragma("unroll") for (int m = 0; m < 4; ++m) _Pragma("unroll") for (int k = 0; k < 2; ++k) dst[m][k] = *(const PG8_LAS bf16x8*)(lds + PG8_SA(b, h) + aoff + m * 2048 + k * 1024); } while (0)
; #define PG8_LDB(dst, b, h) do { _Pragma("unroll") for (int n = 0; n < 2; ++n) _Pragma("unroll") for (int k = 0; k < 2; ++k) dst[n][k] = *(const PG8_LAS bf16x8*)(lds + PG8_SB(b, h) + boff + n * 2048 + k * 1024); } while (0)
; #define PG8_WAIT_V(n) asm volatile("s_waitcnt vmcnt(" #n ")" ::: "memory")
; #define PG8_WAIT_L(n) asm volatile("s_waitcnt lgkmcnt(" #n ")" ::: "memory")
; #define PG8_BAR __builtin_amdgcn_s_barrier()
; #define PG8_SCHED __builtin_amdgcn_sched_barrier(0)
; template <class Epi, class Sched, bool ALIGN_EPI = false, bool SP2 = false, bool F8 = false>
; __device__ __forceinline__ void gemm_phase(PG8_LAS unsigned char* lds, const Gemm g, const Sched& S, const Epi& E) {
;     ...
;             const bool last = (t == nt - 2);
;             const char* a1 = cA + (size_t)(t + 1) * kstep;
;             const char* a2 = last ? nA : cA + (size_t)(t + 2) * kstep; const char* b2 = last ? nB : cB + (size_t)(t + 2) * kstep;
;             const char* a3 = a2 + kstep; const char* b3 = b2 + kstep;
;             if (last && has_next) S.a_ready(nxt);
;             if constexpr (SP2) {
;             PG8_LDB(B0, 0, 0); PG8_LDB(B1, 0, 1); PG8_SCHED; PG8_LDA(At, 0, 0); PG8_STAGE(PG8_SA(1, 1), a1 + hstepA, voffA);
;             PG8_WAIT_V(8); PG8_WAIT_L(0); PG8_BAR; PG8_MMA(0, 0, At, B0); PG8_MMA(0, 1, At, B1); PG8_BAR; PG8_SCHED;
.Lk1_Y:
	ds_read_b128 v[26:29], v195
	ds_read_b128 v[30:33], v195 offset:1024
	ds_read_b128 v[18:21], v195 offset:2048
	ds_read_b128 v[22:25], v195 offset:3072
	ds_read_b128 v[10:13], v196
	ds_read_b128 v[14:17], v196 offset:1024
	ds_read_b128 v[2:5], v196 offset:2048
	ds_read_b128 v[6:9], v196 offset:3072
	s_add_u32 s24, s72, 0xfffc0080
	s_addc_u32 s25, s73, -1
	s_cmp_eq_u32 s87, 12
	s_cselect_b32 s77, s7, s25
	s_cselect_b32 s76, s65, s24
	s_cselect_b32 s75, s63, s86
	s_cselect_b32 s74, s71, s85
	s_add_i32 m0, s26, 0xc000
	ds_read_b128 v[182:185], v197
	ds_read_b128 v[186:189], v197 offset:1024
	ds_read_b128 v[200:203], v197 offset:2048
	ds_read_b128 v[204:207], v197 offset:3072
	ds_read_b128 v[208:211], v197 offset:4096
	ds_read_b128 v[212:215], v197 offset:5120
	ds_read_b128 v[218:221], v197 offset:6144
	ds_read_b128 v[222:225], v197 offset:7168
	global_load_lds_dwordx4 v178, s[72:73]
	s_add_i32 m0, s26, 0xe000
	s_nop 0
	global_load_lds_dwordx4 v180, s[72:73]
	s_waitcnt vmcnt(8)
	s_waitcnt lgkmcnt(0)
	s_barrier
	s_setprio 3
	s_waitcnt lgkmcnt(0)
	v_mfma_f32_16x16x128_f8f6f4 v[158:161], v[26:33], v[182:189], v[158:161]
	v_mfma_f32_16x16x128_f8f6f4 v[154:157], v[18:25], v[182:189], v[154:157]
	v_mfma_f32_16x16x128_f8f6f4 v[142:145], v[26:33], v[200:207], v[142:145]
	v_mfma_f32_16x16x128_f8f6f4 v[138:141], v[18:25], v[200:207], v[138:141]
	v_mfma_f32_16x16x128_f8f6f4 v[126:129], v[26:33], v[208:215], v[126:129]
	v_mfma_f32_16x16x128_f8f6f4 v[122:125], v[18:25], v[208:215], v[122:125]
	v_mfma_f32_16x16x128_f8f6f4 v[110:113], v[26:33], v[218:225], v[110:113]
	v_mfma_f32_16x16x128_f8f6f4 v[106:109], v[18:25], v[218:225], v[106:109]


; #define PG8_STAGE(bufoff, gbase, voff) do { _Pragma("unroll") for (int _i = 0; _i < 2; ++_i) \
;         __builtin_amdgcn_global_load_lds((const unsigned*)((const char*)(gbase) + (voff)[_i]), (PG8_LAS unsigned*)(lds + (bufoff) + ldsw + _i * 8192), 16, 0, 0); } while (0)
; #define PG8_LDA(dst, b, h) do { _Pragma("unroll") for (int m = 0; m < 4; ++m) _Pragma("unroll") for (int k = 0; k < 2; ++k) dst[m][k] = *(const PG8_LAS bf16x8*)(lds + PG8_SA(b, h) + aoff + m * 2048 + k * 1024); } while (0)
; #define PG8_WAIT_V(n) asm volatile("s_waitcnt vmcnt(" #n ")" ::: "memory")
; #define PG8_WAIT_L(n) asm volatile("s_waitcnt lgkmcnt(" #n ")" ::: "memory")
; #define PG8_BAR __builtin_amdgcn_s_barrier()
; #define PG8_SCHED __builtin_amdgcn_sched_barrier(0)
; template <class Epi, class Sched, bool ALIGN_EPI = false, bool SP2 = false, bool F8 = false>
; __device__ __forceinline__ void gemm_phase(PG8_LAS unsigned char* lds, const Gemm g, const Sched& S, const Epi& E) {
;     ...
;             PG8_WAIT_V(8); PG8_WAIT_L(0); PG8_BAR; PG8_MMA(0, 0, At, B0); PG8_MMA(0, 1, At, B1); PG8_BAR; PG8_SCHED;
;             PG8_LDA(At, 0, 1); PG8_STAGE(PG8_SB(0, 0), b2, voffB); PG8_STAGE(PG8_SB(0, 1), b2 + hstep, voffB); PG8_STAGE(PG8_SA(0, 0), a2, voffA);
;             PG8_WAIT_V(8); PG8_WAIT_L(0); PG8_BAR; PG8_MMA(1, 0, At, B0); PG8_MMA(1, 1, At, B1); PG8_BAR; PG8_SCHED;
	v_mfma_f32_16x16x128_f8f6f4 v[150:153], v[10:17], v[182:189], v[150:153]
	v_mfma_f32_16x16x128_f8f6f4 v[146:149], v[2:9], v[182:189], v[146:149]
	v_mfma_f32_16x16x128_f8f6f4 v[134:137], v[10:17], v[200:207], v[134:137]
	v_mfma_f32_16x16x128_f8f6f4 v[130:133], v[2:9], v[200:207], v[130:133]
	v_mfma_f32_16x16x128_f8f6f4 v[118:121], v[10:17], v[208:215], v[118:121]
	v_mfma_f32_16x16x128_f8f6f4 v[114:117], v[2:9], v[208:215], v[114:117]
	v_mfma_f32_16x16x128_f8f6f4 v[102:105], v[10:17], v[218:225], v[102:105]
	v_mfma_f32_16x16x128_f8f6f4 v[98:101], v[2:9], v[218:225], v[98:101]
	s_setprio 0
	s_add_i32 s24, s81, s14
	s_mov_b32 m0, s24
	ds_read_b128 v[200:203], v197 offset:16384
	ds_read_b128 v[204:207], v197 offset:17408
	ds_read_b128 v[208:211], v197 offset:18432
	ds_read_b128 v[212:215], v197 offset:19456
	ds_read_b128 v[218:221], v197 offset:20480
	ds_read_b128 v[222:225], v197 offset:21504
	ds_read_b128 v[226:229], v197 offset:22528
	ds_read_b128 v[230:233], v197 offset:23552
	global_load_lds_dwordx4 v166, s[74:75]
	s_add_i32 m0, s24, 0x2000
	s_add_u32 s24, s74, 0x40000
	s_addc_u32 s25, s75, 0
	s_add_i32 s36, s82, s14
	global_load_lds_dwordx4 v170, s[74:75]
	s_mov_b32 m0, s36
	s_nop 0
	global_load_lds_dwordx4 v166, s[24:25]
	s_add_i32 m0, s36, 0x2000
	s_nop 0
	global_load_lds_dwordx4 v170, s[24:25]
	s_mov_b32 m0, s26
	s_nop 0
	global_load_lds_dwordx4 v164, s[76:77]
	s_mov_b32 m0, s27
	s_nop 0
	global_load_lds_dwordx4 v168, s[76:77]
	s_waitcnt vmcnt(8)
	s_waitcnt lgkmcnt(0)
	s_barrier
	s_setprio 3
	s_waitcnt lgkmcnt(0)
	v_mfma_f32_16x16x128_f8f6f4 v[94:97], v[26:33], v[200:207], v[94:97]
	v_mfma_f32_16x16x128_f8f6f4 v[90:93], v[18:25], v[200:207], v[90:93]
	v_mfma_f32_16x16x128_f8f6f4 v[78:81], v[26:33], v[208:215], v[78:81]
	v_mfma_f32_16x16x128_f8f6f4 v[74:77], v[18:25], v[208:215], v[74:77]
	v_mfma_f32_16x16x128_f8f6f4 v[62:65], v[26:33], v[218:225], v[62:65]
	v_mfma_f32_16x16x128_f8f6f4 v[58:61], v[18:25], v[218:225], v[58:61]
	v_mfma_f32_16x16x128_f8f6f4 v[46:49], v[26:33], v[226:233], v[46:49]
	v_mfma_f32_16x16x128_f8f6f4 v[42:45], v[18:25], v[226:233], v[42:45]


; #define PG8_STAGE(bufoff, gbase, voff) do { _Pragma("unroll") for (int _i = 0; _i < 2; ++_i) \
;         __builtin_amdgcn_global_load_lds((const unsigned*)((const char*)(gbase) + (voff)[_i]), (PG8_LAS unsigned*)(lds + (bufoff) + ldsw + _i * 8192), 16, 0, 0); } while (0)
; #define PG8_LDA(dst, b, h) do { _Pragma("unroll") for (int m = 0; m < 4; ++m) _Pragma("unroll") for (int k = 0; k < 2; ++k) dst[m][k] = *(const PG8_LAS bf16x8*)(lds + PG8_SA(b, h) + aoff + m * 2048 + k * 1024); } while (0)
; #define PG8_LDB(dst, b, h) do { _Pragma("unroll") for (int n = 0; n < 2; ++n) _Pragma("unroll") for (int k = 0; k < 2; ++k) dst[n][k] = *(const PG8_LAS bf16x8*)(lds + PG8_SB(b, h) + boff + n * 2048 + k * 1024); } while (0)
; #define PG8_WAIT_V(n) asm volatile("s_waitcnt vmcnt(" #n ")" ::: "memory")
; #define PG8_WAIT_L(n) asm volatile("s_waitcnt lgkmcnt(" #n ")" ::: "memory")
; #define PG8_BAR __builtin_amdgcn_s_barrier()
; #define PG8_SCHED __builtin_amdgcn_sched_barrier(0)
; template <class Epi, class Sched, bool ALIGN_EPI = false, bool SP2 = false, bool F8 = false>
; __device__ __forceinline__ void gemm_phase(PG8_LAS unsigned char* lds, const Gemm g, const Sched& S, const Epi& E) {
;     ...
;             PG8_LDB(B0, 1, 0); PG8_LDB(B1, 1, 1); PG8_SCHED; PG8_LDA(At, 1, 0); PG8_STAGE(PG8_SA(0, 1), a2 + hstepA, voffA);
;             PG8_WAIT_V(8); PG8_WAIT_L(0); PG8_BAR; PG8_MMA(0, 0, At, B0); PG8_MMA(0, 1, At, B1); PG8_BAR; PG8_SCHED;
	v_mfma_f32_16x16x128_f8f6f4 v[86:89], v[10:17], v[200:207], v[86:89]
	v_mfma_f32_16x16x128_f8f6f4 v[82:85], v[2:9], v[200:207], v[82:85]
	v_mfma_f32_16x16x128_f8f6f4 v[70:73], v[10:17], v[208:215], v[70:73]
	v_mfma_f32_16x16x128_f8f6f4 v[66:69], v[2:9], v[208:215], v[66:69]
	v_mfma_f32_16x16x128_f8f6f4 v[54:57], v[10:17], v[218:225], v[54:57]
	v_mfma_f32_16x16x128_f8f6f4 v[50:53], v[2:9], v[218:225], v[50:53]
	v_mfma_f32_16x16x128_f8f6f4 v[38:41], v[10:17], v[226:233], v[38:41]
	v_mfma_f32_16x16x128_f8f6f4 v[34:37], v[2:9], v[226:233], v[34:37]
	s_setprio 0
	s_add_i32 s36, 0, 0x18000
	s_add_i32 s37, 0, 0x1c000
	v_add_u32_e32 v14, s36, v190
	v_add_u32_e32 v30, s37, v190
	ds_read_b128 v[2:5], v14
	ds_read_b128 v[6:9], v14 offset:1024
	ds_read_b128 v[10:13], v14 offset:2048
	ds_read_b128 v[14:17], v14 offset:3072
	ds_read_b128 v[18:21], v30
	ds_read_b128 v[22:25], v30 offset:1024
	ds_read_b128 v[26:29], v30 offset:2048
	ds_read_b128 v[30:33], v30 offset:3072
	s_add_u32 s24, s76, 0x40000
	s_addc_u32 s25, s77, 0
	s_mov_b32 m0, s28
	ds_read_b128 v[200:203], v197 offset:32768
	ds_read_b128 v[204:207], v197 offset:33792
	ds_read_b128 v[208:211], v197 offset:34816
	ds_read_b128 v[212:215], v197 offset:35840
	ds_read_b128 v[218:221], v197 offset:36864
	ds_read_b128 v[222:225], v197 offset:37888
	ds_read_b128 v[226:229], v197 offset:38912
	ds_read_b128 v[230:233], v197 offset:39936
	global_load_lds_dwordx4 v164, s[24:25]
	s_mov_b32 m0, s29
	s_nop 0
	global_load_lds_dwordx4 v168, s[24:25]
	s_waitcnt vmcnt(8)
	s_waitcnt lgkmcnt(0)
	s_barrier
	s_setprio 3
	s_waitcnt lgkmcnt(0)
	v_mfma_f32_16x16x128_f8f6f4 v[158:161], v[2:9], v[200:207], v[158:161]
	v_mfma_f32_16x16x128_f8f6f4 v[154:157], v[10:17], v[200:207], v[154:157]
	v_mfma_f32_16x16x128_f8f6f4 v[142:145], v[2:9], v[208:215], v[142:145]
	v_mfma_f32_16x16x128_f8f6f4 v[138:141], v[10:17], v[208:215], v[138:141]
	v_mfma_f32_16x16x128_f8f6f4 v[126:129], v[2:9], v[218:225], v[126:129]
	v_mfma_f32_16x16x128_f8f6f4 v[122:125], v[10:17], v[218:225], v[122:125]
	v_mfma_f32_16x16x128_f8f6f4 v[110:113], v[2:9], v[226:233], v[110:113]
	v_mfma_f32_16x16x128_f8f6f4 v[106:109], v[10:17], v[226:233], v[106:109]


; #define PG8_STAGE(bufoff, gbase, voff) do { _Pragma("unroll") for (int _i = 0; _i < 2; ++_i) \
;         __builtin_amdgcn_global_load_lds((const unsigned*)((const char*)(gbase) + (voff)[_i]), (PG8_LAS unsigned*)(lds + (bufoff) + ldsw + _i * 8192), 16, 0, 0); } while (0)
; #define PG8_LDA(dst, b, h) do { _Pragma("unroll") for (int m = 0; m < 4; ++m) _Pragma("unroll") for (int k = 0; k < 2; ++k) dst[m][k] = *(const PG8_LAS bf16x8*)(lds + PG8_SA(b, h) + aoff + m * 2048 + k * 1024); } while (0)
; #define PG8_WAIT_V(n) asm volatile("s_waitcnt vmcnt(" #n ")" ::: "memory")
; #define PG8_WAIT_L(n) asm volatile("s_waitcnt lgkmcnt(" #n ")" ::: "memory")
; #define PG8_BAR __builtin_amdgcn_s_barrier()
; #define PG8_SCHED __builtin_amdgcn_sched_barrier(0)
; template <class Epi, class Sched, bool ALIGN_EPI = false, bool SP2 = false, bool F8 = false>
; __device__ __forceinline__ void gemm_phase(PG8_LAS unsigned char* lds, const Gemm g, const Sched& S, const Epi& E) {
;     ...
;             PG8_WAIT_V(8); PG8_WAIT_L(0); PG8_BAR; PG8_MMA(0, 0, At, B0); PG8_MMA(0, 1, At, B1); PG8_BAR; PG8_SCHED;
;             PG8_LDA(At, 1, 1); PG8_STAGE(PG8_SB(1, 0), b3, voffB); PG8_STAGE(PG8_SB(1, 1), b3 + hstep, voffB); PG8_STAGE(PG8_SA(1, 0), a3, voffA);
;             PG8_WAIT_V(8); PG8_WAIT_L(0); PG8_BAR; PG8_MMA(1, 0, At, B0); PG8_MMA(1, 1, At, B1); PG8_BAR; PG8_SCHED;
	v_mfma_f32_16x16x128_f8f6f4 v[150:153], v[18:25], v[200:207], v[150:153]
	v_mfma_f32_16x16x128_f8f6f4 v[146:149], v[26:33], v[200:207], v[146:149]
	v_mfma_f32_16x16x128_f8f6f4 v[134:137], v[18:25], v[208:215], v[134:137]
	v_mfma_f32_16x16x128_f8f6f4 v[130:133], v[26:33], v[208:215], v[130:133]
	v_mfma_f32_16x16x128_f8f6f4 v[118:121], v[18:25], v[218:225], v[118:121]
	v_mfma_f32_16x16x128_f8f6f4 v[114:117], v[26:33], v[218:225], v[114:117]
	v_mfma_f32_16x16x128_f8f6f4 v[102:105], v[18:25], v[226:233], v[102:105]
	v_mfma_f32_16x16x128_f8f6f4 v[98:101], v[26:33], v[226:233], v[98:101]
	s_setprio 0
	s_add_i32 s24, s36, s14
	s_mov_b32 m0, s24
	ds_read_b128 v[200:203], v197 offset:49152
	ds_read_b128 v[204:207], v197 offset:50176
	ds_read_b128 v[208:211], v197 offset:51200
	ds_read_b128 v[212:215], v197 offset:52224
	ds_read_b128 v[218:221], v197 offset:53248
	ds_read_b128 v[222:225], v197 offset:54272
	ds_read_b128 v[226:229], v197 offset:55296
	ds_read_b128 v[230:233], v197 offset:56320
	s_add_u32 s98, s74, 0x80
	s_addc_u32 s99, s75, 0
	global_load_lds_dwordx4 v166, s[98:99]
	s_add_i32 m0, s24, 0x2000
	s_add_u32 s24, s74, 0x40080
	s_addc_u32 s25, s75, 0
	s_add_i32 s36, s37, s14
	s_add_u32 s100, s74, 0x80
	s_addc_u32 s101, s75, 0
	global_load_lds_dwordx4 v170, s[100:101]
	s_mov_b32 m0, s36
	s_nop 0
	global_load_lds_dwordx4 v166, s[24:25]
	s_add_i32 m0, s36, 0x2000
	s_nop 0
	global_load_lds_dwordx4 v170, s[24:25]
	s_mov_b32 m0, s45
	s_nop 0
	s_add_u32 s98, s76, 0x80
	s_addc_u32 s99, s77, 0
	global_load_lds_dwordx4 v164, s[98:99]
	s_mov_b32 m0, s78
	s_nop 0
	s_add_u32 s100, s76, 0x80
	s_addc_u32 s101, s77, 0
	global_load_lds_dwordx4 v168, s[100:101]
	s_waitcnt vmcnt(8)
	s_waitcnt lgkmcnt(0)
	s_barrier
	s_setprio 3
	s_waitcnt lgkmcnt(0)
	v_mfma_f32_16x16x128_f8f6f4 v[94:97], v[2:9], v[200:207], v[94:97]
	v_mfma_f32_16x16x128_f8f6f4 v[90:93], v[10:17], v[200:207], v[90:93]
	v_mfma_f32_16x16x128_f8f6f4 v[78:81], v[2:9], v[208:215], v[78:81]
	v_mfma_f32_16x16x128_f8f6f4 v[74:77], v[10:17], v[208:215], v[74:77]
	v_mfma_f32_16x16x128_f8f6f4 v[62:65], v[2:9], v[218:225], v[62:65]
	v_mfma_f32_16x16x128_f8f6f4 v[58:61], v[10:17], v[218:225], v[58:61]
	v_mfma_f32_16x16x128_f8f6f4 v[46:49], v[2:9], v[226:233], v[46:49]
	v_mfma_f32_16x16x128_f8f6f4 v[42:45], v[10:17], v[226:233], v[42:45]


; #define PG8_STAGE(bufoff, gbase, voff) do { _Pragma("unroll") for (int _i = 0; _i < 2; ++_i) \
;         __builtin_amdgcn_global_load_lds((const unsigned*)((const char*)(gbase) + (voff)[_i]), (PG8_LAS unsigned*)(lds + (bufoff) + ldsw + _i * 8192), 16, 0, 0); } while (0)
; #define PG8_LDA(dst, b, h) do { _Pragma("unroll") for (int m = 0; m < 4; ++m) _Pragma("unroll") for (int k = 0; k < 2; ++k) dst[m][k] = *(const PG8_LAS bf16x8*)(lds + PG8_SA(b, h) + aoff + m * 2048 + k * 1024); } while (0)
; #define PG8_LDB(dst, b, h) do { _Pragma("unroll") for (int n = 0; n < 2; ++n) _Pragma("unroll") for (int k = 0; k < 2; ++k) dst[n][k] = *(const PG8_LAS bf16x8*)(lds + PG8_SB(b, h) + boff + n * 2048 + k * 1024); } while (0)
; #define PG8_WAIT_V(n) asm volatile("s_waitcnt vmcnt(" #n ")" ::: "memory")
; #define PG8_WAIT_L(n) asm volatile("s_waitcnt lgkmcnt(" #n ")" ::: "memory")
; #define PG8_BAR __builtin_amdgcn_s_barrier()
; #define PG8_SCHED __builtin_amdgcn_sched_barrier(0)
; template <class Epi, class Sched, bool ALIGN_EPI = false, bool SP2 = false, bool F8 = false>
; __device__ __forceinline__ void gemm_phase(PG8_LAS unsigned char* lds, const Gemm g, const Sched& S, const Epi& E) {
;     ...
;             PG8_LDB(B0, 0, 0); PG8_LDB(B1, 0, 1); PG8_SCHED; PG8_LDA(At, 0, 0); PG8_STAGE(PG8_SA(1, 1), a1 + hstepA, voffA);
;             PG8_WAIT_V(8); PG8_WAIT_L(0); PG8_BAR; PG8_MMA(0, 0, At, B0); PG8_MMA(0, 1, At, B1); PG8_BAR; PG8_SCHED;
;             PG8_LDA(At, 0, 1); PG8_STAGE(PG8_SB(0, 0), b2, voffB); PG8_STAGE(PG8_SB(0, 1), b2 + hstep, voffB); PG8_STAGE(PG8_SA(0, 0), a2, voffA);
;             PG8_WAIT_V(8); PG8_WAIT_L(0); PG8_BAR; PG8_MMA(1, 0, At, B0); PG8_MMA(1, 1, At, B1); PG8_BAR; PG8_SCHED;
	v_mfma_f32_16x16x128_f8f6f4 v[86:89], v[18:25], v[200:207], v[86:89]
	v_mfma_f32_16x16x128_f8f6f4 v[82:85], v[26:33], v[200:207], v[82:85]
	v_mfma_f32_16x16x128_f8f6f4 v[70:73], v[18:25], v[208:215], v[70:73]
	v_mfma_f32_16x16x128_f8f6f4 v[66:69], v[26:33], v[208:215], v[66:69]
	v_mfma_f32_16x16x128_f8f6f4 v[54:57], v[18:25], v[218:225], v[54:57]
	v_mfma_f32_16x16x128_f8f6f4 v[50:53], v[26:33], v[218:225], v[50:53]
	v_mfma_f32_16x16x128_f8f6f4 v[38:41], v[18:25], v[226:233], v[38:41]
	v_mfma_f32_16x16x128_f8f6f4 v[34:37], v[26:33], v[226:233], v[34:37]
	s_setprio 0
	s_add_i32 s87, s87, 2
	s_add_u32 s72, s72, 0x100
	s_addc_u32 s73, s73, 0
	s_add_u32 s85, s85, 0x100
	s_addc_u32 s86, s86, 0
	s_cmp_gt_u32 s87, 13
	s_cbranch_scc0 .Lk1_Y
	s_branch .Lk1_exit
.Lk1_Xz:
	ds_read_b128 v[26:29], v195
	ds_read_b128 v[30:33], v195 offset:1024
	ds_read_b128 v[18:21], v195 offset:2048
	ds_read_b128 v[22:25], v195 offset:3072
	ds_read_b128 v[10:13], v196
	ds_read_b128 v[14:17], v196 offset:1024
	ds_read_b128 v[2:5], v196 offset:2048
	ds_read_b128 v[6:9], v196 offset:3072
	s_add_u32 s24, s72, 0xfffc0080
	s_addc_u32 s25, s73, -1
	s_cmp_eq_u32 s87, 12
	s_cselect_b32 s77, s7, s25
	s_cselect_b32 s76, s65, s24
	s_cselect_b32 s75, s63, s86
	s_cselect_b32 s74, s71, s85
	s_add_i32 m0, s26, 0xc000
	ds_read_b128 v[182:185], v197
	ds_read_b128 v[186:189], v197 offset:1024
	ds_read_b128 v[200:203], v197 offset:2048
	ds_read_b128 v[204:207], v197 offset:3072
	ds_read_b128 v[208:211], v197 offset:4096
	ds_read_b128 v[212:215], v197 offset:5120
	ds_read_b128 v[218:221], v197 offset:6144
	ds_read_b128 v[222:225], v197 offset:7168
	global_load_lds_dwordx4 v178, s[72:73]
	s_add_i32 m0, s26, 0xe000
	s_nop 0
	global_load_lds_dwordx4 v180, s[72:73]
	s_waitcnt vmcnt(8)
	s_waitcnt lgkmcnt(0)
	s_setprio 1
	s_waitcnt lgkmcnt(0)
	v_mfma_f32_16x16x128_f8f6f4 v[158:161], v[26:33], v[182:189], 0
	v_mfma_f32_16x16x128_f8f6f4 v[154:157], v[18:25], v[182:189], 0
	v_mfma_f32_16x16x128_f8f6f4 v[142:145], v[26:33], v[200:207], 0
	v_mfma_f32_16x16x128_f8f6f4 v[138:141], v[18:25], v[200:207], 0
	v_mfma_f32_16x16x128_f8f6f4 v[126:129], v[26:33], v[208:215], 0
	v_mfma_f32_16x16x128_f8f6f4 v[122:125], v[18:25], v[208:215], 0
	v_mfma_f32_16x16x128_f8f6f4 v[110:113], v[26:33], v[218:225], 0
	v_mfma_f32_16x16x128_f8f6f4 v[106:109], v[18:25], v[218:225], 0
	s_setprio 0
	s_setprio 1
	v_mfma_f32_16x16x128_f8f6f4 v[150:153], v[10:17], v[182:189], 0
	v_mfma_f32_16x16x128_f8f6f4 v[146:149], v[2:9], v[182:189], 0
	v_mfma_f32_16x16x128_f8f6f4 v[134:137], v[10:17], v[200:207], 0
	v_mfma_f32_16x16x128_f8f6f4 v[130:133], v[2:9], v[200:207], 0
	v_mfma_f32_16x16x128_f8f6f4 v[118:121], v[10:17], v[208:215], 0
	v_mfma_f32_16x16x128_f8f6f4 v[114:117], v[2:9], v[208:215], 0
	v_mfma_f32_16x16x128_f8f6f4 v[102:105], v[10:17], v[218:225], 0
	v_mfma_f32_16x16x128_f8f6f4 v[98:101], v[2:9], v[218:225], 0
	s_setprio 0
	s_barrier
	s_add_i32 s24, s81, s14
	s_mov_b32 m0, s24
	ds_read_b128 v[200:203], v197 offset:16384
	ds_read_b128 v[204:207], v197 offset:17408
	ds_read_b128 v[208:211], v197 offset:18432
	ds_read_b128 v[212:215], v197 offset:19456
	ds_read_b128 v[218:221], v197 offset:20480
	ds_read_b128 v[222:225], v197 offset:21504
	ds_read_b128 v[226:229], v197 offset:22528
	ds_read_b128 v[230:233], v197 offset:23552
	global_load_lds_dwordx4 v166, s[74:75]
	s_add_i32 m0, s24, 0x2000
	s_add_u32 s24, s74, 0x40000
	s_addc_u32 s25, s75, 0
	s_add_i32 s36, s82, s14
	global_load_lds_dwordx4 v170, s[74:75]
	s_mov_b32 m0, s36
	s_nop 0
	global_load_lds_dwordx4 v166, s[24:25]
	s_add_i32 m0, s36, 0x2000
	s_nop 0
	global_load_lds_dwordx4 v170, s[24:25]
	s_mov_b32 m0, s26
	s_nop 0
	global_load_lds_dwordx4 v164, s[76:77]
	s_mov_b32 m0, s27
	s_nop 0
	global_load_lds_dwordx4 v168, s[76:77]
	s_waitcnt vmcnt(8)
	s_waitcnt lgkmcnt(0)
	s_setprio 1
	s_waitcnt lgkmcnt(0)
	v_mfma_f32_16x16x128_f8f6f4 v[94:97], v[26:33], v[200:207], 0
	v_mfma_f32_16x16x128_f8f6f4 v[90:93], v[18:25], v[200:207], 0
	v_mfma_f32_16x16x128_f8f6f4 v[78:81], v[26:33], v[208:215], 0
	v_mfma_f32_16x16x128_f8f6f4 v[74:77], v[18:25], v[208:215], 0
	v_mfma_f32_16x16x128_f8f6f4 v[62:65], v[26:33], v[218:225], 0
	v_mfma_f32_16x16x128_f8f6f4 v[58:61], v[18:25], v[218:225], 0
	v_mfma_f32_16x16x128_f8f6f4 v[46:49], v[26:33], v[226:233], 0
	v_mfma_f32_16x16x128_f8f6f4 v[42:45], v[18:25], v[226:233], 0
	s_setprio 0
	s_setprio 1
	v_mfma_f32_16x16x128_f8f6f4 v[86:89], v[10:17], v[200:207], 0
	v_mfma_f32_16x16x128_f8f6f4 v[82:85], v[2:9], v[200:207], 0
	v_mfma_f32_16x16x128_f8f6f4 v[70:73], v[10:17], v[208:215], 0
	v_mfma_f32_16x16x128_f8f6f4 v[66:69], v[2:9], v[208:215], 0
	v_mfma_f32_16x16x128_f8f6f4 v[54:57], v[10:17], v[218:225], 0
	v_mfma_f32_16x16x128_f8f6f4 v[50:53], v[2:9], v[218:225], 0
	v_mfma_f32_16x16x128_f8f6f4 v[38:41], v[10:17], v[226:233], 0
	v_mfma_f32_16x16x128_f8f6f4 v[34:37], v[2:9], v[226:233], 0
	s_setprio 0
	s_barrier
; #define PG8_STAGE(bufoff, gbase, voff) do { _Pragma("unroll") for (int _i = 0; _i < 2; ++_i) \
;         __builtin_amdgcn_global_load_lds((const unsigned*)((const char*)(gbase) + (voff)[_i]), (PG8_LAS unsigned*)(lds + (bufoff) + ldsw + _i * 8192), 16, 0, 0); } while (0)
; #define PG8_LDA(dst, b, h) do { _Pragma("unroll") for (int m = 0; m < 4; ++m) _Pragma("unroll") for (int k = 0; k < 2; ++k) dst[m][k] = *(const PG8_LAS bf16x8*)(lds + PG8_SA(b, h) + aoff + m * 2048 + k * 1024); } while (0)
; #define PG8_LDB(dst, b, h) do { _Pragma("unroll") for (int n = 0; n < 2; ++n) _Pragma("unroll") for (int k = 0; k < 2; ++k) dst[n][k] = *(const PG8_LAS bf16x8*)(lds + PG8_SB(b, h) + boff + n * 2048 + k * 1024); } while (0)
; #define PG8_WAIT_V(n) asm volatile("s_waitcnt vmcnt(" #n ")" ::: "memory")
; #define PG8_WAIT_L(n) asm volatile("s_waitcnt lgkmcnt(" #n ")" ::: "memory")
; #define PG8_BAR __builtin_amdgcn_s_barrier()
; #define PG8_SCHED __builtin_amdgcn_sched_barrier(0)
; template <class Epi, class Sched, bool ALIGN_EPI = false, bool SP2 = false, bool F8 = false>
; __device__ __forceinline__ void gemm_phase(PG8_LAS unsigned char* lds, const Gemm g, const Sched& S, const Epi& E) {
;     ...
;             PG8_LDB(B0, 0, 0); PG8_LDB(B1, 0, 1); PG8_SCHED; PG8_LDA(At, 0, 0); PG8_STAGE(PG8_SA(1, 1), a1 + hstepA, voffA);
;             PG8_WAIT_V(8); PG8_WAIT_L(0); PG8_BAR; PG8_MMA(0, 0, At, B0); PG8_MMA(0, 1, At, B1); PG8_BAR; PG8_SCHED;
;             PG8_LDA(At, 0, 1); PG8_STAGE(PG8_SB(0, 0), b2, voffB); PG8_STAGE(PG8_SB(0, 1), b2 + hstep, voffB); PG8_STAGE(PG8_SA(0, 0), a2, voffA);
;             PG8_WAIT_V(8); PG8_WAIT_L(0); PG8_BAR; PG8_MMA(1, 0, At, B0); PG8_MMA(1, 1, At, B1); PG8_BAR; PG8_SCHED;
;             PG8_LDB(B0, 1, 0); PG8_LDB(B1, 1, 1); PG8_SCHED; PG8_LDA(At, 1, 0); PG8_STAGE(PG8_SA(0, 1), a2 + hstepA, voffA);
;             PG8_WAIT_V(8); PG8_WAIT_L(0); PG8_BAR; PG8_MMA(0, 0, At, B0); PG8_MMA(0, 1, At, B1); PG8_BAR; PG8_SCHED;
;             PG8_LDA(At, 1, 1); PG8_STAGE(PG8_SB(1, 0), b3, voffB); PG8_STAGE(PG8_SB(1, 1), b3 + hstep, voffB); PG8_STAGE(PG8_SA(1, 0), a3, voffA);
;             PG8_WAIT_V(8); PG8_WAIT_L(0); PG8_BAR; PG8_MMA(1, 0, At, B0); PG8_MMA(1, 1, At, B1); PG8_BAR; PG8_SCHED;
	s_add_i32 s36, 0, 0x18000
	s_add_i32 s37, 0, 0x1c000
	v_add_u32_e32 v14, s36, v190
	v_add_u32_e32 v30, s37, v190
	ds_read_b128 v[2:5], v14
	ds_read_b128 v[6:9], v14 offset:1024
	ds_read_b128 v[10:13], v14 offset:2048
	ds_read_b128 v[14:17], v14 offset:3072
	ds_read_b128 v[18:21], v30
	ds_read_b128 v[22:25], v30 offset:1024
	ds_read_b128 v[26:29], v30 offset:2048
	ds_read_b128 v[30:33], v30 offset:3072
	s_add_u32 s24, s76, 0x40000
	s_addc_u32 s25, s77, 0
	s_mov_b32 m0, s28
	ds_read_b128 v[200:203], v197 offset:32768
	ds_read_b128 v[204:207], v197 offset:33792
	ds_read_b128 v[208:211], v197 offset:34816
	ds_read_b128 v[212:215], v197 offset:35840
	ds_read_b128 v[218:221], v197 offset:36864
	ds_read_b128 v[222:225], v197 offset:37888
	ds_read_b128 v[226:229], v197 offset:38912
	ds_read_b128 v[230:233], v197 offset:39936
	global_load_lds_dwordx4 v164, s[24:25]
	s_mov_b32 m0, s29
	s_nop 0
	global_load_lds_dwordx4 v168, s[24:25]
	s_waitcnt vmcnt(8)
	s_waitcnt lgkmcnt(0)
	s_setprio 1
	s_waitcnt lgkmcnt(0)
	v_mfma_f32_16x16x128_f8f6f4 v[158:161], v[2:9], v[200:207], v[158:161]
	v_mfma_f32_16x16x128_f8f6f4 v[154:157], v[10:17], v[200:207], v[154:157]
	v_mfma_f32_16x16x128_f8f6f4 v[142:145], v[2:9], v[208:215], v[142:145]
	v_mfma_f32_16x16x128_f8f6f4 v[138:141], v[10:17], v[208:215], v[138:141]
	v_mfma_f32_16x16x128_f8f6f4 v[126:129], v[2:9], v[218:225], v[126:129]
	v_mfma_f32_16x16x128_f8f6f4 v[122:125], v[10:17], v[218:225], v[122:125]
	v_mfma_f32_16x16x128_f8f6f4 v[110:113], v[2:9], v[226:233], v[110:113]
	v_mfma_f32_16x16x128_f8f6f4 v[106:109], v[10:17], v[226:233], v[106:109]
	s_setprio 0
	s_setprio 1
	v_mfma_f32_16x16x128_f8f6f4 v[150:153], v[18:25], v[200:207], v[150:153]
	v_mfma_f32_16x16x128_f8f6f4 v[146:149], v[26:33], v[200:207], v[146:149]
	v_mfma_f32_16x16x128_f8f6f4 v[134:137], v[18:25], v[208:215], v[134:137]
	v_mfma_f32_16x16x128_f8f6f4 v[130:133], v[26:33], v[208:215], v[130:133]
	v_mfma_f32_16x16x128_f8f6f4 v[118:121], v[18:25], v[218:225], v[118:121]
	v_mfma_f32_16x16x128_f8f6f4 v[114:117], v[26:33], v[218:225], v[114:117]
	v_mfma_f32_16x16x128_f8f6f4 v[102:105], v[18:25], v[226:233], v[102:105]
	v_mfma_f32_16x16x128_f8f6f4 v[98:101], v[26:33], v[226:233], v[98:101]
	s_setprio 0
	s_barrier
	s_add_i32 s24, s36, s14
	s_mov_b32 m0, s24
	ds_read_b128 v[200:203], v197 offset:49152
	ds_read_b128 v[204:207], v197 offset:50176
	ds_read_b128 v[208:211], v197 offset:51200
	ds_read_b128 v[212:215], v197 offset:52224
	ds_read_b128 v[218:221], v197 offset:53248
	ds_read_b128 v[222:225], v197 offset:54272
	ds_read_b128 v[226:229], v197 offset:55296
	ds_read_b128 v[230:233], v197 offset:56320
	s_add_u32 s98, s74, 0x80
	s_addc_u32 s99, s75, 0
	global_load_lds_dwordx4 v166, s[98:99]
	s_add_i32 m0, s24, 0x2000
	s_add_u32 s24, s74, 0x40080
	s_addc_u32 s25, s75, 0
	s_add_i32 s36, s37, s14
	s_add_u32 s100, s74, 0x80
	s_addc_u32 s101, s75, 0
	global_load_lds_dwordx4 v170, s[100:101]
	s_mov_b32 m0, s36
	s_nop 0
	global_load_lds_dwordx4 v166, s[24:25]
	s_add_i32 m0, s36, 0x2000
	s_nop 0
	global_load_lds_dwordx4 v170, s[24:25]
	s_mov_b32 m0, s45
	s_nop 0
	s_add_u32 s98, s76, 0x80
	s_addc_u32 s99, s77, 0
	global_load_lds_dwordx4 v164, s[98:99]
	s_mov_b32 m0, s78
	s_nop 0
	s_add_u32 s100, s76, 0x80
	s_addc_u32 s101, s77, 0
	global_load_lds_dwordx4 v168, s[100:101]
	s_waitcnt vmcnt(8)
	s_waitcnt lgkmcnt(0)
	s_setprio 1
	s_waitcnt lgkmcnt(0)
	v_mfma_f32_16x16x128_f8f6f4 v[94:97], v[2:9], v[200:207], v[94:97]
	v_mfma_f32_16x16x128_f8f6f4 v[90:93], v[10:17], v[200:207], v[90:93]
	v_mfma_f32_16x16x128_f8f6f4 v[78:81], v[2:9], v[208:215], v[78:81]
	v_mfma_f32_16x16x128_f8f6f4 v[74:77], v[10:17], v[208:215], v[74:77]
	v_mfma_f32_16x16x128_f8f6f4 v[62:65], v[2:9], v[218:225], v[62:65]
	v_mfma_f32_16x16x128_f8f6f4 v[58:61], v[10:17], v[218:225], v[58:61]
	v_mfma_f32_16x16x128_f8f6f4 v[46:49], v[2:9], v[226:233], v[46:49]
	v_mfma_f32_16x16x128_f8f6f4 v[42:45], v[10:17], v[226:233], v[42:45]
	s_setprio 0
	s_setprio 1
	v_mfma_f32_16x16x128_f8f6f4 v[86:89], v[18:25], v[200:207], v[86:89]
	v_mfma_f32_16x16x128_f8f6f4 v[82:85], v[26:33], v[200:207], v[82:85]
	v_mfma_f32_16x16x128_f8f6f4 v[70:73], v[18:25], v[208:215], v[70:73]
	v_mfma_f32_16x16x128_f8f6f4 v[66:69], v[26:33], v[208:215], v[66:69]
	v_mfma_f32_16x16x128_f8f6f4 v[54:57], v[18:25], v[218:225], v[54:57]
	v_mfma_f32_16x16x128_f8f6f4 v[50:53], v[26:33], v[218:225], v[50:53]
	v_mfma_f32_16x16x128_f8f6f4 v[38:41], v[18:25], v[226:233], v[38:41]
	v_mfma_f32_16x16x128_f8f6f4 v[34:37], v[26:33], v[226:233], v[34:37]
	s_setprio 0
	s_barrier
	s_add_i32 s87, s87, 2
	s_add_u32 s72, s72, 0x100
	s_addc_u32 s73, s73, 0
	s_add_u32 s85, s85, 0x100
	s_addc_u32 s86, s86, 0
	s_cmp_gt_u32 s87, 13
	s_branch .LBB0_291
.Lk1_Yz:
	ds_read_b128 v[26:29], v195
	ds_read_b128 v[30:33], v195 offset:1024
	ds_read_b128 v[18:21], v195 offset:2048
	ds_read_b128 v[22:25], v195 offset:3072
	ds_read_b128 v[10:13], v196
	ds_read_b128 v[14:17], v196 offset:1024
	ds_read_b128 v[2:5], v196 offset:2048
	ds_read_b128 v[6:9], v196 offset:3072
	s_add_u32 s24, s72, 0xfffc0080
	s_addc_u32 s25, s73, -1
	s_cmp_eq_u32 s87, 12
	s_cselect_b32 s77, s7, s25
	s_cselect_b32 s76, s65, s24
	s_cselect_b32 s75, s63, s86
	s_cselect_b32 s74, s71, s85
	s_add_i32 m0, s26, 0xc000
	ds_read_b128 v[182:185], v197
	ds_read_b128 v[186:189], v197 offset:1024
	ds_read_b128 v[200:203], v197 offset:2048
	ds_read_b128 v[204:207], v197 offset:3072
	ds_read_b128 v[208:211], v197 offset:4096
	ds_read_b128 v[212:215], v197 offset:5120
	ds_read_b128 v[218:221], v197 offset:6144
	ds_read_b128 v[222:225], v197 offset:7168
	global_load_lds_dwordx4 v178, s[72:73]
	s_add_i32 m0, s26, 0xe000
	s_nop 0
	global_load_lds_dwordx4 v180, s[72:73]
	s_waitcnt vmcnt(8)
	s_waitcnt lgkmcnt(0)
	s_barrier
	s_setprio 3
	s_waitcnt lgkmcnt(0)
	v_mfma_f32_16x16x128_f8f6f4 v[158:161], v[26:33], v[182:189], 0
	v_mfma_f32_16x16x128_f8f6f4 v[154:157], v[18:25], v[182:189], 0
	v_mfma_f32_16x16x128_f8f6f4 v[142:145], v[26:33], v[200:207], 0
	v_mfma_f32_16x16x128_f8f6f4 v[138:141], v[18:25], v[200:207], 0
	v_mfma_f32_16x16x128_f8f6f4 v[126:129], v[26:33], v[208:215], 0
	v_mfma_f32_16x16x128_f8f6f4 v[122:125], v[18:25], v[208:215], 0
	v_mfma_f32_16x16x128_f8f6f4 v[110:113], v[26:33], v[218:225], 0
	v_mfma_f32_16x16x128_f8f6f4 v[106:109], v[18:25], v[218:225], 0


; #define PG8_STAGE(bufoff, gbase, voff) do { _Pragma("unroll") for (int _i = 0; _i < 2; ++_i) \
;         __builtin_amdgcn_global_load_lds((const unsigned*)((const char*)(gbase) + (voff)[_i]), (PG8_LAS unsigned*)(lds + (bufoff) + ldsw + _i * 8192), 16, 0, 0); } while (0)
; #define PG8_LDA(dst, b, h) do { _Pragma("unroll") for (int m = 0; m < 4; ++m) _Pragma("unroll") for (int k = 0; k < 2; ++k) dst[m][k] = *(const PG8_LAS bf16x8*)(lds + PG8_SA(b, h) + aoff + m * 2048 + k * 1024); } while (0)
; #define PG8_WAIT_V(n) asm volatile("s_waitcnt vmcnt(" #n ")" ::: "memory")
; #define PG8_WAIT_L(n) asm volatile("s_waitcnt lgkmcnt(" #n ")" ::: "memory")
; #define PG8_BAR __builtin_amdgcn_s_barrier()
; #define PG8_SCHED __builtin_amdgcn_sched_barrier(0)
; template <class Epi, class Sched, bool ALIGN_EPI = false, bool SP2 = false, bool F8 = false>
; __device__ __forceinline__ void gemm_phase(PG8_LAS unsigned char* lds, const Gemm g, const Sched& S, const Epi& E) {
;     ...
;             PG8_WAIT_V(8); PG8_WAIT_L(0); PG8_BAR; PG8_MMA(0, 0, At, B0); PG8_MMA(0, 1, At, B1); PG8_BAR; PG8_SCHED;
;             PG8_LDA(At, 0, 1); PG8_STAGE(PG8_SB(0, 0), b2, voffB); PG8_STAGE(PG8_SB(0, 1), b2 + hstep, voffB); PG8_STAGE(PG8_SA(0, 0), a2, voffA);
;             PG8_WAIT_V(8); PG8_WAIT_L(0); PG8_BAR; PG8_MMA(1, 0, At, B0); PG8_MMA(1, 1, At, B1); PG8_BAR; PG8_SCHED;
	v_mfma_f32_16x16x128_f8f6f4 v[150:153], v[10:17], v[182:189], 0
	v_mfma_f32_16x16x128_f8f6f4 v[146:149], v[2:9], v[182:189], 0
	v_mfma_f32_16x16x128_f8f6f4 v[134:137], v[10:17], v[200:207], 0
	v_mfma_f32_16x16x128_f8f6f4 v[130:133], v[2:9], v[200:207], 0
	v_mfma_f32_16x16x128_f8f6f4 v[118:121], v[10:17], v[208:215], 0
	v_mfma_f32_16x16x128_f8f6f4 v[114:117], v[2:9], v[208:215], 0
	v_mfma_f32_16x16x128_f8f6f4 v[102:105], v[10:17], v[218:225], 0
	v_mfma_f32_16x16x128_f8f6f4 v[98:101], v[2:9], v[218:225], 0
	s_setprio 0
	s_add_i32 s24, s81, s14
	s_mov_b32 m0, s24
	ds_read_b128 v[200:203], v197 offset:16384
	ds_read_b128 v[204:207], v197 offset:17408
	ds_read_b128 v[208:211], v197 offset:18432
	ds_read_b128 v[212:215], v197 offset:19456
	ds_read_b128 v[218:221], v197 offset:20480
	ds_read_b128 v[222:225], v197 offset:21504
	ds_read_b128 v[226:229], v197 offset:22528
	ds_read_b128 v[230:233], v197 offset:23552
	global_load_lds_dwordx4 v166, s[74:75]
	s_add_i32 m0, s24, 0x2000
	s_add_u32 s24, s74, 0x40000
	s_addc_u32 s25, s75, 0
	s_add_i32 s36, s82, s14
	global_load_lds_dwordx4 v170, s[74:75]
	s_mov_b32 m0, s36
	s_nop 0
	global_load_lds_dwordx4 v166, s[24:25]
	s_add_i32 m0, s36, 0x2000
	s_nop 0
	global_load_lds_dwordx4 v170, s[24:25]
	s_mov_b32 m0, s26
	s_nop 0
	global_load_lds_dwordx4 v164, s[76:77]
	s_mov_b32 m0, s27
	s_nop 0
	global_load_lds_dwordx4 v168, s[76:77]
	s_waitcnt vmcnt(8)
	s_waitcnt lgkmcnt(0)
	s_barrier
	s_setprio 3
	s_waitcnt lgkmcnt(0)
	v_mfma_f32_16x16x128_f8f6f4 v[94:97], v[26:33], v[200:207], 0
	v_mfma_f32_16x16x128_f8f6f4 v[90:93], v[18:25], v[200:207], 0
	v_mfma_f32_16x16x128_f8f6f4 v[78:81], v[26:33], v[208:215], 0
	v_mfma_f32_16x16x128_f8f6f4 v[74:77], v[18:25], v[208:215], 0
	v_mfma_f32_16x16x128_f8f6f4 v[62:65], v[26:33], v[218:225], 0
	v_mfma_f32_16x16x128_f8f6f4 v[58:61], v[18:25], v[218:225], 0
	v_mfma_f32_16x16x128_f8f6f4 v[46:49], v[26:33], v[226:233], 0
	v_mfma_f32_16x16x128_f8f6f4 v[42:45], v[18:25], v[226:233], 0


; #define PG8_STAGE(bufoff, gbase, voff) do { _Pragma("unroll") for (int _i = 0; _i < 2; ++_i) \
;         __builtin_amdgcn_global_load_lds((const unsigned*)((const char*)(gbase) + (voff)[_i]), (PG8_LAS unsigned*)(lds + (bufoff) + ldsw + _i * 8192), 16, 0, 0); } while (0)
; #define PG8_LDA(dst, b, h) do { _Pragma("unroll") for (int m = 0; m < 4; ++m) _Pragma("unroll") for (int k = 0; k < 2; ++k) dst[m][k] = *(const PG8_LAS bf16x8*)(lds + PG8_SA(b, h) + aoff + m * 2048 + k * 1024); } while (0)
; #define PG8_LDB(dst, b, h) do { _Pragma("unroll") for (int n = 0; n < 2; ++n) _Pragma("unroll") for (int k = 0; k < 2; ++k) dst[n][k] = *(const PG8_LAS bf16x8*)(lds + PG8_SB(b, h) + boff + n * 2048 + k * 1024); } while (0)
; #define PG8_WAIT_V(n) asm volatile("s_waitcnt vmcnt(" #n ")" ::: "memory")
; #define PG8_WAIT_L(n) asm volatile("s_waitcnt lgkmcnt(" #n ")" ::: "memory")
; #define PG8_BAR __builtin_amdgcn_s_barrier()
; #define PG8_SCHED __builtin_amdgcn_sched_barrier(0)
; template <class Epi, class Sched, bool ALIGN_EPI = false, bool SP2 = false, bool F8 = false>
; __device__ __forceinline__ void gemm_phase(PG8_LAS unsigned char* lds, const Gemm g, const Sched& S, const Epi& E) {
;     ...
;             PG8_WAIT_V(8); PG8_WAIT_L(0); PG8_BAR; PG8_MMA(1, 0, At, B0); PG8_MMA(1, 1, At, B1); PG8_BAR; PG8_SCHED;
;             PG8_LDB(B0, 1, 0); PG8_LDB(B1, 1, 1); PG8_SCHED; PG8_LDA(At, 1, 0); PG8_STAGE(PG8_SA(0, 1), a2 + hstepA, voffA);
;             PG8_WAIT_V(8); PG8_WAIT_L(0); PG8_BAR; PG8_MMA(0, 0, At, B0); PG8_MMA(0, 1, At, B1); PG8_BAR; PG8_SCHED;
	v_mfma_f32_16x16x128_f8f6f4 v[86:89], v[10:17], v[200:207], 0
	v_mfma_f32_16x16x128_f8f6f4 v[82:85], v[2:9], v[200:207], 0
	v_mfma_f32_16x16x128_f8f6f4 v[70:73], v[10:17], v[208:215], 0
	v_mfma_f32_16x16x128_f8f6f4 v[66:69], v[2:9], v[208:215], 0
	v_mfma_f32_16x16x128_f8f6f4 v[54:57], v[10:17], v[218:225], 0
	v_mfma_f32_16x16x128_f8f6f4 v[50:53], v[2:9], v[218:225], 0
	v_mfma_f32_16x16x128_f8f6f4 v[38:41], v[10:17], v[226:233], 0
	v_mfma_f32_16x16x128_f8f6f4 v[34:37], v[2:9], v[226:233], 0
	s_setprio 0
	s_add_i32 s36, 0, 0x18000
	s_add_i32 s37, 0, 0x1c000
	v_add_u32_e32 v14, s36, v190
	v_add_u32_e32 v30, s37, v190
	ds_read_b128 v[2:5], v14
	ds_read_b128 v[6:9], v14 offset:1024
	ds_read_b128 v[10:13], v14 offset:2048
	ds_read_b128 v[14:17], v14 offset:3072
	ds_read_b128 v[18:21], v30
	ds_read_b128 v[22:25], v30 offset:1024
	ds_read_b128 v[26:29], v30 offset:2048
	ds_read_b128 v[30:33], v30 offset:3072
	s_add_u32 s24, s76, 0x40000
	s_addc_u32 s25, s77, 0
	s_mov_b32 m0, s28
	ds_read_b128 v[200:203], v197 offset:32768
	ds_read_b128 v[204:207], v197 offset:33792
	ds_read_b128 v[208:211], v197 offset:34816
	ds_read_b128 v[212:215], v197 offset:35840
	ds_read_b128 v[218:221], v197 offset:36864
	ds_read_b128 v[222:225], v197 offset:37888
	ds_read_b128 v[226:229], v197 offset:38912
	ds_read_b128 v[230:233], v197 offset:39936
	global_load_lds_dwordx4 v164, s[24:25]
	s_mov_b32 m0, s29
	s_nop 0
	global_load_lds_dwordx4 v168, s[24:25]
	s_waitcnt vmcnt(8)
	s_waitcnt lgkmcnt(0)
	s_barrier
	s_setprio 3
	s_waitcnt lgkmcnt(0)
	v_mfma_f32_16x16x128_f8f6f4 v[158:161], v[2:9], v[200:207], v[158:161]
	v_mfma_f32_16x16x128_f8f6f4 v[154:157], v[10:17], v[200:207], v[154:157]
	v_mfma_f32_16x16x128_f8f6f4 v[142:145], v[2:9], v[208:215], v[142:145]
	v_mfma_f32_16x16x128_f8f6f4 v[138:141], v[10:17], v[208:215], v[138:141]
	v_mfma_f32_16x16x128_f8f6f4 v[126:129], v[2:9], v[218:225], v[126:129]
	v_mfma_f32_16x16x128_f8f6f4 v[122:125], v[10:17], v[218:225], v[122:125]
	v_mfma_f32_16x16x128_f8f6f4 v[110:113], v[2:9], v[226:233], v[110:113]
	v_mfma_f32_16x16x128_f8f6f4 v[106:109], v[10:17], v[226:233], v[106:109]


; #define PG8_STAGE(bufoff, gbase, voff) do { _Pragma("unroll") for (int _i = 0; _i < 2; ++_i) \
;         __builtin_amdgcn_global_load_lds((const unsigned*)((const char*)(gbase) + (voff)[_i]), (PG8_LAS unsigned*)(lds + (bufoff) + ldsw + _i * 8192), 16, 0, 0); } while (0)
; #define PG8_LDA(dst, b, h) do { _Pragma("unroll") for (int m = 0; m < 4; ++m) _Pragma("unroll") for (int k = 0; k < 2; ++k) dst[m][k] = *(const PG8_LAS bf16x8*)(lds + PG8_SA(b, h) + aoff + m * 2048 + k * 1024); } while (0)
; #define PG8_WAIT_V(n) asm volatile("s_waitcnt vmcnt(" #n ")" ::: "memory")
; #define PG8_WAIT_L(n) asm volatile("s_waitcnt lgkmcnt(" #n ")" ::: "memory")
; #define PG8_BAR __builtin_amdgcn_s_barrier()
; #define PG8_SCHED __builtin_amdgcn_sched_barrier(0)
; template <class Epi, class Sched, bool ALIGN_EPI = false, bool SP2 = false, bool F8 = false>
; __device__ __forceinline__ void gemm_phase(PG8_LAS unsigned char* lds, const Gemm g, const Sched& S, const Epi& E) {
;     ...
;             PG8_WAIT_V(8); PG8_WAIT_L(0); PG8_BAR; PG8_MMA(0, 0, At, B0); PG8_MMA(0, 1, At, B1); PG8_BAR; PG8_SCHED;
;             PG8_LDA(At, 1, 1); PG8_STAGE(PG8_SB(1, 0), b3, voffB); PG8_STAGE(PG8_SB(1, 1), b3 + hstep, voffB); PG8_STAGE(PG8_SA(1, 0), a3, voffA);
;             PG8_WAIT_V(8); PG8_WAIT_L(0); PG8_BAR; PG8_MMA(1, 0, At, B0); PG8_MMA(1, 1, At, B1); PG8_BAR; PG8_SCHED;
	v_mfma_f32_16x16x128_f8f6f4 v[150:153], v[18:25], v[200:207], v[150:153]
	v_mfma_f32_16x16x128_f8f6f4 v[146:149], v[26:33], v[200:207], v[146:149]
	v_mfma_f32_16x16x128_f8f6f4 v[134:137], v[18:25], v[208:215], v[134:137]
	v_mfma_f32_16x16x128_f8f6f4 v[130:133], v[26:33], v[208:215], v[130:133]
	v_mfma_f32_16x16x128_f8f6f4 v[118:121], v[18:25], v[218:225], v[118:121]
	v_mfma_f32_16x16x128_f8f6f4 v[114:117], v[26:33], v[218:225], v[114:117]
	v_mfma_f32_16x16x128_f8f6f4 v[102:105], v[18:25], v[226:233], v[102:105]
	v_mfma_f32_16x16x128_f8f6f4 v[98:101], v[26:33], v[226:233], v[98:101]
	s_setprio 0
	s_add_i32 s24, s36, s14
	s_mov_b32 m0, s24
	ds_read_b128 v[200:203], v197 offset:49152
	ds_read_b128 v[204:207], v197 offset:50176
	ds_read_b128 v[208:211], v197 offset:51200
	ds_read_b128 v[212:215], v197 offset:52224
	ds_read_b128 v[218:221], v197 offset:53248
	ds_read_b128 v[222:225], v197 offset:54272
	ds_read_b128 v[226:229], v197 offset:55296
	ds_read_b128 v[230:233], v197 offset:56320
	s_add_u32 s98, s74, 0x80
	s_addc_u32 s99, s75, 0
	global_load_lds_dwordx4 v166, s[98:99]
	s_add_i32 m0, s24, 0x2000
	s_add_u32 s24, s74, 0x40080
	s_addc_u32 s25, s75, 0
	s_add_i32 s36, s37, s14
	s_add_u32 s100, s74, 0x80
	s_addc_u32 s101, s75, 0
	global_load_lds_dwordx4 v170, s[100:101]
	s_mov_b32 m0, s36
	s_nop 0
	global_load_lds_dwordx4 v166, s[24:25]
	s_add_i32 m0, s36, 0x2000
	s_nop 0
	global_load_lds_dwordx4 v170, s[24:25]
	s_mov_b32 m0, s45
	s_nop 0
	s_add_u32 s98, s76, 0x80
	s_addc_u32 s99, s77, 0
	global_load_lds_dwordx4 v164, s[98:99]
	s_mov_b32 m0, s78
	s_nop 0
	s_add_u32 s100, s76, 0x80
	s_addc_u32 s101, s77, 0
	global_load_lds_dwordx4 v168, s[100:101]
	s_waitcnt vmcnt(8)
	s_waitcnt lgkmcnt(0)
	s_barrier
	s_setprio 3
	s_waitcnt lgkmcnt(0)
	v_mfma_f32_16x16x128_f8f6f4 v[94:97], v[2:9], v[200:207], v[94:97]
	v_mfma_f32_16x16x128_f8f6f4 v[90:93], v[10:17], v[200:207], v[90:93]
	v_mfma_f32_16x16x128_f8f6f4 v[78:81], v[2:9], v[208:215], v[78:81]
	v_mfma_f32_16x16x128_f8f6f4 v[74:77], v[10:17], v[208:215], v[74:77]
	v_mfma_f32_16x16x128_f8f6f4 v[62:65], v[2:9], v[218:225], v[62:65]
	v_mfma_f32_16x16x128_f8f6f4 v[58:61], v[10:17], v[218:225], v[58:61]
	v_mfma_f32_16x16x128_f8f6f4 v[46:49], v[2:9], v[226:233], v[46:49]
	v_mfma_f32_16x16x128_f8f6f4 v[42:45], v[10:17], v[226:233], v[42:45]


; #define PG8_WAIT_V(n) asm volatile("s_waitcnt vmcnt(" #n ")" ::: "memory")
; #define PG8_WAIT_L(n) asm volatile("s_waitcnt lgkmcnt(" #n ")" ::: "memory")
; #define PG8_BAR __builtin_amdgcn_s_barrier()
; #define PG8_SCHED __builtin_amdgcn_sched_barrier(0)
; template <class Epi, class Sched, bool ALIGN_EPI = false, bool SP2 = false, bool F8 = false>
; __device__ __forceinline__ void gemm_phase(PG8_LAS unsigned char* lds, const Gemm g, const Sched& S, const Epi& E) {
;     ...
;         for (int t = 0; t < nt; t += 2) {
;             const bool last = (t == nt - 2);
;             const char* a1 = cA + (size_t)(t + 1) * kstep;
;             const char* a2 = last ? nA : cA + (size_t)(t + 2) * kstep; const char* b2 = last ? nB : cB + (size_t)(t + 2) * kstep;
;     ...
;             PG8_WAIT_V(8); PG8_WAIT_L(0); PG8_BAR; PG8_MMA(1, 0, At, B0); PG8_MMA(1, 1, At, B1); PG8_BAR; PG8_SCHED;
	v_mfma_f32_16x16x128_f8f6f4 v[86:89], v[18:25], v[200:207], v[86:89]
	v_mfma_f32_16x16x128_f8f6f4 v[82:85], v[26:33], v[200:207], v[82:85]
	v_mfma_f32_16x16x128_f8f6f4 v[70:73], v[18:25], v[208:215], v[70:73]
	v_mfma_f32_16x16x128_f8f6f4 v[66:69], v[26:33], v[208:215], v[66:69]
	v_mfma_f32_16x16x128_f8f6f4 v[54:57], v[18:25], v[218:225], v[54:57]
	v_mfma_f32_16x16x128_f8f6f4 v[50:53], v[26:33], v[218:225], v[50:53]
	v_mfma_f32_16x16x128_f8f6f4 v[38:41], v[18:25], v[226:233], v[38:41]
	v_mfma_f32_16x16x128_f8f6f4 v[34:37], v[26:33], v[226:233], v[34:37]
	s_setprio 0
	s_add_i32 s87, s87, 2
	s_add_u32 s72, s72, 0x100
	s_addc_u32 s73, s73, 0
	s_add_u32 s85, s85, 0x100
	s_addc_u32 s86, s86, 0
	s_cmp_gt_u32 s87, 13
	s_branch .Lk1_Y

;     __host__ __device__ bool next(int i, Unit& u) const { const long L = (long)i * G + c; if (L >= nwg) return false; u.pm = 0; u.pn = c % nN; return true; }
; template <class Epi, class Sched, bool ALIGN_EPI = false, bool SP2 = false, bool F8 = false>
; __device__ __forceinline__ void gemm_phase(PG8_LAS unsigned char* lds, const Gemm g, const Sched& S, const Epi& E) {
;     ...
;         const bool has_next = S.next(ui + 1, nxt);
;         const char* nA = has_next ? PG8_ABASE(nxt.pm) : cA; const char* nB = has_next ? (const char*)g.Bt + (size_t)nxt.pn * tstep : cB;
;         for (int t = 0; t < nt; t += 2) {
;             const bool last = (t == nt - 2);
;             const char* a1 = cA + (size_t)(t + 1) * kstep;
;             const char* a2 = last ? nA : cA + (size_t)(t + 2) * kstep; const char* b2 = last ? nB : cB + (size_t)(t + 2) * kstep;
;     ...
; #pragma unroll
;         for (int a = 0; a < 2; ++a)
; #pragma unroll
;             for (int b = 0; b < 2; ++b)
; #pragma unroll
;                 for (int m = 0; m < 4; ++m)
; #pragma unroll
;                     for (int n = 0; n < 2; ++n) acc[a][b][m][n] = (f32x4){0.f, 0.f, 0.f, 0.f};
.LBB0_771:
	s_ashr_i32 s55, s54, 31
	s_lshl_b64 s[24:25], s[54:55], 20
	s_add_u32 s56, s8, s24
	s_addc_u32 s57, s9, s25
	s_and_b64 s[24:25], s[6:7], exec
	s_cselect_b32 s55, s57, s63
	s_cselect_b32 s61, s56, s62
	s_ashr_i32 s53, s52, 31
	s_lshl_b64 s[24:25], s[52:53], 20
	s_add_u32 s58, s46, s24
	s_addc_u32 s59, s47, s25
	s_and_b64 s[24:25], s[6:7], exec
	s_cselect_b32 s53, s59, s65
	s_cselect_b32 s73, s58, s64
	s_add_u32 s62, s62, 0x80080
	s_addc_u32 s63, s63, 0
	s_add_u32 s74, s64, 0x100
	s_addc_u32 s75, s65, 0
	s_mov_b32 s76, -2
	s_waitcnt lgkmcnt(0)
	s_waitcnt vmcnt(0)
	s_cmp_lg_u64 s[40:41], 0
	s_cbranch_scc1 .Lk2_Yz
	s_branch .Lk2_Xz

; #define PG8_STAGE(bufoff, gbase, voff) do { _Pragma("unroll") for (int _i = 0; _i < 2; ++_i) \
;         __builtin_amdgcn_global_load_lds((const unsigned*)((const char*)(gbase) + (voff)[_i]), (PG8_LAS unsigned*)(lds + (bufoff) + ldsw + _i * 8192), 16, 0, 0); } while (0)
; #define PG8_LDA(dst, b, h) do { _Pragma("unroll") for (int m = 0; m < 4; ++m) _Pragma("unroll") for (int k = 0; k < 2; ++k) dst[m][k] = *(const PG8_LAS bf16x8*)(lds + PG8_SA(b, h) + aoff + m * 2048 + k * 1024); } while (0)
; #define PG8_LDB(dst, b, h) do { _Pragma("unroll") for (int n = 0; n < 2; ++n) _Pragma("unroll") for (int k = 0; k < 2; ++k) dst[n][k] = *(const PG8_LAS bf16x8*)(lds + PG8_SB(b, h) + boff + n * 2048 + k * 1024); } while (0)
; #define PG8_WAIT_V(n) asm volatile("s_waitcnt vmcnt(" #n ")" ::: "memory")
; #define PG8_WAIT_L(n) asm volatile("s_waitcnt lgkmcnt(" #n ")" ::: "memory")
; #define PG8_BAR __builtin_amdgcn_s_barrier()
; #define PG8_SCHED __builtin_amdgcn_sched_barrier(0)
; template <class Epi, class Sched, bool ALIGN_EPI = false, bool SP2 = false, bool F8 = false>
; __device__ __forceinline__ void gemm_phase(PG8_LAS unsigned char* lds, const Gemm g, const Sched& S, const Epi& E) {
;     ...
;             PG8_LDB(B0, 0, 0); PG8_LDB(B1, 0, 1); PG8_SCHED; PG8_LDA(At, 0, 0); PG8_STAGE(PG8_SA(1, 1), a1 + hstepA, voffA);
;             PG8_WAIT_V(8); PG8_WAIT_L(0); PG8_BAR; PG8_MMA(0, 0, At, B0); PG8_MMA(0, 1, At, B1); PG8_BAR; PG8_SCHED;
.Lk2_Y:
	ds_read_b128 v[82:85], v204
	ds_read_b128 v[86:89], v204 offset:1024
	ds_read_b128 v[90:93], v204 offset:2048
	ds_read_b128 v[94:97], v204 offset:3072
	ds_read_b128 v[102:105], v205
	ds_read_b128 v[106:109], v205 offset:1024
	ds_read_b128 v[114:117], v205 offset:2048
	ds_read_b128 v[118:121], v205 offset:3072
	s_add_u32 s24, s62, 0xfff80080
	s_addc_u32 s25, s63, -1
	s_cmp_eq_u32 s76, 28
	s_cselect_b32 s67, s55, s25
	s_cselect_b32 s66, s61, s24
	s_cselect_b32 s65, s53, s75
	s_cselect_b32 s64, s73, s74
	s_add_i32 m0, s15, 0xc000
	ds_read_b128 v[162:165], v206
	ds_read_b128 v[166:169], v206 offset:1024
	ds_read_b128 v[170:173], v206 offset:2048
	ds_read_b128 v[174:177], v206 offset:3072
	ds_read_b128 v[194:197], v206 offset:4096
	ds_read_b128 v[198:201], v206 offset:5120
	ds_read_b128 v[208:211], v206 offset:6144
	ds_read_b128 v[212:215], v206 offset:7168
	global_load_lds_dwordx4 v186, s[62:63]
	s_add_i32 m0, s15, 0xe000
	s_nop 0
	global_load_lds_dwordx4 v188, s[62:63]
	s_waitcnt vmcnt(8)
	s_waitcnt lgkmcnt(0)
	s_barrier
	s_setprio 3
	s_waitcnt lgkmcnt(0)
	v_mfma_f32_16x16x32_bf16 v[158:161], v[82:85], v[162:165], v[158:161]
	v_mfma_f32_16x16x32_bf16 v[154:157], v[90:93], v[162:165], v[154:157]
	v_mfma_f32_16x16x32_bf16 v[142:145], v[82:85], v[170:173], v[142:145]
	v_mfma_f32_16x16x32_bf16 v[138:141], v[90:93], v[170:173], v[138:141]
	v_mfma_f32_16x16x32_bf16 v[126:129], v[82:85], v[194:197], v[126:129]
	v_mfma_f32_16x16x32_bf16 v[122:125], v[90:93], v[194:197], v[122:125]
	v_mfma_f32_16x16x32_bf16 v[78:81], v[82:85], v[208:211], v[78:81]
	v_mfma_f32_16x16x32_bf16 v[74:77], v[90:93], v[208:211], v[74:77]
	v_mfma_f32_16x16x32_bf16 v[158:161], v[86:89], v[166:169], v[158:161]
	v_mfma_f32_16x16x32_bf16 v[154:157], v[94:97], v[166:169], v[154:157]
	v_mfma_f32_16x16x32_bf16 v[142:145], v[86:89], v[174:177], v[142:145]
	v_mfma_f32_16x16x32_bf16 v[138:141], v[94:97], v[174:177], v[138:141]
	v_mfma_f32_16x16x32_bf16 v[126:129], v[86:89], v[198:201], v[126:129]
	v_mfma_f32_16x16x32_bf16 v[122:125], v[94:97], v[198:201], v[122:125]
	v_mfma_f32_16x16x32_bf16 v[78:81], v[86:89], v[212:215], v[78:81]
	v_mfma_f32_16x16x32_bf16 v[74:77], v[94:97], v[212:215], v[74:77]


; #define PG8_STAGE(bufoff, gbase, voff) do { _Pragma("unroll") for (int _i = 0; _i < 2; ++_i) \
;         __builtin_amdgcn_global_load_lds((const unsigned*)((const char*)(gbase) + (voff)[_i]), (PG8_LAS unsigned*)(lds + (bufoff) + ldsw + _i * 8192), 16, 0, 0); } while (0)
; #define PG8_LDA(dst, b, h) do { _Pragma("unroll") for (int m = 0; m < 4; ++m) _Pragma("unroll") for (int k = 0; k < 2; ++k) dst[m][k] = *(const PG8_LAS bf16x8*)(lds + PG8_SA(b, h) + aoff + m * 2048 + k * 1024); } while (0)
; #define PG8_WAIT_V(n) asm volatile("s_waitcnt vmcnt(" #n ")" ::: "memory")
; #define PG8_WAIT_L(n) asm volatile("s_waitcnt lgkmcnt(" #n ")" ::: "memory")
; #define PG8_BAR __builtin_amdgcn_s_barrier()
; #define PG8_SCHED __builtin_amdgcn_sched_barrier(0)
; template <class Epi, class Sched, bool ALIGN_EPI = false, bool SP2 = false, bool F8 = false>
; __device__ __forceinline__ void gemm_phase(PG8_LAS unsigned char* lds, const Gemm g, const Sched& S, const Epi& E) {
;     ...
;             PG8_WAIT_V(8); PG8_WAIT_L(0); PG8_BAR; PG8_MMA(0, 0, At, B0); PG8_MMA(0, 1, At, B1); PG8_BAR; PG8_SCHED;
;             PG8_LDA(At, 0, 1); PG8_STAGE(PG8_SB(0, 0), b2, voffB); PG8_STAGE(PG8_SB(0, 1), b2 + hstep, voffB); PG8_STAGE(PG8_SA(0, 0), a2, voffA);
;             PG8_WAIT_V(8); PG8_WAIT_L(0); PG8_BAR; PG8_MMA(1, 0, At, B0); PG8_MMA(1, 1, At, B1); PG8_BAR; PG8_SCHED;
	v_mfma_f32_16x16x32_bf16 v[150:153], v[102:105], v[162:165], v[150:153]
	v_mfma_f32_16x16x32_bf16 v[146:149], v[114:117], v[162:165], v[146:149]
	v_mfma_f32_16x16x32_bf16 v[134:137], v[102:105], v[170:173], v[134:137]
	v_mfma_f32_16x16x32_bf16 v[130:133], v[114:117], v[170:173], v[130:133]
	v_mfma_f32_16x16x32_bf16 v[110:113], v[102:105], v[194:197], v[110:113]
	v_mfma_f32_16x16x32_bf16 v[98:101], v[114:117], v[194:197], v[98:101]
	v_mfma_f32_16x16x32_bf16 v[70:73], v[102:105], v[208:211], v[70:73]
	v_mfma_f32_16x16x32_bf16 v[66:69], v[114:117], v[208:211], v[66:69]
	v_mfma_f32_16x16x32_bf16 v[150:153], v[106:109], v[166:169], v[150:153]
	v_mfma_f32_16x16x32_bf16 v[146:149], v[118:121], v[166:169], v[146:149]
	v_mfma_f32_16x16x32_bf16 v[134:137], v[106:109], v[174:177], v[134:137]
	v_mfma_f32_16x16x32_bf16 v[130:133], v[118:121], v[174:177], v[130:133]
	v_mfma_f32_16x16x32_bf16 v[110:113], v[106:109], v[198:201], v[110:113]
	v_mfma_f32_16x16x32_bf16 v[98:101], v[118:121], v[198:201], v[98:101]
	v_mfma_f32_16x16x32_bf16 v[70:73], v[106:109], v[212:215], v[70:73]
	v_mfma_f32_16x16x32_bf16 v[66:69], v[118:121], v[212:215], v[66:69]
	s_setprio 0
	s_add_i32 s24, s70, s14
	s_mov_b32 m0, s24
	ds_read_b128 v[162:165], v206 offset:16384
	ds_read_b128 v[166:169], v206 offset:17408
	ds_read_b128 v[170:173], v206 offset:18432
	ds_read_b128 v[174:177], v206 offset:19456
	ds_read_b128 v[194:197], v206 offset:20480
	ds_read_b128 v[198:201], v206 offset:21504
	ds_read_b128 v[208:211], v206 offset:22528
	ds_read_b128 v[212:215], v206 offset:23552
	global_load_lds_dwordx4 v180, s[64:65]
	s_add_i32 m0, s24, 0x2000
	s_add_u32 s24, s64, 0x80000
	s_addc_u32 s25, s65, 0
	s_add_i32 s36, s71, s14
	global_load_lds_dwordx4 v184, s[64:65]
	s_mov_b32 m0, s36
	s_nop 0
	global_load_lds_dwordx4 v180, s[24:25]
	s_add_i32 m0, s36, 0x2000
	s_nop 0
	global_load_lds_dwordx4 v184, s[24:25]
	s_mov_b32 m0, s15
	s_nop 0
	global_load_lds_dwordx4 v178, s[66:67]
	s_mov_b32 m0, s23
	s_nop 0
	global_load_lds_dwordx4 v182, s[66:67]
	s_waitcnt vmcnt(8)
	s_waitcnt lgkmcnt(0)
	s_barrier
	s_setprio 3
	s_waitcnt lgkmcnt(0)
	v_mfma_f32_16x16x32_bf16 v[62:65], v[82:85], v[162:165], v[62:65]
	v_mfma_f32_16x16x32_bf16 v[58:61], v[90:93], v[162:165], v[58:61]
	v_mfma_f32_16x16x32_bf16 v[46:49], v[82:85], v[170:173], v[46:49]
	v_mfma_f32_16x16x32_bf16 v[42:45], v[90:93], v[170:173], v[42:45]
	v_mfma_f32_16x16x32_bf16 v[30:33], v[82:85], v[194:197], v[30:33]
	v_mfma_f32_16x16x32_bf16 v[26:29], v[90:93], v[194:197], v[26:29]
	v_mfma_f32_16x16x32_bf16 v[14:17], v[82:85], v[208:211], v[14:17]
	v_mfma_f32_16x16x32_bf16 v[10:13], v[90:93], v[208:211], v[10:13]
	v_mfma_f32_16x16x32_bf16 v[62:65], v[86:89], v[166:169], v[62:65]
	v_mfma_f32_16x16x32_bf16 v[58:61], v[94:97], v[166:169], v[58:61]
	v_mfma_f32_16x16x32_bf16 v[46:49], v[86:89], v[174:177], v[46:49]
	v_mfma_f32_16x16x32_bf16 v[42:45], v[94:97], v[174:177], v[42:45]
	v_mfma_f32_16x16x32_bf16 v[30:33], v[86:89], v[198:201], v[30:33]
	v_mfma_f32_16x16x32_bf16 v[26:29], v[94:97], v[198:201], v[26:29]
	v_mfma_f32_16x16x32_bf16 v[14:17], v[86:89], v[212:215], v[14:17]
	v_mfma_f32_16x16x32_bf16 v[10:13], v[94:97], v[212:215], v[10:13]


; #define PG8_STAGE(bufoff, gbase, voff) do { _Pragma("unroll") for (int _i = 0; _i < 2; ++_i) \
;         __builtin_amdgcn_global_load_lds((const unsigned*)((const char*)(gbase) + (voff)[_i]), (PG8_LAS unsigned*)(lds + (bufoff) + ldsw + _i * 8192), 16, 0, 0); } while (0)
; #define PG8_LDA(dst, b, h) do { _Pragma("unroll") for (int m = 0; m < 4; ++m) _Pragma("unroll") for (int k = 0; k < 2; ++k) dst[m][k] = *(const PG8_LAS bf16x8*)(lds + PG8_SA(b, h) + aoff + m * 2048 + k * 1024); } while (0)
; #define PG8_LDB(dst, b, h) do { _Pragma("unroll") for (int n = 0; n < 2; ++n) _Pragma("unroll") for (int k = 0; k < 2; ++k) dst[n][k] = *(const PG8_LAS bf16x8*)(lds + PG8_SB(b, h) + boff + n * 2048 + k * 1024); } while (0)
; #define PG8_WAIT_V(n) asm volatile("s_waitcnt vmcnt(" #n ")" ::: "memory")
; #define PG8_WAIT_L(n) asm volatile("s_waitcnt lgkmcnt(" #n ")" ::: "memory")
; #define PG8_BAR __builtin_amdgcn_s_barrier()
; #define PG8_SCHED __builtin_amdgcn_sched_barrier(0)
; template <class Epi, class Sched, bool ALIGN_EPI = false, bool SP2 = false, bool F8 = false>
; __device__ __forceinline__ void gemm_phase(PG8_LAS unsigned char* lds, const Gemm g, const Sched& S, const Epi& E) {
;     ...
;             PG8_WAIT_V(8); PG8_WAIT_L(0); PG8_BAR; PG8_MMA(1, 0, At, B0); PG8_MMA(1, 1, At, B1); PG8_BAR; PG8_SCHED;
;             PG8_LDB(B0, 1, 0); PG8_LDB(B1, 1, 1); PG8_SCHED; PG8_LDA(At, 1, 0); PG8_STAGE(PG8_SA(0, 1), a2 + hstepA, voffA);
;             PG8_WAIT_V(8); PG8_WAIT_L(0); PG8_BAR; PG8_MMA(0, 0, At, B0); PG8_MMA(0, 1, At, B1); PG8_BAR; PG8_SCHED;
	v_mfma_f32_16x16x32_bf16 v[54:57], v[102:105], v[162:165], v[54:57]
	v_mfma_f32_16x16x32_bf16 v[50:53], v[114:117], v[162:165], v[50:53]
	v_mfma_f32_16x16x32_bf16 v[38:41], v[102:105], v[170:173], v[38:41]
	v_mfma_f32_16x16x32_bf16 v[34:37], v[114:117], v[170:173], v[34:37]
	v_mfma_f32_16x16x32_bf16 v[22:25], v[102:105], v[194:197], v[22:25]
	v_mfma_f32_16x16x32_bf16 v[18:21], v[114:117], v[194:197], v[18:21]
	v_mfma_f32_16x16x32_bf16 v[6:9], v[102:105], v[208:211], v[6:9]
	v_mfma_f32_16x16x32_bf16 v[2:5], v[114:117], v[208:211], v[2:5]
	v_mfma_f32_16x16x32_bf16 v[54:57], v[106:109], v[166:169], v[54:57]
	v_mfma_f32_16x16x32_bf16 v[50:53], v[118:121], v[166:169], v[50:53]
	v_mfma_f32_16x16x32_bf16 v[38:41], v[106:109], v[174:177], v[38:41]
	v_mfma_f32_16x16x32_bf16 v[34:37], v[118:121], v[174:177], v[34:37]
	v_mfma_f32_16x16x32_bf16 v[22:25], v[106:109], v[198:201], v[22:25]
	v_mfma_f32_16x16x32_bf16 v[18:21], v[118:121], v[198:201], v[18:21]
	v_mfma_f32_16x16x32_bf16 v[6:9], v[106:109], v[212:215], v[6:9]
	v_mfma_f32_16x16x32_bf16 v[2:5], v[118:121], v[212:215], v[2:5]
	s_setprio 0
	s_add_i32 s36, 0, 0x18000
	s_add_i32 s37, 0, 0x1c000
	v_add_u32_e32 v94, s36, v202
	v_add_u32_e32 v118, s37, v202
	ds_read_b128 v[82:85], v94
	ds_read_b128 v[86:89], v94 offset:1024
	ds_read_b128 v[90:93], v94 offset:2048
	ds_read_b128 v[94:97], v94 offset:3072
	ds_read_b128 v[102:105], v118
	ds_read_b128 v[106:109], v118 offset:1024
	ds_read_b128 v[114:117], v118 offset:2048
	ds_read_b128 v[118:121], v118 offset:3072
	s_add_u32 s24, s66, 0x80000
	s_addc_u32 s25, s67, 0
	s_mov_b32 m0, s26
	ds_read_b128 v[162:165], v206 offset:32768
	ds_read_b128 v[166:169], v206 offset:33792
	ds_read_b128 v[170:173], v206 offset:34816
	ds_read_b128 v[174:177], v206 offset:35840
	ds_read_b128 v[194:197], v206 offset:36864
	ds_read_b128 v[198:201], v206 offset:37888
	ds_read_b128 v[208:211], v206 offset:38912
	ds_read_b128 v[212:215], v206 offset:39936
	global_load_lds_dwordx4 v178, s[24:25]
	s_mov_b32 m0, s27
	s_nop 0
	global_load_lds_dwordx4 v182, s[24:25]
	s_waitcnt vmcnt(8)
	s_waitcnt lgkmcnt(0)
	s_barrier
	s_setprio 3
	s_waitcnt lgkmcnt(0)
	v_mfma_f32_16x16x32_bf16 v[158:161], v[82:85], v[162:165], v[158:161]
	v_mfma_f32_16x16x32_bf16 v[154:157], v[90:93], v[162:165], v[154:157]
	v_mfma_f32_16x16x32_bf16 v[142:145], v[82:85], v[170:173], v[142:145]
	v_mfma_f32_16x16x32_bf16 v[138:141], v[90:93], v[170:173], v[138:141]
	v_mfma_f32_16x16x32_bf16 v[126:129], v[82:85], v[194:197], v[126:129]
	v_mfma_f32_16x16x32_bf16 v[122:125], v[90:93], v[194:197], v[122:125]
	v_mfma_f32_16x16x32_bf16 v[78:81], v[82:85], v[208:211], v[78:81]
	v_mfma_f32_16x16x32_bf16 v[74:77], v[90:93], v[208:211], v[74:77]
	v_mfma_f32_16x16x32_bf16 v[158:161], v[86:89], v[166:169], v[158:161]
	v_mfma_f32_16x16x32_bf16 v[154:157], v[94:97], v[166:169], v[154:157]
	v_mfma_f32_16x16x32_bf16 v[142:145], v[86:89], v[174:177], v[142:145]
	v_mfma_f32_16x16x32_bf16 v[138:141], v[94:97], v[174:177], v[138:141]
	v_mfma_f32_16x16x32_bf16 v[126:129], v[86:89], v[198:201], v[126:129]
	v_mfma_f32_16x16x32_bf16 v[122:125], v[94:97], v[198:201], v[122:125]
	v_mfma_f32_16x16x32_bf16 v[78:81], v[86:89], v[212:215], v[78:81]
	v_mfma_f32_16x16x32_bf16 v[74:77], v[94:97], v[212:215], v[74:77]


; #define PG8_STAGE(bufoff, gbase, voff) do { _Pragma("unroll") for (int _i = 0; _i < 2; ++_i) \
;         __builtin_amdgcn_global_load_lds((const unsigned*)((const char*)(gbase) + (voff)[_i]), (PG8_LAS unsigned*)(lds + (bufoff) + ldsw + _i * 8192), 16, 0, 0); } while (0)
; #define PG8_LDA(dst, b, h) do { _Pragma("unroll") for (int m = 0; m < 4; ++m) _Pragma("unroll") for (int k = 0; k < 2; ++k) dst[m][k] = *(const PG8_LAS bf16x8*)(lds + PG8_SA(b, h) + aoff + m * 2048 + k * 1024); } while (0)
; #define PG8_WAIT_V(n) asm volatile("s_waitcnt vmcnt(" #n ")" ::: "memory")
; #define PG8_WAIT_L(n) asm volatile("s_waitcnt lgkmcnt(" #n ")" ::: "memory")
; #define PG8_BAR __builtin_amdgcn_s_barrier()
; #define PG8_SCHED __builtin_amdgcn_sched_barrier(0)
; template <class Epi, class Sched, bool ALIGN_EPI = false, bool SP2 = false, bool F8 = false>
; __device__ __forceinline__ void gemm_phase(PG8_LAS unsigned char* lds, const Gemm g, const Sched& S, const Epi& E) {
;     ...
;             PG8_WAIT_V(8); PG8_WAIT_L(0); PG8_BAR; PG8_MMA(0, 0, At, B0); PG8_MMA(0, 1, At, B1); PG8_BAR; PG8_SCHED;
;             PG8_LDA(At, 1, 1); PG8_STAGE(PG8_SB(1, 0), b3, voffB); PG8_STAGE(PG8_SB(1, 1), b3 + hstep, voffB); PG8_STAGE(PG8_SA(1, 0), a3, voffA);
;             PG8_WAIT_V(8); PG8_WAIT_L(0); PG8_BAR; PG8_MMA(1, 0, At, B0); PG8_MMA(1, 1, At, B1); PG8_BAR; PG8_SCHED;
	v_mfma_f32_16x16x32_bf16 v[150:153], v[102:105], v[162:165], v[150:153]
	v_mfma_f32_16x16x32_bf16 v[146:149], v[114:117], v[162:165], v[146:149]
	v_mfma_f32_16x16x32_bf16 v[134:137], v[102:105], v[170:173], v[134:137]
	v_mfma_f32_16x16x32_bf16 v[130:133], v[114:117], v[170:173], v[130:133]
	v_mfma_f32_16x16x32_bf16 v[110:113], v[102:105], v[194:197], v[110:113]
	v_mfma_f32_16x16x32_bf16 v[98:101], v[114:117], v[194:197], v[98:101]
	v_mfma_f32_16x16x32_bf16 v[70:73], v[102:105], v[208:211], v[70:73]
	v_mfma_f32_16x16x32_bf16 v[66:69], v[114:117], v[208:211], v[66:69]
	v_mfma_f32_16x16x32_bf16 v[150:153], v[106:109], v[166:169], v[150:153]
	v_mfma_f32_16x16x32_bf16 v[146:149], v[118:121], v[166:169], v[146:149]
	v_mfma_f32_16x16x32_bf16 v[134:137], v[106:109], v[174:177], v[134:137]
	v_mfma_f32_16x16x32_bf16 v[130:133], v[118:121], v[174:177], v[130:133]
	v_mfma_f32_16x16x32_bf16 v[110:113], v[106:109], v[198:201], v[110:113]
	v_mfma_f32_16x16x32_bf16 v[98:101], v[118:121], v[198:201], v[98:101]
	v_mfma_f32_16x16x32_bf16 v[70:73], v[106:109], v[212:215], v[70:73]
	v_mfma_f32_16x16x32_bf16 v[66:69], v[118:121], v[212:215], v[66:69]
	s_setprio 0
	s_add_i32 s24, s36, s14
	s_mov_b32 m0, s24
	ds_read_b128 v[162:165], v206 offset:49152
	ds_read_b128 v[166:169], v206 offset:50176
	ds_read_b128 v[170:173], v206 offset:51200
	ds_read_b128 v[174:177], v206 offset:52224
	ds_read_b128 v[194:197], v206 offset:53248
	ds_read_b128 v[198:201], v206 offset:54272
	ds_read_b128 v[208:211], v206 offset:55296
	ds_read_b128 v[212:215], v206 offset:56320
	s_add_u32 s98, s64, 0x80
	s_addc_u32 s99, s65, 0
	global_load_lds_dwordx4 v180, s[98:99]
	s_add_i32 m0, s24, 0x2000
	s_add_u32 s24, s64, 0x80080
	s_addc_u32 s25, s65, 0
	s_add_i32 s36, s37, s14
	s_add_u32 s100, s64, 0x80
	s_addc_u32 s101, s65, 0
	global_load_lds_dwordx4 v184, s[100:101]
	s_mov_b32 m0, s36
	s_nop 0
	global_load_lds_dwordx4 v180, s[24:25]
	s_add_i32 m0, s36, 0x2000
	s_nop 0
	global_load_lds_dwordx4 v184, s[24:25]
	s_mov_b32 m0, s44
	s_nop 0
	s_add_u32 s98, s66, 0x80
	s_addc_u32 s99, s67, 0
	global_load_lds_dwordx4 v178, s[98:99]
	s_mov_b32 m0, s45
	s_nop 0
	s_add_u32 s100, s66, 0x80
	s_addc_u32 s101, s67, 0
	global_load_lds_dwordx4 v182, s[100:101]
	s_waitcnt vmcnt(8)
	s_waitcnt lgkmcnt(0)
	s_barrier
	s_setprio 3
	s_waitcnt lgkmcnt(0)
	v_mfma_f32_16x16x32_bf16 v[62:65], v[82:85], v[162:165], v[62:65]
	v_mfma_f32_16x16x32_bf16 v[58:61], v[90:93], v[162:165], v[58:61]
	v_mfma_f32_16x16x32_bf16 v[46:49], v[82:85], v[170:173], v[46:49]
	v_mfma_f32_16x16x32_bf16 v[42:45], v[90:93], v[170:173], v[42:45]
	v_mfma_f32_16x16x32_bf16 v[30:33], v[82:85], v[194:197], v[30:33]
	v_mfma_f32_16x16x32_bf16 v[26:29], v[90:93], v[194:197], v[26:29]
	v_mfma_f32_16x16x32_bf16 v[14:17], v[82:85], v[208:211], v[14:17]
	v_mfma_f32_16x16x32_bf16 v[10:13], v[90:93], v[208:211], v[10:13]
	v_mfma_f32_16x16x32_bf16 v[62:65], v[86:89], v[166:169], v[62:65]
	v_mfma_f32_16x16x32_bf16 v[58:61], v[94:97], v[166:169], v[58:61]
	v_mfma_f32_16x16x32_bf16 v[46:49], v[86:89], v[174:177], v[46:49]
	v_mfma_f32_16x16x32_bf16 v[42:45], v[94:97], v[174:177], v[42:45]
	v_mfma_f32_16x16x32_bf16 v[30:33], v[86:89], v[198:201], v[30:33]
	v_mfma_f32_16x16x32_bf16 v[26:29], v[94:97], v[198:201], v[26:29]
	v_mfma_f32_16x16x32_bf16 v[14:17], v[86:89], v[212:215], v[14:17]
	v_mfma_f32_16x16x32_bf16 v[10:13], v[94:97], v[212:215], v[10:13]


; #define PG8_STAGE(bufoff, gbase, voff) do { _Pragma("unroll") for (int _i = 0; _i < 2; ++_i) \
;         __builtin_amdgcn_global_load_lds((const unsigned*)((const char*)(gbase) + (voff)[_i]), (PG8_LAS unsigned*)(lds + (bufoff) + ldsw + _i * 8192), 16, 0, 0); } while (0)
; #define PG8_LDA(dst, b, h) do { _Pragma("unroll") for (int m = 0; m < 4; ++m) _Pragma("unroll") for (int k = 0; k < 2; ++k) dst[m][k] = *(const PG8_LAS bf16x8*)(lds + PG8_SA(b, h) + aoff + m * 2048 + k * 1024); } while (0)
; #define PG8_LDB(dst, b, h) do { _Pragma("unroll") for (int n = 0; n < 2; ++n) _Pragma("unroll") for (int k = 0; k < 2; ++k) dst[n][k] = *(const PG8_LAS bf16x8*)(lds + PG8_SB(b, h) + boff + n * 2048 + k * 1024); } while (0)
; #define PG8_WAIT_V(n) asm volatile("s_waitcnt vmcnt(" #n ")" ::: "memory")
; #define PG8_WAIT_L(n) asm volatile("s_waitcnt lgkmcnt(" #n ")" ::: "memory")
; #define PG8_BAR __builtin_amdgcn_s_barrier()
; #define PG8_SCHED __builtin_amdgcn_sched_barrier(0)
; template <class Epi, class Sched, bool ALIGN_EPI = false, bool SP2 = false, bool F8 = false>
; __device__ __forceinline__ void gemm_phase(PG8_LAS unsigned char* lds, const Gemm g, const Sched& S, const Epi& E) {
;     ...
;             PG8_LDB(B0, 0, 0); PG8_LDB(B1, 0, 1); PG8_SCHED; PG8_LDA(At, 0, 0); PG8_STAGE(PG8_SA(1, 1), a1 + hstepA, voffA);
;             PG8_WAIT_V(8); PG8_WAIT_L(0); PG8_BAR; PG8_MMA(0, 0, At, B0); PG8_MMA(0, 1, At, B1); PG8_BAR; PG8_SCHED;
;             PG8_LDA(At, 0, 1); PG8_STAGE(PG8_SB(0, 0), b2, voffB); PG8_STAGE(PG8_SB(0, 1), b2 + hstep, voffB); PG8_STAGE(PG8_SA(0, 0), a2, voffA);
;             PG8_WAIT_V(8); PG8_WAIT_L(0); PG8_BAR; PG8_MMA(1, 0, At, B0); PG8_MMA(1, 1, At, B1); PG8_BAR; PG8_SCHED;
	v_mfma_f32_16x16x32_bf16 v[54:57], v[102:105], v[162:165], v[54:57]
	v_mfma_f32_16x16x32_bf16 v[50:53], v[114:117], v[162:165], v[50:53]
	v_mfma_f32_16x16x32_bf16 v[38:41], v[102:105], v[170:173], v[38:41]
	v_mfma_f32_16x16x32_bf16 v[34:37], v[114:117], v[170:173], v[34:37]
	v_mfma_f32_16x16x32_bf16 v[22:25], v[102:105], v[194:197], v[22:25]
	v_mfma_f32_16x16x32_bf16 v[18:21], v[114:117], v[194:197], v[18:21]
	v_mfma_f32_16x16x32_bf16 v[6:9], v[102:105], v[208:211], v[6:9]
	v_mfma_f32_16x16x32_bf16 v[2:5], v[114:117], v[208:211], v[2:5]
	v_mfma_f32_16x16x32_bf16 v[54:57], v[106:109], v[166:169], v[54:57]
	v_mfma_f32_16x16x32_bf16 v[50:53], v[118:121], v[166:169], v[50:53]
	v_mfma_f32_16x16x32_bf16 v[38:41], v[106:109], v[174:177], v[38:41]
	v_mfma_f32_16x16x32_bf16 v[34:37], v[118:121], v[174:177], v[34:37]
	v_mfma_f32_16x16x32_bf16 v[22:25], v[106:109], v[198:201], v[22:25]
	v_mfma_f32_16x16x32_bf16 v[18:21], v[118:121], v[198:201], v[18:21]
	v_mfma_f32_16x16x32_bf16 v[6:9], v[106:109], v[212:215], v[6:9]
	v_mfma_f32_16x16x32_bf16 v[2:5], v[118:121], v[212:215], v[2:5]
	s_setprio 0
	s_add_i32 s76, s76, 2
	s_add_u32 s62, s62, 0x100
	s_addc_u32 s63, s63, 0
	s_add_u32 s74, s74, 0x100
	s_addc_u32 s75, s75, 0
	s_cmp_gt_u32 s76, 29
	s_cbranch_scc0 .Lk2_Y
	s_branch .Lk2_exit
.Lk2_Xz:
	ds_read_b128 v[82:85], v204
	ds_read_b128 v[86:89], v204 offset:1024
	ds_read_b128 v[90:93], v204 offset:2048
	ds_read_b128 v[94:97], v204 offset:3072
	ds_read_b128 v[102:105], v205
	ds_read_b128 v[106:109], v205 offset:1024
	ds_read_b128 v[114:117], v205 offset:2048
	ds_read_b128 v[118:121], v205 offset:3072
	s_add_u32 s24, s62, 0xfff80080
	s_addc_u32 s25, s63, -1
	s_cmp_eq_u32 s76, 28
	s_cselect_b32 s67, s55, s25
	s_cselect_b32 s66, s61, s24
	s_cselect_b32 s65, s53, s75
	s_cselect_b32 s64, s73, s74
	s_add_i32 m0, s15, 0xc000
	ds_read_b128 v[162:165], v206
	ds_read_b128 v[166:169], v206 offset:1024
	ds_read_b128 v[170:173], v206 offset:2048
	ds_read_b128 v[174:177], v206 offset:3072
	ds_read_b128 v[194:197], v206 offset:4096
	ds_read_b128 v[198:201], v206 offset:5120
	ds_read_b128 v[208:211], v206 offset:6144
	ds_read_b128 v[212:215], v206 offset:7168
	global_load_lds_dwordx4 v186, s[62:63]
	s_add_i32 m0, s15, 0xe000
	s_nop 0
	global_load_lds_dwordx4 v188, s[62:63]
	s_waitcnt vmcnt(8)
	s_waitcnt lgkmcnt(0)
	s_setprio 1
	s_waitcnt lgkmcnt(0)
	v_mfma_f32_16x16x32_bf16 v[158:161], v[82:85], v[162:165], 0
	v_mfma_f32_16x16x32_bf16 v[154:157], v[90:93], v[162:165], 0
	v_mfma_f32_16x16x32_bf16 v[142:145], v[82:85], v[170:173], 0
	v_mfma_f32_16x16x32_bf16 v[138:141], v[90:93], v[170:173], 0
	v_mfma_f32_16x16x32_bf16 v[126:129], v[82:85], v[194:197], 0
	v_mfma_f32_16x16x32_bf16 v[122:125], v[90:93], v[194:197], 0
	v_mfma_f32_16x16x32_bf16 v[78:81], v[82:85], v[208:211], 0
	v_mfma_f32_16x16x32_bf16 v[74:77], v[90:93], v[208:211], 0
	v_mfma_f32_16x16x32_bf16 v[158:161], v[86:89], v[166:169], v[158:161]
	v_mfma_f32_16x16x32_bf16 v[154:157], v[94:97], v[166:169], v[154:157]
	v_mfma_f32_16x16x32_bf16 v[142:145], v[86:89], v[174:177], v[142:145]
	v_mfma_f32_16x16x32_bf16 v[138:141], v[94:97], v[174:177], v[138:141]
	v_mfma_f32_16x16x32_bf16 v[126:129], v[86:89], v[198:201], v[126:129]
	v_mfma_f32_16x16x32_bf16 v[122:125], v[94:97], v[198:201], v[122:125]
	v_mfma_f32_16x16x32_bf16 v[78:81], v[86:89], v[212:215], v[78:81]
	v_mfma_f32_16x16x32_bf16 v[74:77], v[94:97], v[212:215], v[74:77]
	s_setprio 0
	s_setprio 1
	v_mfma_f32_16x16x32_bf16 v[150:153], v[102:105], v[162:165], 0
	v_mfma_f32_16x16x32_bf16 v[146:149], v[114:117], v[162:165], 0
	v_mfma_f32_16x16x32_bf16 v[134:137], v[102:105], v[170:173], 0
	v_mfma_f32_16x16x32_bf16 v[130:133], v[114:117], v[170:173], 0
	v_mfma_f32_16x16x32_bf16 v[110:113], v[102:105], v[194:197], 0
	v_mfma_f32_16x16x32_bf16 v[98:101], v[114:117], v[194:197], 0
	v_mfma_f32_16x16x32_bf16 v[70:73], v[102:105], v[208:211], 0
	v_mfma_f32_16x16x32_bf16 v[66:69], v[114:117], v[208:211], 0
	v_mfma_f32_16x16x32_bf16 v[150:153], v[106:109], v[166:169], v[150:153]
	v_mfma_f32_16x16x32_bf16 v[146:149], v[118:121], v[166:169], v[146:149]
	v_mfma_f32_16x16x32_bf16 v[134:137], v[106:109], v[174:177], v[134:137]
	v_mfma_f32_16x16x32_bf16 v[130:133], v[118:121], v[174:177], v[130:133]
	v_mfma_f32_16x16x32_bf16 v[110:113], v[106:109], v[198:201], v[110:113]
	v_mfma_f32_16x16x32_bf16 v[98:101], v[118:121], v[198:201], v[98:101]
	v_mfma_f32_16x16x32_bf16 v[70:73], v[106:109], v[212:215], v[70:73]
	v_mfma_f32_16x16x32_bf16 v[66:69], v[118:121], v[212:215], v[66:69]
	s_setprio 0
	s_barrier
; #define PG8_STAGE(bufoff, gbase, voff) do { _Pragma("unroll") for (int _i = 0; _i < 2; ++_i) \
;         __builtin_amdgcn_global_load_lds((const unsigned*)((const char*)(gbase) + (voff)[_i]), (PG8_LAS unsigned*)(lds + (bufoff) + ldsw + _i * 8192), 16, 0, 0); } while (0)
; #define PG8_LDA(dst, b, h) do { _Pragma("unroll") for (int m = 0; m < 4; ++m) _Pragma("unroll") for (int k = 0; k < 2; ++k) dst[m][k] = *(const PG8_LAS bf16x8*)(lds + PG8_SA(b, h) + aoff + m * 2048 + k * 1024); } while (0)
; #define PG8_LDB(dst, b, h) do { _Pragma("unroll") for (int n = 0; n < 2; ++n) _Pragma("unroll") for (int k = 0; k < 2; ++k) dst[n][k] = *(const PG8_LAS bf16x8*)(lds + PG8_SB(b, h) + boff + n * 2048 + k * 1024); } while (0)
; #define PG8_WAIT_V(n) asm volatile("s_waitcnt vmcnt(" #n ")" ::: "memory")
; #define PG8_WAIT_L(n) asm volatile("s_waitcnt lgkmcnt(" #n ")" ::: "memory")
; #define PG8_BAR __builtin_amdgcn_s_barrier()
; #define PG8_SCHED __builtin_amdgcn_sched_barrier(0)
; template <class Epi, class Sched, bool ALIGN_EPI = false, bool SP2 = false, bool F8 = false>
; __device__ __forceinline__ void gemm_phase(PG8_LAS unsigned char* lds, const Gemm g, const Sched& S, const Epi& E) {
;     ...
;             PG8_LDA(At, 0, 1); PG8_STAGE(PG8_SB(0, 0), b2, voffB); PG8_STAGE(PG8_SB(0, 1), b2 + hstep, voffB); PG8_STAGE(PG8_SA(0, 0), a2, voffA);
;             PG8_WAIT_V(8); PG8_WAIT_L(0); PG8_BAR; PG8_MMA(1, 0, At, B0); PG8_MMA(1, 1, At, B1); PG8_BAR; PG8_SCHED;
;             PG8_LDB(B0, 1, 0); PG8_LDB(B1, 1, 1); PG8_SCHED; PG8_LDA(At, 1, 0); PG8_STAGE(PG8_SA(0, 1), a2 + hstepA, voffA);
;             PG8_WAIT_V(8); PG8_WAIT_L(0); PG8_BAR; PG8_MMA(0, 0, At, B0); PG8_MMA(0, 1, At, B1); PG8_BAR; PG8_SCHED;
	s_add_i32 s24, s70, s14
	s_mov_b32 m0, s24
	ds_read_b128 v[162:165], v206 offset:16384
	ds_read_b128 v[166:169], v206 offset:17408
	ds_read_b128 v[170:173], v206 offset:18432
	ds_read_b128 v[174:177], v206 offset:19456
	ds_read_b128 v[194:197], v206 offset:20480
	ds_read_b128 v[198:201], v206 offset:21504
	ds_read_b128 v[208:211], v206 offset:22528
	ds_read_b128 v[212:215], v206 offset:23552
	global_load_lds_dwordx4 v180, s[64:65]
	s_add_i32 m0, s24, 0x2000
	s_add_u32 s24, s64, 0x80000
	s_addc_u32 s25, s65, 0
	s_add_i32 s36, s71, s14
	global_load_lds_dwordx4 v184, s[64:65]
	s_mov_b32 m0, s36
	s_nop 0
	global_load_lds_dwordx4 v180, s[24:25]
	s_add_i32 m0, s36, 0x2000
	s_nop 0
	global_load_lds_dwordx4 v184, s[24:25]
	s_mov_b32 m0, s15
	s_nop 0
	global_load_lds_dwordx4 v178, s[66:67]
	s_mov_b32 m0, s23
	s_nop 0
	global_load_lds_dwordx4 v182, s[66:67]
	s_waitcnt vmcnt(8)
	s_waitcnt lgkmcnt(0)
	s_setprio 1
	s_waitcnt lgkmcnt(0)
	v_mfma_f32_16x16x32_bf16 v[62:65], v[82:85], v[162:165], 0
	v_mfma_f32_16x16x32_bf16 v[58:61], v[90:93], v[162:165], 0
	v_mfma_f32_16x16x32_bf16 v[46:49], v[82:85], v[170:173], 0
	v_mfma_f32_16x16x32_bf16 v[42:45], v[90:93], v[170:173], 0
	v_mfma_f32_16x16x32_bf16 v[30:33], v[82:85], v[194:197], 0
	v_mfma_f32_16x16x32_bf16 v[26:29], v[90:93], v[194:197], 0
	v_mfma_f32_16x16x32_bf16 v[14:17], v[82:85], v[208:211], 0
	v_mfma_f32_16x16x32_bf16 v[10:13], v[90:93], v[208:211], 0
	v_mfma_f32_16x16x32_bf16 v[62:65], v[86:89], v[166:169], v[62:65]
	v_mfma_f32_16x16x32_bf16 v[58:61], v[94:97], v[166:169], v[58:61]
	v_mfma_f32_16x16x32_bf16 v[46:49], v[86:89], v[174:177], v[46:49]
	v_mfma_f32_16x16x32_bf16 v[42:45], v[94:97], v[174:177], v[42:45]
	v_mfma_f32_16x16x32_bf16 v[30:33], v[86:89], v[198:201], v[30:33]
	v_mfma_f32_16x16x32_bf16 v[26:29], v[94:97], v[198:201], v[26:29]
	v_mfma_f32_16x16x32_bf16 v[14:17], v[86:89], v[212:215], v[14:17]
	v_mfma_f32_16x16x32_bf16 v[10:13], v[94:97], v[212:215], v[10:13]
	s_setprio 0
	s_setprio 1
	v_mfma_f32_16x16x32_bf16 v[54:57], v[102:105], v[162:165], 0
	v_mfma_f32_16x16x32_bf16 v[50:53], v[114:117], v[162:165], 0
	v_mfma_f32_16x16x32_bf16 v[38:41], v[102:105], v[170:173], 0
	v_mfma_f32_16x16x32_bf16 v[34:37], v[114:117], v[170:173], 0
	v_mfma_f32_16x16x32_bf16 v[22:25], v[102:105], v[194:197], 0
	v_mfma_f32_16x16x32_bf16 v[18:21], v[114:117], v[194:197], 0
	v_mfma_f32_16x16x32_bf16 v[6:9], v[102:105], v[208:211], 0
	v_mfma_f32_16x16x32_bf16 v[2:5], v[114:117], v[208:211], 0
	v_mfma_f32_16x16x32_bf16 v[54:57], v[106:109], v[166:169], v[54:57]
	v_mfma_f32_16x16x32_bf16 v[50:53], v[118:121], v[166:169], v[50:53]
	v_mfma_f32_16x16x32_bf16 v[38:41], v[106:109], v[174:177], v[38:41]
	v_mfma_f32_16x16x32_bf16 v[34:37], v[118:121], v[174:177], v[34:37]
	v_mfma_f32_16x16x32_bf16 v[22:25], v[106:109], v[198:201], v[22:25]
	v_mfma_f32_16x16x32_bf16 v[18:21], v[118:121], v[198:201], v[18:21]
	v_mfma_f32_16x16x32_bf16 v[6:9], v[106:109], v[212:215], v[6:9]
	v_mfma_f32_16x16x32_bf16 v[2:5], v[118:121], v[212:215], v[2:5]
	s_setprio 0
	s_barrier
	s_add_i32 s36, 0, 0x18000
	s_add_i32 s37, 0, 0x1c000
	v_add_u32_e32 v94, s36, v202
	v_add_u32_e32 v118, s37, v202
	ds_read_b128 v[82:85], v94
	ds_read_b128 v[86:89], v94 offset:1024
	ds_read_b128 v[90:93], v94 offset:2048
	ds_read_b128 v[94:97], v94 offset:3072
	ds_read_b128 v[102:105], v118
	ds_read_b128 v[106:109], v118 offset:1024
	ds_read_b128 v[114:117], v118 offset:2048
	ds_read_b128 v[118:121], v118 offset:3072
	s_add_u32 s24, s66, 0x80000
	s_addc_u32 s25, s67, 0
	s_mov_b32 m0, s26
	ds_read_b128 v[162:165], v206 offset:32768
	ds_read_b128 v[166:169], v206 offset:33792
	ds_read_b128 v[170:173], v206 offset:34816
	ds_read_b128 v[174:177], v206 offset:35840
	ds_read_b128 v[194:197], v206 offset:36864
	ds_read_b128 v[198:201], v206 offset:37888
	ds_read_b128 v[208:211], v206 offset:38912
	ds_read_b128 v[212:215], v206 offset:39936
	global_load_lds_dwordx4 v178, s[24:25]
	s_mov_b32 m0, s27
	s_nop 0
	global_load_lds_dwordx4 v182, s[24:25]
	s_waitcnt vmcnt(8)
	s_waitcnt lgkmcnt(0)
	s_setprio 1
	s_waitcnt lgkmcnt(0)
	v_mfma_f32_16x16x32_bf16 v[158:161], v[82:85], v[162:165], v[158:161]
	v_mfma_f32_16x16x32_bf16 v[154:157], v[90:93], v[162:165], v[154:157]
	v_mfma_f32_16x16x32_bf16 v[142:145], v[82:85], v[170:173], v[142:145]
	v_mfma_f32_16x16x32_bf16 v[138:141], v[90:93], v[170:173], v[138:141]
	v_mfma_f32_16x16x32_bf16 v[126:129], v[82:85], v[194:197], v[126:129]
	v_mfma_f32_16x16x32_bf16 v[122:125], v[90:93], v[194:197], v[122:125]
	v_mfma_f32_16x16x32_bf16 v[78:81], v[82:85], v[208:211], v[78:81]
	v_mfma_f32_16x16x32_bf16 v[74:77], v[90:93], v[208:211], v[74:77]
	v_mfma_f32_16x16x32_bf16 v[158:161], v[86:89], v[166:169], v[158:161]
	v_mfma_f32_16x16x32_bf16 v[154:157], v[94:97], v[166:169], v[154:157]
	v_mfma_f32_16x16x32_bf16 v[142:145], v[86:89], v[174:177], v[142:145]
	v_mfma_f32_16x16x32_bf16 v[138:141], v[94:97], v[174:177], v[138:141]
	v_mfma_f32_16x16x32_bf16 v[126:129], v[86:89], v[198:201], v[126:129]
	v_mfma_f32_16x16x32_bf16 v[122:125], v[94:97], v[198:201], v[122:125]
	v_mfma_f32_16x16x32_bf16 v[78:81], v[86:89], v[212:215], v[78:81]
	v_mfma_f32_16x16x32_bf16 v[74:77], v[94:97], v[212:215], v[74:77]
	s_setprio 0
	s_setprio 1
	v_mfma_f32_16x16x32_bf16 v[150:153], v[102:105], v[162:165], v[150:153]
	v_mfma_f32_16x16x32_bf16 v[146:149], v[114:117], v[162:165], v[146:149]
	v_mfma_f32_16x16x32_bf16 v[134:137], v[102:105], v[170:173], v[134:137]
	v_mfma_f32_16x16x32_bf16 v[130:133], v[114:117], v[170:173], v[130:133]
	v_mfma_f32_16x16x32_bf16 v[110:113], v[102:105], v[194:197], v[110:113]
	v_mfma_f32_16x16x32_bf16 v[98:101], v[114:117], v[194:197], v[98:101]
	v_mfma_f32_16x16x32_bf16 v[70:73], v[102:105], v[208:211], v[70:73]
	v_mfma_f32_16x16x32_bf16 v[66:69], v[114:117], v[208:211], v[66:69]
	v_mfma_f32_16x16x32_bf16 v[150:153], v[106:109], v[166:169], v[150:153]
	v_mfma_f32_16x16x32_bf16 v[146:149], v[118:121], v[166:169], v[146:149]
	v_mfma_f32_16x16x32_bf16 v[134:137], v[106:109], v[174:177], v[134:137]
	v_mfma_f32_16x16x32_bf16 v[130:133], v[118:121], v[174:177], v[130:133]
	v_mfma_f32_16x16x32_bf16 v[110:113], v[106:109], v[198:201], v[110:113]
	v_mfma_f32_16x16x32_bf16 v[98:101], v[118:121], v[198:201], v[98:101]
	v_mfma_f32_16x16x32_bf16 v[70:73], v[106:109], v[212:215], v[70:73]
	v_mfma_f32_16x16x32_bf16 v[66:69], v[118:121], v[212:215], v[66:69]
	s_setprio 0
	s_barrier
; #define PG8_STAGE(bufoff, gbase, voff) do { _Pragma("unroll") for (int _i = 0; _i < 2; ++_i) \
;         __builtin_amdgcn_global_load_lds((const unsigned*)((const char*)(gbase) + (voff)[_i]), (PG8_LAS unsigned*)(lds + (bufoff) + ldsw + _i * 8192), 16, 0, 0); } while (0)
; #define PG8_LDA(dst, b, h) do { _Pragma("unroll") for (int m = 0; m < 4; ++m) _Pragma("unroll") for (int k = 0; k < 2; ++k) dst[m][k] = *(const PG8_LAS bf16x8*)(lds + PG8_SA(b, h) + aoff + m * 2048 + k * 1024); } while (0)
; #define PG8_LDB(dst, b, h) do { _Pragma("unroll") for (int n = 0; n < 2; ++n) _Pragma("unroll") for (int k = 0; k < 2; ++k) dst[n][k] = *(const PG8_LAS bf16x8*)(lds + PG8_SB(b, h) + boff + n * 2048 + k * 1024); } while (0)
; #define PG8_WAIT_V(n) asm volatile("s_waitcnt vmcnt(" #n ")" ::: "memory")
; #define PG8_WAIT_L(n) asm volatile("s_waitcnt lgkmcnt(" #n ")" ::: "memory")
; #define PG8_BAR __builtin_amdgcn_s_barrier()
; #define PG8_SCHED __builtin_amdgcn_sched_barrier(0)
; template <class Epi, class Sched, bool ALIGN_EPI = false, bool SP2 = false, bool F8 = false>
; __device__ __forceinline__ void gemm_phase(PG8_LAS unsigned char* lds, const Gemm g, const Sched& S, const Epi& E) {
;     ...
;             PG8_LDB(B0, 0, 0); PG8_LDB(B1, 0, 1); PG8_SCHED; PG8_LDA(At, 0, 0); PG8_STAGE(PG8_SA(1, 1), a1 + hstepA, voffA);
;             PG8_WAIT_V(8); PG8_WAIT_L(0); PG8_BAR; PG8_MMA(0, 0, At, B0); PG8_MMA(0, 1, At, B1); PG8_BAR; PG8_SCHED;
;     ...
;             PG8_LDA(At, 1, 1); PG8_STAGE(PG8_SB(1, 0), b3, voffB); PG8_STAGE(PG8_SB(1, 1), b3 + hstep, voffB); PG8_STAGE(PG8_SA(1, 0), a3, voffA);
;             PG8_WAIT_V(8); PG8_WAIT_L(0); PG8_BAR; PG8_MMA(1, 0, At, B0); PG8_MMA(1, 1, At, B1); PG8_BAR; PG8_SCHED;
	s_add_i32 s24, s36, s14
	s_mov_b32 m0, s24
	ds_read_b128 v[162:165], v206 offset:49152
	ds_read_b128 v[166:169], v206 offset:50176
	ds_read_b128 v[170:173], v206 offset:51200
	ds_read_b128 v[174:177], v206 offset:52224
	ds_read_b128 v[194:197], v206 offset:53248
	ds_read_b128 v[198:201], v206 offset:54272
	ds_read_b128 v[208:211], v206 offset:55296
	ds_read_b128 v[212:215], v206 offset:56320
	s_add_u32 s98, s64, 0x80
	s_addc_u32 s99, s65, 0
	global_load_lds_dwordx4 v180, s[98:99]
	s_add_i32 m0, s24, 0x2000
	s_add_u32 s24, s64, 0x80080
	s_addc_u32 s25, s65, 0
	s_add_i32 s36, s37, s14
	s_add_u32 s100, s64, 0x80
	s_addc_u32 s101, s65, 0
	global_load_lds_dwordx4 v184, s[100:101]
	s_mov_b32 m0, s36
	s_nop 0
	global_load_lds_dwordx4 v180, s[24:25]
	s_add_i32 m0, s36, 0x2000
	s_nop 0
	global_load_lds_dwordx4 v184, s[24:25]
	s_mov_b32 m0, s44
	s_nop 0
	s_add_u32 s98, s66, 0x80
	s_addc_u32 s99, s67, 0
	global_load_lds_dwordx4 v178, s[98:99]
	s_mov_b32 m0, s45
	s_nop 0
	s_add_u32 s100, s66, 0x80
	s_addc_u32 s101, s67, 0
	global_load_lds_dwordx4 v182, s[100:101]
	s_waitcnt vmcnt(8)
	s_waitcnt lgkmcnt(0)
	s_setprio 1
	s_waitcnt lgkmcnt(0)
	v_mfma_f32_16x16x32_bf16 v[62:65], v[82:85], v[162:165], v[62:65]
	v_mfma_f32_16x16x32_bf16 v[58:61], v[90:93], v[162:165], v[58:61]
	v_mfma_f32_16x16x32_bf16 v[46:49], v[82:85], v[170:173], v[46:49]
	v_mfma_f32_16x16x32_bf16 v[42:45], v[90:93], v[170:173], v[42:45]
	v_mfma_f32_16x16x32_bf16 v[30:33], v[82:85], v[194:197], v[30:33]
	v_mfma_f32_16x16x32_bf16 v[26:29], v[90:93], v[194:197], v[26:29]
	v_mfma_f32_16x16x32_bf16 v[14:17], v[82:85], v[208:211], v[14:17]
	v_mfma_f32_16x16x32_bf16 v[10:13], v[90:93], v[208:211], v[10:13]
	v_mfma_f32_16x16x32_bf16 v[62:65], v[86:89], v[166:169], v[62:65]
	v_mfma_f32_16x16x32_bf16 v[58:61], v[94:97], v[166:169], v[58:61]
	v_mfma_f32_16x16x32_bf16 v[46:49], v[86:89], v[174:177], v[46:49]
	v_mfma_f32_16x16x32_bf16 v[42:45], v[94:97], v[174:177], v[42:45]
	v_mfma_f32_16x16x32_bf16 v[30:33], v[86:89], v[198:201], v[30:33]
	v_mfma_f32_16x16x32_bf16 v[26:29], v[94:97], v[198:201], v[26:29]
	v_mfma_f32_16x16x32_bf16 v[14:17], v[86:89], v[212:215], v[14:17]
	v_mfma_f32_16x16x32_bf16 v[10:13], v[94:97], v[212:215], v[10:13]
	s_setprio 0
	s_setprio 1
	v_mfma_f32_16x16x32_bf16 v[54:57], v[102:105], v[162:165], v[54:57]
	v_mfma_f32_16x16x32_bf16 v[50:53], v[114:117], v[162:165], v[50:53]
	v_mfma_f32_16x16x32_bf16 v[38:41], v[102:105], v[170:173], v[38:41]
	v_mfma_f32_16x16x32_bf16 v[34:37], v[114:117], v[170:173], v[34:37]
	v_mfma_f32_16x16x32_bf16 v[22:25], v[102:105], v[194:197], v[22:25]
	v_mfma_f32_16x16x32_bf16 v[18:21], v[114:117], v[194:197], v[18:21]
	v_mfma_f32_16x16x32_bf16 v[6:9], v[102:105], v[208:211], v[6:9]
	v_mfma_f32_16x16x32_bf16 v[2:5], v[114:117], v[208:211], v[2:5]
	v_mfma_f32_16x16x32_bf16 v[54:57], v[106:109], v[166:169], v[54:57]
	v_mfma_f32_16x16x32_bf16 v[50:53], v[118:121], v[166:169], v[50:53]
	v_mfma_f32_16x16x32_bf16 v[38:41], v[106:109], v[174:177], v[38:41]
	v_mfma_f32_16x16x32_bf16 v[34:37], v[118:121], v[174:177], v[34:37]
	v_mfma_f32_16x16x32_bf16 v[22:25], v[106:109], v[198:201], v[22:25]
	v_mfma_f32_16x16x32_bf16 v[18:21], v[118:121], v[198:201], v[18:21]
	v_mfma_f32_16x16x32_bf16 v[6:9], v[106:109], v[212:215], v[6:9]
	v_mfma_f32_16x16x32_bf16 v[2:5], v[118:121], v[212:215], v[2:5]
	s_setprio 0
	s_barrier
	s_add_i32 s76, s76, 2
	s_add_u32 s62, s62, 0x100
	s_addc_u32 s63, s63, 0
	s_add_u32 s74, s74, 0x100
	s_addc_u32 s75, s75, 0
	s_cmp_gt_u32 s76, 29
	s_branch .LBB0_772
.Lk2_Yz:
	ds_read_b128 v[82:85], v204
	ds_read_b128 v[86:89], v204 offset:1024
	ds_read_b128 v[90:93], v204 offset:2048
	ds_read_b128 v[94:97], v204 offset:3072
	ds_read_b128 v[102:105], v205
	ds_read_b128 v[106:109], v205 offset:1024
	ds_read_b128 v[114:117], v205 offset:2048
	ds_read_b128 v[118:121], v205 offset:3072
	s_add_u32 s24, s62, 0xfff80080
	s_addc_u32 s25, s63, -1
	s_cmp_eq_u32 s76, 28
	s_cselect_b32 s67, s55, s25
	s_cselect_b32 s66, s61, s24
	s_cselect_b32 s65, s53, s75
	s_cselect_b32 s64, s73, s74
	s_add_i32 m0, s15, 0xc000
	ds_read_b128 v[162:165], v206
	ds_read_b128 v[166:169], v206 offset:1024
	ds_read_b128 v[170:173], v206 offset:2048
	ds_read_b128 v[174:177], v206 offset:3072
	ds_read_b128 v[194:197], v206 offset:4096
	ds_read_b128 v[198:201], v206 offset:5120
	ds_read_b128 v[208:211], v206 offset:6144
	ds_read_b128 v[212:215], v206 offset:7168
	global_load_lds_dwordx4 v186, s[62:63]
	s_add_i32 m0, s15, 0xe000
	s_nop 0
	global_load_lds_dwordx4 v188, s[62:63]
	s_waitcnt vmcnt(8)
	s_waitcnt lgkmcnt(0)
	s_barrier
	s_setprio 3
	s_waitcnt lgkmcnt(0)
	v_mfma_f32_16x16x32_bf16 v[158:161], v[82:85], v[162:165], 0
	v_mfma_f32_16x16x32_bf16 v[154:157], v[90:93], v[162:165], 0
	v_mfma_f32_16x16x32_bf16 v[142:145], v[82:85], v[170:173], 0
	v_mfma_f32_16x16x32_bf16 v[138:141], v[90:93], v[170:173], 0
	v_mfma_f32_16x16x32_bf16 v[126:129], v[82:85], v[194:197], 0
	v_mfma_f32_16x16x32_bf16 v[122:125], v[90:93], v[194:197], 0
	v_mfma_f32_16x16x32_bf16 v[78:81], v[82:85], v[208:211], 0
	v_mfma_f32_16x16x32_bf16 v[74:77], v[90:93], v[208:211], 0
	v_mfma_f32_16x16x32_bf16 v[158:161], v[86:89], v[166:169], v[158:161]
	v_mfma_f32_16x16x32_bf16 v[154:157], v[94:97], v[166:169], v[154:157]
	v_mfma_f32_16x16x32_bf16 v[142:145], v[86:89], v[174:177], v[142:145]
	v_mfma_f32_16x16x32_bf16 v[138:141], v[94:97], v[174:177], v[138:141]
	v_mfma_f32_16x16x32_bf16 v[126:129], v[86:89], v[198:201], v[126:129]
	v_mfma_f32_16x16x32_bf16 v[122:125], v[94:97], v[198:201], v[122:125]
	v_mfma_f32_16x16x32_bf16 v[78:81], v[86:89], v[212:215], v[78:81]
	v_mfma_f32_16x16x32_bf16 v[74:77], v[94:97], v[212:215], v[74:77]


; #define PG8_STAGE(bufoff, gbase, voff) do { _Pragma("unroll") for (int _i = 0; _i < 2; ++_i) \
;         __builtin_amdgcn_global_load_lds((const unsigned*)((const char*)(gbase) + (voff)[_i]), (PG8_LAS unsigned*)(lds + (bufoff) + ldsw + _i * 8192), 16, 0, 0); } while (0)
; #define PG8_LDA(dst, b, h) do { _Pragma("unroll") for (int m = 0; m < 4; ++m) _Pragma("unroll") for (int k = 0; k < 2; ++k) dst[m][k] = *(const PG8_LAS bf16x8*)(lds + PG8_SA(b, h) + aoff + m * 2048 + k * 1024); } while (0)
; #define PG8_WAIT_V(n) asm volatile("s_waitcnt vmcnt(" #n ")" ::: "memory")
; #define PG8_WAIT_L(n) asm volatile("s_waitcnt lgkmcnt(" #n ")" ::: "memory")
; #define PG8_BAR __builtin_amdgcn_s_barrier()
; #define PG8_SCHED __builtin_amdgcn_sched_barrier(0)
; template <class Epi, class Sched, bool ALIGN_EPI = false, bool SP2 = false, bool F8 = false>
; __device__ __forceinline__ void gemm_phase(PG8_LAS unsigned char* lds, const Gemm g, const Sched& S, const Epi& E) {
;     ...
;             PG8_WAIT_V(8); PG8_WAIT_L(0); PG8_BAR; PG8_MMA(0, 0, At, B0); PG8_MMA(0, 1, At, B1); PG8_BAR; PG8_SCHED;
;             PG8_LDA(At, 0, 1); PG8_STAGE(PG8_SB(0, 0), b2, voffB); PG8_STAGE(PG8_SB(0, 1), b2 + hstep, voffB); PG8_STAGE(PG8_SA(0, 0), a2, voffA);
;             PG8_WAIT_V(8); PG8_WAIT_L(0); PG8_BAR; PG8_MMA(1, 0, At, B0); PG8_MMA(1, 1, At, B1); PG8_BAR; PG8_SCHED;
	v_mfma_f32_16x16x32_bf16 v[150:153], v[102:105], v[162:165], 0
	v_mfma_f32_16x16x32_bf16 v[146:149], v[114:117], v[162:165], 0
	v_mfma_f32_16x16x32_bf16 v[134:137], v[102:105], v[170:173], 0
	v_mfma_f32_16x16x32_bf16 v[130:133], v[114:117], v[170:173], 0
	v_mfma_f32_16x16x32_bf16 v[110:113], v[102:105], v[194:197], 0
	v_mfma_f32_16x16x32_bf16 v[98:101], v[114:117], v[194:197], 0
	v_mfma_f32_16x16x32_bf16 v[70:73], v[102:105], v[208:211], 0
	v_mfma_f32_16x16x32_bf16 v[66:69], v[114:117], v[208:211], 0
	v_mfma_f32_16x16x32_bf16 v[150:153], v[106:109], v[166:169], v[150:153]
	v_mfma_f32_16x16x32_bf16 v[146:149], v[118:121], v[166:169], v[146:149]
	v_mfma_f32_16x16x32_bf16 v[134:137], v[106:109], v[174:177], v[134:137]
	v_mfma_f32_16x16x32_bf16 v[130:133], v[118:121], v[174:177], v[130:133]
	v_mfma_f32_16x16x32_bf16 v[110:113], v[106:109], v[198:201], v[110:113]
	v_mfma_f32_16x16x32_bf16 v[98:101], v[118:121], v[198:201], v[98:101]
	v_mfma_f32_16x16x32_bf16 v[70:73], v[106:109], v[212:215], v[70:73]
	v_mfma_f32_16x16x32_bf16 v[66:69], v[118:121], v[212:215], v[66:69]
	s_setprio 0
	s_add_i32 s24, s70, s14
	s_mov_b32 m0, s24
	ds_read_b128 v[162:165], v206 offset:16384
	ds_read_b128 v[166:169], v206 offset:17408
	ds_read_b128 v[170:173], v206 offset:18432
	ds_read_b128 v[174:177], v206 offset:19456
	ds_read_b128 v[194:197], v206 offset:20480
	ds_read_b128 v[198:201], v206 offset:21504
	ds_read_b128 v[208:211], v206 offset:22528
	ds_read_b128 v[212:215], v206 offset:23552
	global_load_lds_dwordx4 v180, s[64:65]
	s_add_i32 m0, s24, 0x2000
	s_add_u32 s24, s64, 0x80000
	s_addc_u32 s25, s65, 0
	s_add_i32 s36, s71, s14
	global_load_lds_dwordx4 v184, s[64:65]
	s_mov_b32 m0, s36
	s_nop 0
	global_load_lds_dwordx4 v180, s[24:25]
	s_add_i32 m0, s36, 0x2000
	s_nop 0
	global_load_lds_dwordx4 v184, s[24:25]
	s_mov_b32 m0, s15
	s_nop 0
	global_load_lds_dwordx4 v178, s[66:67]
	s_mov_b32 m0, s23
	s_nop 0
	global_load_lds_dwordx4 v182, s[66:67]
	s_waitcnt vmcnt(8)
	s_waitcnt lgkmcnt(0)
	s_barrier
	s_setprio 3
	s_waitcnt lgkmcnt(0)
	v_mfma_f32_16x16x32_bf16 v[62:65], v[82:85], v[162:165], 0
	v_mfma_f32_16x16x32_bf16 v[58:61], v[90:93], v[162:165], 0
	v_mfma_f32_16x16x32_bf16 v[46:49], v[82:85], v[170:173], 0
	v_mfma_f32_16x16x32_bf16 v[42:45], v[90:93], v[170:173], 0
	v_mfma_f32_16x16x32_bf16 v[30:33], v[82:85], v[194:197], 0
	v_mfma_f32_16x16x32_bf16 v[26:29], v[90:93], v[194:197], 0
	v_mfma_f32_16x16x32_bf16 v[14:17], v[82:85], v[208:211], 0
	v_mfma_f32_16x16x32_bf16 v[10:13], v[90:93], v[208:211], 0
	v_mfma_f32_16x16x32_bf16 v[62:65], v[86:89], v[166:169], v[62:65]
	v_mfma_f32_16x16x32_bf16 v[58:61], v[94:97], v[166:169], v[58:61]
	v_mfma_f32_16x16x32_bf16 v[46:49], v[86:89], v[174:177], v[46:49]
	v_mfma_f32_16x16x32_bf16 v[42:45], v[94:97], v[174:177], v[42:45]
	v_mfma_f32_16x16x32_bf16 v[30:33], v[86:89], v[198:201], v[30:33]
	v_mfma_f32_16x16x32_bf16 v[26:29], v[94:97], v[198:201], v[26:29]
	v_mfma_f32_16x16x32_bf16 v[14:17], v[86:89], v[212:215], v[14:17]
	v_mfma_f32_16x16x32_bf16 v[10:13], v[94:97], v[212:215], v[10:13]


; #define PG8_STAGE(bufoff, gbase, voff) do { _Pragma("unroll") for (int _i = 0; _i < 2; ++_i) \
;         __builtin_amdgcn_global_load_lds((const unsigned*)((const char*)(gbase) + (voff)[_i]), (PG8_LAS unsigned*)(lds + (bufoff) + ldsw + _i * 8192), 16, 0, 0); } while (0)
; #define PG8_LDA(dst, b, h) do { _Pragma("unroll") for (int m = 0; m < 4; ++m) _Pragma("unroll") for (int k = 0; k < 2; ++k) dst[m][k] = *(const PG8_LAS bf16x8*)(lds + PG8_SA(b, h) + aoff + m * 2048 + k * 1024); } while (0)
; #define PG8_LDB(dst, b, h) do { _Pragma("unroll") for (int n = 0; n < 2; ++n) _Pragma("unroll") for (int k = 0; k < 2; ++k) dst[n][k] = *(const PG8_LAS bf16x8*)(lds + PG8_SB(b, h) + boff + n * 2048 + k * 1024); } while (0)
; #define PG8_WAIT_V(n) asm volatile("s_waitcnt vmcnt(" #n ")" ::: "memory")
; #define PG8_WAIT_L(n) asm volatile("s_waitcnt lgkmcnt(" #n ")" ::: "memory")
; #define PG8_BAR __builtin_amdgcn_s_barrier()
; #define PG8_SCHED __builtin_amdgcn_sched_barrier(0)
; template <class Epi, class Sched, bool ALIGN_EPI = false, bool SP2 = false, bool F8 = false>
; __device__ __forceinline__ void gemm_phase(PG8_LAS unsigned char* lds, const Gemm g, const Sched& S, const Epi& E) {
;     ...
;             PG8_WAIT_V(8); PG8_WAIT_L(0); PG8_BAR; PG8_MMA(1, 0, At, B0); PG8_MMA(1, 1, At, B1); PG8_BAR; PG8_SCHED;
;             PG8_LDB(B0, 1, 0); PG8_LDB(B1, 1, 1); PG8_SCHED; PG8_LDA(At, 1, 0); PG8_STAGE(PG8_SA(0, 1), a2 + hstepA, voffA);
;             PG8_WAIT_V(8); PG8_WAIT_L(0); PG8_BAR; PG8_MMA(0, 0, At, B0); PG8_MMA(0, 1, At, B1); PG8_BAR; PG8_SCHED;
	v_mfma_f32_16x16x32_bf16 v[54:57], v[102:105], v[162:165], 0
	v_mfma_f32_16x16x32_bf16 v[50:53], v[114:117], v[162:165], 0
	v_mfma_f32_16x16x32_bf16 v[38:41], v[102:105], v[170:173], 0
	v_mfma_f32_16x16x32_bf16 v[34:37], v[114:117], v[170:173], 0
	v_mfma_f32_16x16x32_bf16 v[22:25], v[102:105], v[194:197], 0
	v_mfma_f32_16x16x32_bf16 v[18:21], v[114:117], v[194:197], 0
	v_mfma_f32_16x16x32_bf16 v[6:9], v[102:105], v[208:211], 0
	v_mfma_f32_16x16x32_bf16 v[2:5], v[114:117], v[208:211], 0
	v_mfma_f32_16x16x32_bf16 v[54:57], v[106:109], v[166:169], v[54:57]
	v_mfma_f32_16x16x32_bf16 v[50:53], v[118:121], v[166:169], v[50:53]
	v_mfma_f32_16x16x32_bf16 v[38:41], v[106:109], v[174:177], v[38:41]
	v_mfma_f32_16x16x32_bf16 v[34:37], v[118:121], v[174:177], v[34:37]
	v_mfma_f32_16x16x32_bf16 v[22:25], v[106:109], v[198:201], v[22:25]
	v_mfma_f32_16x16x32_bf16 v[18:21], v[118:121], v[198:201], v[18:21]
	v_mfma_f32_16x16x32_bf16 v[6:9], v[106:109], v[212:215], v[6:9]
	v_mfma_f32_16x16x32_bf16 v[2:5], v[118:121], v[212:215], v[2:5]
	s_setprio 0
	s_add_i32 s36, 0, 0x18000
	s_add_i32 s37, 0, 0x1c000
	v_add_u32_e32 v94, s36, v202
	v_add_u32_e32 v118, s37, v202
	ds_read_b128 v[82:85], v94
	ds_read_b128 v[86:89], v94 offset:1024
	ds_read_b128 v[90:93], v94 offset:2048
	ds_read_b128 v[94:97], v94 offset:3072
	ds_read_b128 v[102:105], v118
	ds_read_b128 v[106:109], v118 offset:1024
	ds_read_b128 v[114:117], v118 offset:2048
	ds_read_b128 v[118:121], v118 offset:3072
	s_add_u32 s24, s66, 0x80000
	s_addc_u32 s25, s67, 0
	s_mov_b32 m0, s26
	ds_read_b128 v[162:165], v206 offset:32768
	ds_read_b128 v[166:169], v206 offset:33792
	ds_read_b128 v[170:173], v206 offset:34816
	ds_read_b128 v[174:177], v206 offset:35840
	ds_read_b128 v[194:197], v206 offset:36864
	ds_read_b128 v[198:201], v206 offset:37888
	ds_read_b128 v[208:211], v206 offset:38912
	ds_read_b128 v[212:215], v206 offset:39936
	global_load_lds_dwordx4 v178, s[24:25]
	s_mov_b32 m0, s27
	s_nop 0
	global_load_lds_dwordx4 v182, s[24:25]
	s_waitcnt vmcnt(8)
	s_waitcnt lgkmcnt(0)
	s_barrier
	s_setprio 3
	s_waitcnt lgkmcnt(0)
	v_mfma_f32_16x16x32_bf16 v[158:161], v[82:85], v[162:165], v[158:161]
	v_mfma_f32_16x16x32_bf16 v[154:157], v[90:93], v[162:165], v[154:157]
	v_mfma_f32_16x16x32_bf16 v[142:145], v[82:85], v[170:173], v[142:145]
	v_mfma_f32_16x16x32_bf16 v[138:141], v[90:93], v[170:173], v[138:141]
	v_mfma_f32_16x16x32_bf16 v[126:129], v[82:85], v[194:197], v[126:129]
	v_mfma_f32_16x16x32_bf16 v[122:125], v[90:93], v[194:197], v[122:125]
	v_mfma_f32_16x16x32_bf16 v[78:81], v[82:85], v[208:211], v[78:81]
	v_mfma_f32_16x16x32_bf16 v[74:77], v[90:93], v[208:211], v[74:77]
	v_mfma_f32_16x16x32_bf16 v[158:161], v[86:89], v[166:169], v[158:161]
	v_mfma_f32_16x16x32_bf16 v[154:157], v[94:97], v[166:169], v[154:157]
	v_mfma_f32_16x16x32_bf16 v[142:145], v[86:89], v[174:177], v[142:145]
	v_mfma_f32_16x16x32_bf16 v[138:141], v[94:97], v[174:177], v[138:141]
	v_mfma_f32_16x16x32_bf16 v[126:129], v[86:89], v[198:201], v[126:129]
	v_mfma_f32_16x16x32_bf16 v[122:125], v[94:97], v[198:201], v[122:125]
	v_mfma_f32_16x16x32_bf16 v[78:81], v[86:89], v[212:215], v[78:81]
	v_mfma_f32_16x16x32_bf16 v[74:77], v[94:97], v[212:215], v[74:77]


; #define PG8_STAGE(bufoff, gbase, voff) do { _Pragma("unroll") for (int _i = 0; _i < 2; ++_i) \
;         __builtin_amdgcn_global_load_lds((const unsigned*)((const char*)(gbase) + (voff)[_i]), (PG8_LAS unsigned*)(lds + (bufoff) + ldsw + _i * 8192), 16, 0, 0); } while (0)
; #define PG8_LDA(dst, b, h) do { _Pragma("unroll") for (int m = 0; m < 4; ++m) _Pragma("unroll") for (int k = 0; k < 2; ++k) dst[m][k] = *(const PG8_LAS bf16x8*)(lds + PG8_SA(b, h) + aoff + m * 2048 + k * 1024); } while (0)
; #define PG8_WAIT_V(n) asm volatile("s_waitcnt vmcnt(" #n ")" ::: "memory")
; #define PG8_WAIT_L(n) asm volatile("s_waitcnt lgkmcnt(" #n ")" ::: "memory")
; #define PG8_BAR __builtin_amdgcn_s_barrier()
; #define PG8_SCHED __builtin_amdgcn_sched_barrier(0)
; template <class Epi, class Sched, bool ALIGN_EPI = false, bool SP2 = false, bool F8 = false>
; __device__ __forceinline__ void gemm_phase(PG8_LAS unsigned char* lds, const Gemm g, const Sched& S, const Epi& E) {
;     ...
;             PG8_WAIT_V(8); PG8_WAIT_L(0); PG8_BAR; PG8_MMA(0, 0, At, B0); PG8_MMA(0, 1, At, B1); PG8_BAR; PG8_SCHED;
;             PG8_LDA(At, 1, 1); PG8_STAGE(PG8_SB(1, 0), b3, voffB); PG8_STAGE(PG8_SB(1, 1), b3 + hstep, voffB); PG8_STAGE(PG8_SA(1, 0), a3, voffA);
;             PG8_WAIT_V(8); PG8_WAIT_L(0); PG8_BAR; PG8_MMA(1, 0, At, B0); PG8_MMA(1, 1, At, B1); PG8_BAR; PG8_SCHED;
	v_mfma_f32_16x16x32_bf16 v[150:153], v[102:105], v[162:165], v[150:153]
	v_mfma_f32_16x16x32_bf16 v[146:149], v[114:117], v[162:165], v[146:149]
	v_mfma_f32_16x16x32_bf16 v[134:137], v[102:105], v[170:173], v[134:137]
	v_mfma_f32_16x16x32_bf16 v[130:133], v[114:117], v[170:173], v[130:133]
	v_mfma_f32_16x16x32_bf16 v[110:113], v[102:105], v[194:197], v[110:113]
	v_mfma_f32_16x16x32_bf16 v[98:101], v[114:117], v[194:197], v[98:101]
	v_mfma_f32_16x16x32_bf16 v[70:73], v[102:105], v[208:211], v[70:73]
	v_mfma_f32_16x16x32_bf16 v[66:69], v[114:117], v[208:211], v[66:69]
	v_mfma_f32_16x16x32_bf16 v[150:153], v[106:109], v[166:169], v[150:153]
	v_mfma_f32_16x16x32_bf16 v[146:149], v[118:121], v[166:169], v[146:149]
	v_mfma_f32_16x16x32_bf16 v[134:137], v[106:109], v[174:177], v[134:137]
	v_mfma_f32_16x16x32_bf16 v[130:133], v[118:121], v[174:177], v[130:133]
	v_mfma_f32_16x16x32_bf16 v[110:113], v[106:109], v[198:201], v[110:113]
	v_mfma_f32_16x16x32_bf16 v[98:101], v[118:121], v[198:201], v[98:101]
	v_mfma_f32_16x16x32_bf16 v[70:73], v[106:109], v[212:215], v[70:73]
	v_mfma_f32_16x16x32_bf16 v[66:69], v[118:121], v[212:215], v[66:69]
	s_setprio 0
	s_add_i32 s24, s36, s14
	s_mov_b32 m0, s24
	ds_read_b128 v[162:165], v206 offset:49152
	ds_read_b128 v[166:169], v206 offset:50176
	ds_read_b128 v[170:173], v206 offset:51200
	ds_read_b128 v[174:177], v206 offset:52224
	ds_read_b128 v[194:197], v206 offset:53248
	ds_read_b128 v[198:201], v206 offset:54272
	ds_read_b128 v[208:211], v206 offset:55296
	ds_read_b128 v[212:215], v206 offset:56320
	s_add_u32 s98, s64, 0x80
	s_addc_u32 s99, s65, 0
	global_load_lds_dwordx4 v180, s[98:99]
	s_add_i32 m0, s24, 0x2000
	s_add_u32 s24, s64, 0x80080
	s_addc_u32 s25, s65, 0
	s_add_i32 s36, s37, s14
	s_add_u32 s100, s64, 0x80
	s_addc_u32 s101, s65, 0
	global_load_lds_dwordx4 v184, s[100:101]
	s_mov_b32 m0, s36
	s_nop 0
	global_load_lds_dwordx4 v180, s[24:25]
	s_add_i32 m0, s36, 0x2000
	s_nop 0
	global_load_lds_dwordx4 v184, s[24:25]
	s_mov_b32 m0, s44
	s_nop 0
	s_add_u32 s98, s66, 0x80
	s_addc_u32 s99, s67, 0
	global_load_lds_dwordx4 v178, s[98:99]
	s_mov_b32 m0, s45
	s_nop 0
	s_add_u32 s100, s66, 0x80
	s_addc_u32 s101, s67, 0
	global_load_lds_dwordx4 v182, s[100:101]
	s_waitcnt vmcnt(8)
	s_waitcnt lgkmcnt(0)
	s_barrier
	s_setprio 3
	s_waitcnt lgkmcnt(0)
	v_mfma_f32_16x16x32_bf16 v[62:65], v[82:85], v[162:165], v[62:65]
	v_mfma_f32_16x16x32_bf16 v[58:61], v[90:93], v[162:165], v[58:61]
	v_mfma_f32_16x16x32_bf16 v[46:49], v[82:85], v[170:173], v[46:49]
	v_mfma_f32_16x16x32_bf16 v[42:45], v[90:93], v[170:173], v[42:45]
	v_mfma_f32_16x16x32_bf16 v[30:33], v[82:85], v[194:197], v[30:33]
	v_mfma_f32_16x16x32_bf16 v[26:29], v[90:93], v[194:197], v[26:29]
	v_mfma_f32_16x16x32_bf16 v[14:17], v[82:85], v[208:211], v[14:17]
	v_mfma_f32_16x16x32_bf16 v[10:13], v[90:93], v[208:211], v[10:13]
	v_mfma_f32_16x16x32_bf16 v[62:65], v[86:89], v[166:169], v[62:65]
	v_mfma_f32_16x16x32_bf16 v[58:61], v[94:97], v[166:169], v[58:61]
	v_mfma_f32_16x16x32_bf16 v[46:49], v[86:89], v[174:177], v[46:49]
	v_mfma_f32_16x16x32_bf16 v[42:45], v[94:97], v[174:177], v[42:45]
	v_mfma_f32_16x16x32_bf16 v[30:33], v[86:89], v[198:201], v[30:33]
	v_mfma_f32_16x16x32_bf16 v[26:29], v[94:97], v[198:201], v[26:29]
	v_mfma_f32_16x16x32_bf16 v[14:17], v[86:89], v[212:215], v[14:17]
	v_mfma_f32_16x16x32_bf16 v[10:13], v[94:97], v[212:215], v[10:13]


; #define PG8_WAIT_V(n) asm volatile("s_waitcnt vmcnt(" #n ")" ::: "memory")
; #define PG8_WAIT_L(n) asm volatile("s_waitcnt lgkmcnt(" #n ")" ::: "memory")
; #define PG8_BAR __builtin_amdgcn_s_barrier()
; #define PG8_SCHED __builtin_amdgcn_sched_barrier(0)
; template <class Epi, class Sched, bool ALIGN_EPI = false, bool SP2 = false, bool F8 = false>
; __device__ __forceinline__ void gemm_phase(PG8_LAS unsigned char* lds, const Gemm g, const Sched& S, const Epi& E) {
;     ...
;         for (int t = 0; t < nt; t += 2) {
;             const bool last = (t == nt - 2);
;             const char* a1 = cA + (size_t)(t + 1) * kstep;
;             const char* a2 = last ? nA : cA + (size_t)(t + 2) * kstep; const char* b2 = last ? nB : cB + (size_t)(t + 2) * kstep;
;     ...
;             PG8_WAIT_V(8); PG8_WAIT_L(0); PG8_BAR; PG8_MMA(1, 0, At, B0); PG8_MMA(1, 1, At, B1); PG8_BAR; PG8_SCHED;
	v_mfma_f32_16x16x32_bf16 v[54:57], v[102:105], v[162:165], v[54:57]
	v_mfma_f32_16x16x32_bf16 v[50:53], v[114:117], v[162:165], v[50:53]
	v_mfma_f32_16x16x32_bf16 v[38:41], v[102:105], v[170:173], v[38:41]
	v_mfma_f32_16x16x32_bf16 v[34:37], v[114:117], v[170:173], v[34:37]
	v_mfma_f32_16x16x32_bf16 v[22:25], v[102:105], v[194:197], v[22:25]
	v_mfma_f32_16x16x32_bf16 v[18:21], v[114:117], v[194:197], v[18:21]
	v_mfma_f32_16x16x32_bf16 v[6:9], v[102:105], v[208:211], v[6:9]
	v_mfma_f32_16x16x32_bf16 v[2:5], v[114:117], v[208:211], v[2:5]
	v_mfma_f32_16x16x32_bf16 v[54:57], v[106:109], v[166:169], v[54:57]
	v_mfma_f32_16x16x32_bf16 v[50:53], v[118:121], v[166:169], v[50:53]
	v_mfma_f32_16x16x32_bf16 v[38:41], v[106:109], v[174:177], v[38:41]
	v_mfma_f32_16x16x32_bf16 v[34:37], v[118:121], v[174:177], v[34:37]
	v_mfma_f32_16x16x32_bf16 v[22:25], v[106:109], v[198:201], v[22:25]
	v_mfma_f32_16x16x32_bf16 v[18:21], v[118:121], v[198:201], v[18:21]
	v_mfma_f32_16x16x32_bf16 v[6:9], v[106:109], v[212:215], v[6:9]
	v_mfma_f32_16x16x32_bf16 v[2:5], v[118:121], v[212:215], v[2:5]
	s_setprio 0
	s_add_i32 s76, s76, 2
	s_add_u32 s62, s62, 0x100
	s_addc_u32 s63, s63, 0
	s_add_u32 s74, s74, 0x100
	s_addc_u32 s75, s75, 0
	s_cmp_gt_u32 s76, 29
	s_branch .Lk2_Y

;     __host__ __device__ bool next(int i, Unit& u) const { const long L = (long)i * G + c; if (L >= nwg) return false; u.pm = 0; u.pn = c % nN; return true; }
; template <class Epi, class Sched, bool ALIGN_EPI = false, bool SP2 = false, bool F8 = false>
; __device__ __forceinline__ void gemm_phase(PG8_LAS unsigned char* lds, const Gemm g, const Sched& S, const Epi& E) {
;     ...
;         const bool has_next = S.next(ui + 1, nxt);
;         const char* nA = has_next ? PG8_ABASE(nxt.pm) : cA; const char* nB = has_next ? (const char*)g.Bt + (size_t)nxt.pn * tstep : cB;
;         for (int t = 0; t < nt; t += 2) {
;             const bool last = (t == nt - 2);
;             const char* a1 = cA + (size_t)(t + 1) * kstep;
;             const char* a2 = last ? nA : cA + (size_t)(t + 2) * kstep; const char* b2 = last ? nB : cB + (size_t)(t + 2) * kstep;
;     ...
; #pragma unroll
;         for (int a = 0; a < 2; ++a)
; #pragma unroll
;             for (int b = 0; b < 2; ++b)
; #pragma unroll
;                 for (int m = 0; m < 4; ++m)
; #pragma unroll
;                     for (int n = 0; n < 2; ++n) acc[a][b][m][n] = (f32x4){0.f, 0.f, 0.f, 0.f};
.LBB0_999:
	s_add_u32 s52, s52, 0xb0080
	s_addc_u32 s53, s53, 0
	s_add_u32 s65, s54, 0x100
	s_waitcnt vmcnt(0)
	s_addc_u32 s66, s55, 0
	s_mov_b32 s67, -2
	s_cmp_lg_u64 s[10:11], 0
	s_cbranch_scc1 .Lk4_Yz
	s_branch .Lk4_Xz

; #define PG8_STAGE(bufoff, gbase, voff) do { _Pragma("unroll") for (int _i = 0; _i < 2; ++_i) \
;         __builtin_amdgcn_global_load_lds((const unsigned*)((const char*)(gbase) + (voff)[_i]), (PG8_LAS unsigned*)(lds + (bufoff) + ldsw + _i * 8192), 16, 0, 0); } while (0)
; #define PG8_LDA(dst, b, h) do { _Pragma("unroll") for (int m = 0; m < 4; ++m) _Pragma("unroll") for (int k = 0; k < 2; ++k) dst[m][k] = *(const PG8_LAS bf16x8*)(lds + PG8_SA(b, h) + aoff + m * 2048 + k * 1024); } while (0)
; #define PG8_LDB(dst, b, h) do { _Pragma("unroll") for (int n = 0; n < 2; ++n) _Pragma("unroll") for (int k = 0; k < 2; ++k) dst[n][k] = *(const PG8_LAS bf16x8*)(lds + PG8_SB(b, h) + boff + n * 2048 + k * 1024); } while (0)
; #define PG8_WAIT_V(n) asm volatile("s_waitcnt vmcnt(" #n ")" ::: "memory")
; #define PG8_WAIT_L(n) asm volatile("s_waitcnt lgkmcnt(" #n ")" ::: "memory")
; #define PG8_BAR __builtin_amdgcn_s_barrier()
; #define PG8_SCHED __builtin_amdgcn_sched_barrier(0)
; template <class Epi, class Sched, bool ALIGN_EPI = false, bool SP2 = false, bool F8 = false>
; __device__ __forceinline__ void gemm_phase(PG8_LAS unsigned char* lds, const Gemm g, const Sched& S, const Epi& E) {
;     ...
;             PG8_LDB(B0, 0, 0); PG8_LDB(B1, 0, 1); PG8_SCHED; PG8_LDA(At, 0, 0); PG8_STAGE(PG8_SA(1, 1), a1 + hstepA, voffA);
;             PG8_WAIT_V(8); PG8_WAIT_L(0); PG8_BAR; PG8_MMA(0, 0, At, B0); PG8_MMA(0, 1, At, B1); PG8_BAR; PG8_SCHED;
.Lk4_Y:
	ds_read_b128 v[24:27], v197
	ds_read_b128 v[28:31], v197 offset:1024
	ds_read_b128 v[16:19], v197 offset:2048
	ds_read_b128 v[20:23], v197 offset:3072
	ds_read_b128 v[8:11], v198
	ds_read_b128 v[12:15], v198 offset:1024
	ds_read_b128 v[0:3], v198 offset:2048
	ds_read_b128 v[4:7], v198 offset:3072
	s_add_u32 s24, s52, 0xfff50080
	s_addc_u32 s25, s53, -1
	s_cmp_eq_u32 s67, 40
	s_cselect_b32 s57, s7, s25
	s_cselect_b32 s56, s6, s24
	s_cselect_b32 s55, s51, s66
	s_cselect_b32 s54, s50, s65
	s_add_i32 m0, s15, 0xc000
	ds_read_b128 v[176:179], v199
	ds_read_b128 v[180:183], v199 offset:1024
	ds_read_b128 v[184:187], v199 offset:2048
	ds_read_b128 v[188:191], v199 offset:3072
	ds_read_b128 v[200:203], v199 offset:4096
	ds_read_b128 v[204:207], v199 offset:5120
	ds_read_b128 v[208:211], v199 offset:6144
	ds_read_b128 v[212:215], v199 offset:7168
	global_load_lds_dwordx4 v168, s[52:53]
	s_add_i32 m0, s15, 0xe000
	s_nop 0
	global_load_lds_dwordx4 v170, s[52:53]
	s_waitcnt vmcnt(8)
	s_waitcnt lgkmcnt(0)
	s_barrier
	s_setprio 3
	s_waitcnt lgkmcnt(0)
	v_mfma_f32_16x16x128_f8f6f4 v[156:159], v[24:31], v[176:183], v[156:159]
	v_mfma_f32_16x16x128_f8f6f4 v[152:155], v[16:23], v[176:183], v[152:155]
	v_mfma_f32_16x16x128_f8f6f4 v[140:143], v[24:31], v[184:191], v[140:143]
	v_mfma_f32_16x16x128_f8f6f4 v[136:139], v[16:23], v[184:191], v[136:139]
	v_mfma_f32_16x16x128_f8f6f4 v[124:127], v[24:31], v[200:207], v[124:127]
	v_mfma_f32_16x16x128_f8f6f4 v[120:123], v[16:23], v[200:207], v[120:123]
	v_mfma_f32_16x16x128_f8f6f4 v[108:111], v[24:31], v[208:215], v[108:111]
	v_mfma_f32_16x16x128_f8f6f4 v[104:107], v[16:23], v[208:215], v[104:107]


; #define PG8_STAGE(bufoff, gbase, voff) do { _Pragma("unroll") for (int _i = 0; _i < 2; ++_i) \
;         __builtin_amdgcn_global_load_lds((const unsigned*)((const char*)(gbase) + (voff)[_i]), (PG8_LAS unsigned*)(lds + (bufoff) + ldsw + _i * 8192), 16, 0, 0); } while (0)
; #define PG8_LDA(dst, b, h) do { _Pragma("unroll") for (int m = 0; m < 4; ++m) _Pragma("unroll") for (int k = 0; k < 2; ++k) dst[m][k] = *(const PG8_LAS bf16x8*)(lds + PG8_SA(b, h) + aoff + m * 2048 + k * 1024); } while (0)
; #define PG8_WAIT_V(n) asm volatile("s_waitcnt vmcnt(" #n ")" ::: "memory")
; #define PG8_WAIT_L(n) asm volatile("s_waitcnt lgkmcnt(" #n ")" ::: "memory")
; #define PG8_BAR __builtin_amdgcn_s_barrier()
; #define PG8_SCHED __builtin_amdgcn_sched_barrier(0)
; template <class Epi, class Sched, bool ALIGN_EPI = false, bool SP2 = false, bool F8 = false>
; __device__ __forceinline__ void gemm_phase(PG8_LAS unsigned char* lds, const Gemm g, const Sched& S, const Epi& E) {
;     ...
;             PG8_WAIT_V(8); PG8_WAIT_L(0); PG8_BAR; PG8_MMA(0, 0, At, B0); PG8_MMA(0, 1, At, B1); PG8_BAR; PG8_SCHED;
;             PG8_LDA(At, 0, 1); PG8_STAGE(PG8_SB(0, 0), b2, voffB); PG8_STAGE(PG8_SB(0, 1), b2 + hstep, voffB); PG8_STAGE(PG8_SA(0, 0), a2, voffA);
;             PG8_WAIT_V(8); PG8_WAIT_L(0); PG8_BAR; PG8_MMA(1, 0, At, B0); PG8_MMA(1, 1, At, B1); PG8_BAR; PG8_SCHED;
	v_mfma_f32_16x16x128_f8f6f4 v[148:151], v[8:15], v[176:183], v[148:151]
	v_mfma_f32_16x16x128_f8f6f4 v[144:147], v[0:7], v[176:183], v[144:147]
	v_mfma_f32_16x16x128_f8f6f4 v[132:135], v[8:15], v[184:191], v[132:135]
	v_mfma_f32_16x16x128_f8f6f4 v[128:131], v[0:7], v[184:191], v[128:131]
	v_mfma_f32_16x16x128_f8f6f4 v[116:119], v[8:15], v[200:207], v[116:119]
	v_mfma_f32_16x16x128_f8f6f4 v[112:115], v[0:7], v[200:207], v[112:115]
	v_mfma_f32_16x16x128_f8f6f4 v[100:103], v[8:15], v[208:215], v[100:103]
	v_mfma_f32_16x16x128_f8f6f4 v[96:99], v[0:7], v[208:215], v[96:99]
	s_setprio 0
	s_add_i32 s24, s59, s14
	s_mov_b32 m0, s24
	ds_read_b128 v[184:187], v199 offset:16384
	ds_read_b128 v[188:191], v199 offset:17408
	ds_read_b128 v[200:203], v199 offset:18432
	ds_read_b128 v[204:207], v199 offset:19456
	ds_read_b128 v[208:211], v199 offset:20480
	ds_read_b128 v[212:215], v199 offset:21504
	ds_read_b128 v[218:221], v199 offset:22528
	ds_read_b128 v[222:225], v199 offset:23552
	global_load_lds_dwordx4 v162, s[54:55]
	s_add_i32 m0, s24, 0x2000
	s_add_u32 s24, s54, 0xb0000
	s_addc_u32 s25, s55, 0
	s_add_i32 s36, s60, s14
	global_load_lds_dwordx4 v166, s[54:55]
	s_mov_b32 m0, s36
	s_nop 0
	global_load_lds_dwordx4 v162, s[24:25]
	s_add_i32 m0, s36, 0x2000
	s_nop 0
	global_load_lds_dwordx4 v166, s[24:25]
	s_mov_b32 m0, s15
	s_nop 0
	global_load_lds_dwordx4 v160, s[56:57]
	s_mov_b32 m0, s21
	s_nop 0
	global_load_lds_dwordx4 v164, s[56:57]
	s_waitcnt vmcnt(8)
	s_waitcnt lgkmcnt(0)
	s_barrier
	s_setprio 3
	s_waitcnt lgkmcnt(0)
	v_mfma_f32_16x16x128_f8f6f4 v[92:95], v[24:31], v[184:191], v[92:95]
	v_mfma_f32_16x16x128_f8f6f4 v[88:91], v[16:23], v[184:191], v[88:91]
	v_mfma_f32_16x16x128_f8f6f4 v[76:79], v[24:31], v[200:207], v[76:79]
	v_mfma_f32_16x16x128_f8f6f4 v[72:75], v[16:23], v[200:207], v[72:75]
	v_mfma_f32_16x16x128_f8f6f4 v[60:63], v[24:31], v[208:215], v[60:63]
	v_mfma_f32_16x16x128_f8f6f4 v[56:59], v[16:23], v[208:215], v[56:59]
	v_mfma_f32_16x16x128_f8f6f4 v[44:47], v[24:31], v[218:225], v[44:47]
	v_mfma_f32_16x16x128_f8f6f4 v[40:43], v[16:23], v[218:225], v[40:43]


; #define PG8_STAGE(bufoff, gbase, voff) do { _Pragma("unroll") for (int _i = 0; _i < 2; ++_i) \
;         __builtin_amdgcn_global_load_lds((const unsigned*)((const char*)(gbase) + (voff)[_i]), (PG8_LAS unsigned*)(lds + (bufoff) + ldsw + _i * 8192), 16, 0, 0); } while (0)
; #define PG8_LDA(dst, b, h) do { _Pragma("unroll") for (int m = 0; m < 4; ++m) _Pragma("unroll") for (int k = 0; k < 2; ++k) dst[m][k] = *(const PG8_LAS bf16x8*)(lds + PG8_SA(b, h) + aoff + m * 2048 + k * 1024); } while (0)
; #define PG8_LDB(dst, b, h) do { _Pragma("unroll") for (int n = 0; n < 2; ++n) _Pragma("unroll") for (int k = 0; k < 2; ++k) dst[n][k] = *(const PG8_LAS bf16x8*)(lds + PG8_SB(b, h) + boff + n * 2048 + k * 1024); } while (0)
; #define PG8_WAIT_V(n) asm volatile("s_waitcnt vmcnt(" #n ")" ::: "memory")
; #define PG8_WAIT_L(n) asm volatile("s_waitcnt lgkmcnt(" #n ")" ::: "memory")
; #define PG8_BAR __builtin_amdgcn_s_barrier()
; #define PG8_SCHED __builtin_amdgcn_sched_barrier(0)
; template <class Epi, class Sched, bool ALIGN_EPI = false, bool SP2 = false, bool F8 = false>
; __device__ __forceinline__ void gemm_phase(PG8_LAS unsigned char* lds, const Gemm g, const Sched& S, const Epi& E) {
;     ...
;             PG8_WAIT_V(8); PG8_WAIT_L(0); PG8_BAR; PG8_MMA(1, 0, At, B0); PG8_MMA(1, 1, At, B1); PG8_BAR; PG8_SCHED;
;             PG8_LDB(B0, 1, 0); PG8_LDB(B1, 1, 1); PG8_SCHED; PG8_LDA(At, 1, 0); PG8_STAGE(PG8_SA(0, 1), a2 + hstepA, voffA);
;             PG8_WAIT_V(8); PG8_WAIT_L(0); PG8_BAR; PG8_MMA(0, 0, At, B0); PG8_MMA(0, 1, At, B1); PG8_BAR; PG8_SCHED;
	v_mfma_f32_16x16x128_f8f6f4 v[84:87], v[8:15], v[184:191], v[84:87]
	v_mfma_f32_16x16x128_f8f6f4 v[80:83], v[0:7], v[184:191], v[80:83]
	v_mfma_f32_16x16x128_f8f6f4 v[68:71], v[8:15], v[200:207], v[68:71]
	v_mfma_f32_16x16x128_f8f6f4 v[64:67], v[0:7], v[200:207], v[64:67]
	v_mfma_f32_16x16x128_f8f6f4 v[52:55], v[8:15], v[208:215], v[52:55]
	v_mfma_f32_16x16x128_f8f6f4 v[48:51], v[0:7], v[208:215], v[48:51]
	v_mfma_f32_16x16x128_f8f6f4 v[36:39], v[8:15], v[218:225], v[36:39]
	v_mfma_f32_16x16x128_f8f6f4 v[32:35], v[0:7], v[218:225], v[32:35]
	s_setprio 0
	s_add_i32 s36, 0, 0x18000
	s_add_i32 s37, 0, 0x1c000
	v_add_u32_e32 v12, s36, v195
	v_add_u32_e32 v28, s37, v195
	ds_read_b128 v[0:3], v12
	ds_read_b128 v[4:7], v12 offset:1024
	ds_read_b128 v[8:11], v12 offset:2048
	ds_read_b128 v[12:15], v12 offset:3072
	ds_read_b128 v[16:19], v28
	ds_read_b128 v[20:23], v28 offset:1024
	ds_read_b128 v[24:27], v28 offset:2048
	ds_read_b128 v[28:31], v28 offset:3072
	s_add_u32 s24, s56, 0xb0000
	s_addc_u32 s25, s57, 0
	s_mov_b32 m0, s23
	ds_read_b128 v[184:187], v199 offset:32768
	ds_read_b128 v[188:191], v199 offset:33792
	ds_read_b128 v[200:203], v199 offset:34816
	ds_read_b128 v[204:207], v199 offset:35840
	ds_read_b128 v[208:211], v199 offset:36864
	ds_read_b128 v[212:215], v199 offset:37888
	ds_read_b128 v[218:221], v199 offset:38912
	ds_read_b128 v[222:225], v199 offset:39936
	global_load_lds_dwordx4 v160, s[24:25]
	s_mov_b32 m0, s26
	s_nop 0
	global_load_lds_dwordx4 v164, s[24:25]
	s_waitcnt vmcnt(8)
	s_waitcnt lgkmcnt(0)
	s_barrier
	s_setprio 3
	s_waitcnt lgkmcnt(0)
	v_mfma_f32_16x16x128_f8f6f4 v[156:159], v[0:7], v[184:191], v[156:159]
	v_mfma_f32_16x16x128_f8f6f4 v[152:155], v[8:15], v[184:191], v[152:155]
	v_mfma_f32_16x16x128_f8f6f4 v[140:143], v[0:7], v[200:207], v[140:143]
	v_mfma_f32_16x16x128_f8f6f4 v[136:139], v[8:15], v[200:207], v[136:139]
	v_mfma_f32_16x16x128_f8f6f4 v[124:127], v[0:7], v[208:215], v[124:127]
	v_mfma_f32_16x16x128_f8f6f4 v[120:123], v[8:15], v[208:215], v[120:123]
	v_mfma_f32_16x16x128_f8f6f4 v[108:111], v[0:7], v[218:225], v[108:111]
	v_mfma_f32_16x16x128_f8f6f4 v[104:107], v[8:15], v[218:225], v[104:107]


; #define PG8_STAGE(bufoff, gbase, voff) do { _Pragma("unroll") for (int _i = 0; _i < 2; ++_i) \
;         __builtin_amdgcn_global_load_lds((const unsigned*)((const char*)(gbase) + (voff)[_i]), (PG8_LAS unsigned*)(lds + (bufoff) + ldsw + _i * 8192), 16, 0, 0); } while (0)
; #define PG8_LDA(dst, b, h) do { _Pragma("unroll") for (int m = 0; m < 4; ++m) _Pragma("unroll") for (int k = 0; k < 2; ++k) dst[m][k] = *(const PG8_LAS bf16x8*)(lds + PG8_SA(b, h) + aoff + m * 2048 + k * 1024); } while (0)
; #define PG8_WAIT_V(n) asm volatile("s_waitcnt vmcnt(" #n ")" ::: "memory")
; #define PG8_WAIT_L(n) asm volatile("s_waitcnt lgkmcnt(" #n ")" ::: "memory")
; #define PG8_BAR __builtin_amdgcn_s_barrier()
; #define PG8_SCHED __builtin_amdgcn_sched_barrier(0)
; template <class Epi, class Sched, bool ALIGN_EPI = false, bool SP2 = false, bool F8 = false>
; __device__ __forceinline__ void gemm_phase(PG8_LAS unsigned char* lds, const Gemm g, const Sched& S, const Epi& E) {
;     ...
;             PG8_WAIT_V(8); PG8_WAIT_L(0); PG8_BAR; PG8_MMA(0, 0, At, B0); PG8_MMA(0, 1, At, B1); PG8_BAR; PG8_SCHED;
;             PG8_LDA(At, 1, 1); PG8_STAGE(PG8_SB(1, 0), b3, voffB); PG8_STAGE(PG8_SB(1, 1), b3 + hstep, voffB); PG8_STAGE(PG8_SA(1, 0), a3, voffA);
;             PG8_WAIT_V(8); PG8_WAIT_L(0); PG8_BAR; PG8_MMA(1, 0, At, B0); PG8_MMA(1, 1, At, B1); PG8_BAR; PG8_SCHED;
	v_mfma_f32_16x16x128_f8f6f4 v[148:151], v[16:23], v[184:191], v[148:151]
	v_mfma_f32_16x16x128_f8f6f4 v[144:147], v[24:31], v[184:191], v[144:147]
	v_mfma_f32_16x16x128_f8f6f4 v[132:135], v[16:23], v[200:207], v[132:135]
	v_mfma_f32_16x16x128_f8f6f4 v[128:131], v[24:31], v[200:207], v[128:131]
	v_mfma_f32_16x16x128_f8f6f4 v[116:119], v[16:23], v[208:215], v[116:119]
	v_mfma_f32_16x16x128_f8f6f4 v[112:115], v[24:31], v[208:215], v[112:115]
	v_mfma_f32_16x16x128_f8f6f4 v[100:103], v[16:23], v[218:225], v[100:103]
	v_mfma_f32_16x16x128_f8f6f4 v[96:99], v[24:31], v[218:225], v[96:99]
	s_setprio 0
	s_add_i32 s24, s36, s14
	s_mov_b32 m0, s24
	ds_read_b128 v[184:187], v199 offset:49152
	ds_read_b128 v[188:191], v199 offset:50176
	ds_read_b128 v[200:203], v199 offset:51200
	ds_read_b128 v[204:207], v199 offset:52224
	ds_read_b128 v[208:211], v199 offset:53248
	ds_read_b128 v[212:215], v199 offset:54272
	ds_read_b128 v[218:221], v199 offset:55296
	ds_read_b128 v[222:225], v199 offset:56320
	s_add_u32 s98, s54, 0x80
	s_addc_u32 s99, s55, 0
	global_load_lds_dwordx4 v162, s[98:99]
	s_add_i32 m0, s24, 0x2000
	s_add_u32 s24, s54, 0xb0080
	s_addc_u32 s25, s55, 0
	s_add_i32 s36, s37, s14
	s_add_u32 s100, s54, 0x80
	s_addc_u32 s101, s55, 0
	global_load_lds_dwordx4 v166, s[100:101]
	s_mov_b32 m0, s36
	s_nop 0
	global_load_lds_dwordx4 v162, s[24:25]
	s_add_i32 m0, s36, 0x2000
	s_nop 0
	global_load_lds_dwordx4 v166, s[24:25]
	s_mov_b32 m0, s33
	s_nop 0
	s_add_u32 s98, s56, 0x80
	s_addc_u32 s99, s57, 0
	global_load_lds_dwordx4 v160, s[98:99]
	s_mov_b32 m0, s43
	s_nop 0
	s_add_u32 s100, s56, 0x80
	s_addc_u32 s101, s57, 0
	global_load_lds_dwordx4 v164, s[100:101]
	s_waitcnt vmcnt(8)
	s_waitcnt lgkmcnt(0)
	s_barrier
	s_setprio 3
	s_waitcnt lgkmcnt(0)
	v_mfma_f32_16x16x128_f8f6f4 v[92:95], v[0:7], v[184:191], v[92:95]
	v_mfma_f32_16x16x128_f8f6f4 v[88:91], v[8:15], v[184:191], v[88:91]
	v_mfma_f32_16x16x128_f8f6f4 v[76:79], v[0:7], v[200:207], v[76:79]
	v_mfma_f32_16x16x128_f8f6f4 v[72:75], v[8:15], v[200:207], v[72:75]
	v_mfma_f32_16x16x128_f8f6f4 v[60:63], v[0:7], v[208:215], v[60:63]
	v_mfma_f32_16x16x128_f8f6f4 v[56:59], v[8:15], v[208:215], v[56:59]
	v_mfma_f32_16x16x128_f8f6f4 v[44:47], v[0:7], v[218:225], v[44:47]
	v_mfma_f32_16x16x128_f8f6f4 v[40:43], v[8:15], v[218:225], v[40:43]


; #define PG8_STAGE(bufoff, gbase, voff) do { _Pragma("unroll") for (int _i = 0; _i < 2; ++_i) \
;         __builtin_amdgcn_global_load_lds((const unsigned*)((const char*)(gbase) + (voff)[_i]), (PG8_LAS unsigned*)(lds + (bufoff) + ldsw + _i * 8192), 16, 0, 0); } while (0)
; #define PG8_LDA(dst, b, h) do { _Pragma("unroll") for (int m = 0; m < 4; ++m) _Pragma("unroll") for (int k = 0; k < 2; ++k) dst[m][k] = *(const PG8_LAS bf16x8*)(lds + PG8_SA(b, h) + aoff + m * 2048 + k * 1024); } while (0)
; #define PG8_LDB(dst, b, h) do { _Pragma("unroll") for (int n = 0; n < 2; ++n) _Pragma("unroll") for (int k = 0; k < 2; ++k) dst[n][k] = *(const PG8_LAS bf16x8*)(lds + PG8_SB(b, h) + boff + n * 2048 + k * 1024); } while (0)
; #define PG8_WAIT_V(n) asm volatile("s_waitcnt vmcnt(" #n ")" ::: "memory")
; #define PG8_WAIT_L(n) asm volatile("s_waitcnt lgkmcnt(" #n ")" ::: "memory")
; #define PG8_BAR __builtin_amdgcn_s_barrier()
; #define PG8_SCHED __builtin_amdgcn_sched_barrier(0)
; template <class Epi, class Sched, bool ALIGN_EPI = false, bool SP2 = false, bool F8 = false>
; __device__ __forceinline__ void gemm_phase(PG8_LAS unsigned char* lds, const Gemm g, const Sched& S, const Epi& E) {
;     ...
;             PG8_LDB(B0, 0, 0); PG8_LDB(B1, 0, 1); PG8_SCHED; PG8_LDA(At, 0, 0); PG8_STAGE(PG8_SA(1, 1), a1 + hstepA, voffA);
;             PG8_WAIT_V(8); PG8_WAIT_L(0); PG8_BAR; PG8_MMA(0, 0, At, B0); PG8_MMA(0, 1, At, B1); PG8_BAR; PG8_SCHED;
;             PG8_LDA(At, 0, 1); PG8_STAGE(PG8_SB(0, 0), b2, voffB); PG8_STAGE(PG8_SB(0, 1), b2 + hstep, voffB); PG8_STAGE(PG8_SA(0, 0), a2, voffA);
;             PG8_WAIT_V(8); PG8_WAIT_L(0); PG8_BAR; PG8_MMA(1, 0, At, B0); PG8_MMA(1, 1, At, B1); PG8_BAR; PG8_SCHED;
	v_mfma_f32_16x16x128_f8f6f4 v[84:87], v[16:23], v[184:191], v[84:87]
	v_mfma_f32_16x16x128_f8f6f4 v[80:83], v[24:31], v[184:191], v[80:83]
	v_mfma_f32_16x16x128_f8f6f4 v[68:71], v[16:23], v[200:207], v[68:71]
	v_mfma_f32_16x16x128_f8f6f4 v[64:67], v[24:31], v[200:207], v[64:67]
	v_mfma_f32_16x16x128_f8f6f4 v[52:55], v[16:23], v[208:215], v[52:55]
	v_mfma_f32_16x16x128_f8f6f4 v[48:51], v[24:31], v[208:215], v[48:51]
	v_mfma_f32_16x16x128_f8f6f4 v[36:39], v[16:23], v[218:225], v[36:39]
	v_mfma_f32_16x16x128_f8f6f4 v[32:35], v[24:31], v[218:225], v[32:35]
	s_setprio 0
	s_add_i32 s67, s67, 2
	s_add_u32 s52, s52, 0x100
	s_addc_u32 s53, s53, 0
	s_add_u32 s65, s65, 0x100
	s_addc_u32 s66, s66, 0
	s_cmp_gt_u32 s67, 41
	s_cbranch_scc0 .Lk4_Y
	s_branch .Lk4_exit
.Lk4_Xz:
	ds_read_b128 v[24:27], v197
	ds_read_b128 v[28:31], v197 offset:1024
	ds_read_b128 v[16:19], v197 offset:2048
	ds_read_b128 v[20:23], v197 offset:3072
	ds_read_b128 v[8:11], v198
	ds_read_b128 v[12:15], v198 offset:1024
	ds_read_b128 v[0:3], v198 offset:2048
	ds_read_b128 v[4:7], v198 offset:3072
	s_add_u32 s24, s52, 0xfff50080
	s_addc_u32 s25, s53, -1
	s_cmp_eq_u32 s67, 40
	s_cselect_b32 s57, s7, s25
	s_cselect_b32 s56, s6, s24
	s_cselect_b32 s55, s51, s66
	s_cselect_b32 s54, s50, s65
	s_add_i32 m0, s15, 0xc000
	ds_read_b128 v[176:179], v199
	ds_read_b128 v[180:183], v199 offset:1024
	ds_read_b128 v[184:187], v199 offset:2048
	ds_read_b128 v[188:191], v199 offset:3072
	ds_read_b128 v[200:203], v199 offset:4096
	ds_read_b128 v[204:207], v199 offset:5120
	ds_read_b128 v[208:211], v199 offset:6144
	ds_read_b128 v[212:215], v199 offset:7168
	global_load_lds_dwordx4 v168, s[52:53]
	s_add_i32 m0, s15, 0xe000
	s_nop 0
	global_load_lds_dwordx4 v170, s[52:53]
	s_waitcnt vmcnt(8)
	s_waitcnt lgkmcnt(0)
	s_setprio 1
	s_waitcnt lgkmcnt(0)
	v_mfma_f32_16x16x128_f8f6f4 v[156:159], v[24:31], v[176:183], 0
	v_mfma_f32_16x16x128_f8f6f4 v[152:155], v[16:23], v[176:183], 0
	v_mfma_f32_16x16x128_f8f6f4 v[140:143], v[24:31], v[184:191], 0
	v_mfma_f32_16x16x128_f8f6f4 v[136:139], v[16:23], v[184:191], 0
	v_mfma_f32_16x16x128_f8f6f4 v[124:127], v[24:31], v[200:207], 0
	v_mfma_f32_16x16x128_f8f6f4 v[120:123], v[16:23], v[200:207], 0
	v_mfma_f32_16x16x128_f8f6f4 v[108:111], v[24:31], v[208:215], 0
	v_mfma_f32_16x16x128_f8f6f4 v[104:107], v[16:23], v[208:215], 0
	s_setprio 0
	s_setprio 1
	v_mfma_f32_16x16x128_f8f6f4 v[148:151], v[8:15], v[176:183], 0
	v_mfma_f32_16x16x128_f8f6f4 v[144:147], v[0:7], v[176:183], 0
	v_mfma_f32_16x16x128_f8f6f4 v[132:135], v[8:15], v[184:191], 0
	v_mfma_f32_16x16x128_f8f6f4 v[128:131], v[0:7], v[184:191], 0
	v_mfma_f32_16x16x128_f8f6f4 v[116:119], v[8:15], v[200:207], 0
	v_mfma_f32_16x16x128_f8f6f4 v[112:115], v[0:7], v[200:207], 0
	v_mfma_f32_16x16x128_f8f6f4 v[100:103], v[8:15], v[208:215], 0
	v_mfma_f32_16x16x128_f8f6f4 v[96:99], v[0:7], v[208:215], 0
	s_setprio 0
	s_barrier
	s_add_i32 s24, s59, s14
	s_mov_b32 m0, s24
	ds_read_b128 v[184:187], v199 offset:16384
	ds_read_b128 v[188:191], v199 offset:17408
	ds_read_b128 v[200:203], v199 offset:18432
	ds_read_b128 v[204:207], v199 offset:19456
	ds_read_b128 v[208:211], v199 offset:20480
	ds_read_b128 v[212:215], v199 offset:21504
	ds_read_b128 v[218:221], v199 offset:22528
	ds_read_b128 v[222:225], v199 offset:23552
	global_load_lds_dwordx4 v162, s[54:55]
	s_add_i32 m0, s24, 0x2000
	s_add_u32 s24, s54, 0xb0000
	s_addc_u32 s25, s55, 0
	s_add_i32 s36, s60, s14
	global_load_lds_dwordx4 v166, s[54:55]
	s_mov_b32 m0, s36
	s_nop 0
	global_load_lds_dwordx4 v162, s[24:25]
	s_add_i32 m0, s36, 0x2000
	s_nop 0
	global_load_lds_dwordx4 v166, s[24:25]
	s_mov_b32 m0, s15
	s_nop 0
	global_load_lds_dwordx4 v160, s[56:57]
	s_mov_b32 m0, s21
	s_nop 0
	global_load_lds_dwordx4 v164, s[56:57]
	s_waitcnt vmcnt(8)
	s_waitcnt lgkmcnt(0)
	s_setprio 1
	s_waitcnt lgkmcnt(0)
	v_mfma_f32_16x16x128_f8f6f4 v[92:95], v[24:31], v[184:191], 0
	v_mfma_f32_16x16x128_f8f6f4 v[88:91], v[16:23], v[184:191], 0
	v_mfma_f32_16x16x128_f8f6f4 v[76:79], v[24:31], v[200:207], 0
	v_mfma_f32_16x16x128_f8f6f4 v[72:75], v[16:23], v[200:207], 0
	v_mfma_f32_16x16x128_f8f6f4 v[60:63], v[24:31], v[208:215], 0
	v_mfma_f32_16x16x128_f8f6f4 v[56:59], v[16:23], v[208:215], 0
	v_mfma_f32_16x16x128_f8f6f4 v[44:47], v[24:31], v[218:225], 0
	v_mfma_f32_16x16x128_f8f6f4 v[40:43], v[16:23], v[218:225], 0
	s_setprio 0
	s_setprio 1
	v_mfma_f32_16x16x128_f8f6f4 v[84:87], v[8:15], v[184:191], 0
	v_mfma_f32_16x16x128_f8f6f4 v[80:83], v[0:7], v[184:191], 0
	v_mfma_f32_16x16x128_f8f6f4 v[68:71], v[8:15], v[200:207], 0
	v_mfma_f32_16x16x128_f8f6f4 v[64:67], v[0:7], v[200:207], 0
	v_mfma_f32_16x16x128_f8f6f4 v[52:55], v[8:15], v[208:215], 0
	v_mfma_f32_16x16x128_f8f6f4 v[48:51], v[0:7], v[208:215], 0
	v_mfma_f32_16x16x128_f8f6f4 v[36:39], v[8:15], v[218:225], 0
	v_mfma_f32_16x16x128_f8f6f4 v[32:35], v[0:7], v[218:225], 0
	s_setprio 0
	s_barrier
; #define PG8_STAGE(bufoff, gbase, voff) do { _Pragma("unroll") for (int _i = 0; _i < 2; ++_i) \
;         __builtin_amdgcn_global_load_lds((const unsigned*)((const char*)(gbase) + (voff)[_i]), (PG8_LAS unsigned*)(lds + (bufoff) + ldsw + _i * 8192), 16, 0, 0); } while (0)
; #define PG8_LDA(dst, b, h) do { _Pragma("unroll") for (int m = 0; m < 4; ++m) _Pragma("unroll") for (int k = 0; k < 2; ++k) dst[m][k] = *(const PG8_LAS bf16x8*)(lds + PG8_SA(b, h) + aoff + m * 2048 + k * 1024); } while (0)
; #define PG8_LDB(dst, b, h) do { _Pragma("unroll") for (int n = 0; n < 2; ++n) _Pragma("unroll") for (int k = 0; k < 2; ++k) dst[n][k] = *(const PG8_LAS bf16x8*)(lds + PG8_SB(b, h) + boff + n * 2048 + k * 1024); } while (0)
; #define PG8_WAIT_V(n) asm volatile("s_waitcnt vmcnt(" #n ")" ::: "memory")
; #define PG8_WAIT_L(n) asm volatile("s_waitcnt lgkmcnt(" #n ")" ::: "memory")
; #define PG8_BAR __builtin_amdgcn_s_barrier()
; #define PG8_SCHED __builtin_amdgcn_sched_barrier(0)
; template <class Epi, class Sched, bool ALIGN_EPI = false, bool SP2 = false, bool F8 = false>
; __device__ __forceinline__ void gemm_phase(PG8_LAS unsigned char* lds, const Gemm g, const Sched& S, const Epi& E) {
;     ...
;             PG8_LDB(B0, 0, 0); PG8_LDB(B1, 0, 1); PG8_SCHED; PG8_LDA(At, 0, 0); PG8_STAGE(PG8_SA(1, 1), a1 + hstepA, voffA);
;             PG8_WAIT_V(8); PG8_WAIT_L(0); PG8_BAR; PG8_MMA(0, 0, At, B0); PG8_MMA(0, 1, At, B1); PG8_BAR; PG8_SCHED;
;     ...
;             PG8_LDB(B0, 1, 0); PG8_LDB(B1, 1, 1); PG8_SCHED; PG8_LDA(At, 1, 0); PG8_STAGE(PG8_SA(0, 1), a2 + hstepA, voffA);
;             PG8_WAIT_V(8); PG8_WAIT_L(0); PG8_BAR; PG8_MMA(0, 0, At, B0); PG8_MMA(0, 1, At, B1); PG8_BAR; PG8_SCHED;
;             PG8_LDA(At, 1, 1); PG8_STAGE(PG8_SB(1, 0), b3, voffB); PG8_STAGE(PG8_SB(1, 1), b3 + hstep, voffB); PG8_STAGE(PG8_SA(1, 0), a3, voffA);
;             PG8_WAIT_V(8); PG8_WAIT_L(0); PG8_BAR; PG8_MMA(1, 0, At, B0); PG8_MMA(1, 1, At, B1); PG8_BAR; PG8_SCHED;
	s_add_i32 s36, 0, 0x18000
	s_add_i32 s37, 0, 0x1c000
	v_add_u32_e32 v12, s36, v195
	v_add_u32_e32 v28, s37, v195
	ds_read_b128 v[0:3], v12
	ds_read_b128 v[4:7], v12 offset:1024
	ds_read_b128 v[8:11], v12 offset:2048
	ds_read_b128 v[12:15], v12 offset:3072
	ds_read_b128 v[16:19], v28
	ds_read_b128 v[20:23], v28 offset:1024
	ds_read_b128 v[24:27], v28 offset:2048
	ds_read_b128 v[28:31], v28 offset:3072
	s_add_u32 s24, s56, 0xb0000
	s_addc_u32 s25, s57, 0
	s_mov_b32 m0, s23
	ds_read_b128 v[184:187], v199 offset:32768
	ds_read_b128 v[188:191], v199 offset:33792
	ds_read_b128 v[200:203], v199 offset:34816
	ds_read_b128 v[204:207], v199 offset:35840
	ds_read_b128 v[208:211], v199 offset:36864
	ds_read_b128 v[212:215], v199 offset:37888
	ds_read_b128 v[218:221], v199 offset:38912
	ds_read_b128 v[222:225], v199 offset:39936
	global_load_lds_dwordx4 v160, s[24:25]
	s_mov_b32 m0, s26
	s_nop 0
	global_load_lds_dwordx4 v164, s[24:25]
	s_waitcnt vmcnt(8)
	s_waitcnt lgkmcnt(0)
	s_setprio 1
	s_waitcnt lgkmcnt(0)
	v_mfma_f32_16x16x128_f8f6f4 v[156:159], v[0:7], v[184:191], v[156:159]
	v_mfma_f32_16x16x128_f8f6f4 v[152:155], v[8:15], v[184:191], v[152:155]
	v_mfma_f32_16x16x128_f8f6f4 v[140:143], v[0:7], v[200:207], v[140:143]
	v_mfma_f32_16x16x128_f8f6f4 v[136:139], v[8:15], v[200:207], v[136:139]
	v_mfma_f32_16x16x128_f8f6f4 v[124:127], v[0:7], v[208:215], v[124:127]
	v_mfma_f32_16x16x128_f8f6f4 v[120:123], v[8:15], v[208:215], v[120:123]
	v_mfma_f32_16x16x128_f8f6f4 v[108:111], v[0:7], v[218:225], v[108:111]
	v_mfma_f32_16x16x128_f8f6f4 v[104:107], v[8:15], v[218:225], v[104:107]
	s_setprio 0
	s_setprio 1
	v_mfma_f32_16x16x128_f8f6f4 v[148:151], v[16:23], v[184:191], v[148:151]
	v_mfma_f32_16x16x128_f8f6f4 v[144:147], v[24:31], v[184:191], v[144:147]
	v_mfma_f32_16x16x128_f8f6f4 v[132:135], v[16:23], v[200:207], v[132:135]
	v_mfma_f32_16x16x128_f8f6f4 v[128:131], v[24:31], v[200:207], v[128:131]
	v_mfma_f32_16x16x128_f8f6f4 v[116:119], v[16:23], v[208:215], v[116:119]
	v_mfma_f32_16x16x128_f8f6f4 v[112:115], v[24:31], v[208:215], v[112:115]
	v_mfma_f32_16x16x128_f8f6f4 v[100:103], v[16:23], v[218:225], v[100:103]
	v_mfma_f32_16x16x128_f8f6f4 v[96:99], v[24:31], v[218:225], v[96:99]
	s_setprio 0
	s_barrier
	s_add_i32 s24, s36, s14
	s_mov_b32 m0, s24
	ds_read_b128 v[184:187], v199 offset:49152
	ds_read_b128 v[188:191], v199 offset:50176
	ds_read_b128 v[200:203], v199 offset:51200
	ds_read_b128 v[204:207], v199 offset:52224
	ds_read_b128 v[208:211], v199 offset:53248
	ds_read_b128 v[212:215], v199 offset:54272
	ds_read_b128 v[218:221], v199 offset:55296
	ds_read_b128 v[222:225], v199 offset:56320
	s_add_u32 s98, s54, 0x80
	s_addc_u32 s99, s55, 0
	global_load_lds_dwordx4 v162, s[98:99]
	s_add_i32 m0, s24, 0x2000
	s_add_u32 s24, s54, 0xb0080
	s_addc_u32 s25, s55, 0
	s_add_i32 s36, s37, s14
	s_add_u32 s100, s54, 0x80
	s_addc_u32 s101, s55, 0
	global_load_lds_dwordx4 v166, s[100:101]
	s_mov_b32 m0, s36
	s_nop 0
	global_load_lds_dwordx4 v162, s[24:25]
	s_add_i32 m0, s36, 0x2000
	s_nop 0
	global_load_lds_dwordx4 v166, s[24:25]
	s_mov_b32 m0, s33
	s_nop 0
	s_add_u32 s98, s56, 0x80
	s_addc_u32 s99, s57, 0
	global_load_lds_dwordx4 v160, s[98:99]
	s_mov_b32 m0, s43
	s_nop 0
	s_add_u32 s100, s56, 0x80
	s_addc_u32 s101, s57, 0
	global_load_lds_dwordx4 v164, s[100:101]
	s_waitcnt vmcnt(8)
	s_waitcnt lgkmcnt(0)
	s_setprio 1
	s_waitcnt lgkmcnt(0)
	v_mfma_f32_16x16x128_f8f6f4 v[92:95], v[0:7], v[184:191], v[92:95]
	v_mfma_f32_16x16x128_f8f6f4 v[88:91], v[8:15], v[184:191], v[88:91]
	v_mfma_f32_16x16x128_f8f6f4 v[76:79], v[0:7], v[200:207], v[76:79]
	v_mfma_f32_16x16x128_f8f6f4 v[72:75], v[8:15], v[200:207], v[72:75]
	v_mfma_f32_16x16x128_f8f6f4 v[60:63], v[0:7], v[208:215], v[60:63]
	v_mfma_f32_16x16x128_f8f6f4 v[56:59], v[8:15], v[208:215], v[56:59]
	v_mfma_f32_16x16x128_f8f6f4 v[44:47], v[0:7], v[218:225], v[44:47]
	v_mfma_f32_16x16x128_f8f6f4 v[40:43], v[8:15], v[218:225], v[40:43]
	s_setprio 0
	s_setprio 1
	v_mfma_f32_16x16x128_f8f6f4 v[84:87], v[16:23], v[184:191], v[84:87]
	v_mfma_f32_16x16x128_f8f6f4 v[80:83], v[24:31], v[184:191], v[80:83]
	v_mfma_f32_16x16x128_f8f6f4 v[68:71], v[16:23], v[200:207], v[68:71]
	v_mfma_f32_16x16x128_f8f6f4 v[64:67], v[24:31], v[200:207], v[64:67]
	v_mfma_f32_16x16x128_f8f6f4 v[52:55], v[16:23], v[208:215], v[52:55]
	v_mfma_f32_16x16x128_f8f6f4 v[48:51], v[24:31], v[208:215], v[48:51]
	v_mfma_f32_16x16x128_f8f6f4 v[36:39], v[16:23], v[218:225], v[36:39]
	v_mfma_f32_16x16x128_f8f6f4 v[32:35], v[24:31], v[218:225], v[32:35]
	s_setprio 0
	s_barrier
	s_add_i32 s67, s67, 2
	s_add_u32 s52, s52, 0x100
	s_addc_u32 s53, s53, 0
	s_add_u32 s65, s65, 0x100
	s_addc_u32 s66, s66, 0
	s_cmp_gt_u32 s67, 41
	s_branch .LBB0_1000
.Lk4_Yz:
	ds_read_b128 v[24:27], v197
	ds_read_b128 v[28:31], v197 offset:1024
	ds_read_b128 v[16:19], v197 offset:2048
	ds_read_b128 v[20:23], v197 offset:3072
	ds_read_b128 v[8:11], v198
	ds_read_b128 v[12:15], v198 offset:1024
	ds_read_b128 v[0:3], v198 offset:2048
	ds_read_b128 v[4:7], v198 offset:3072
	s_add_u32 s24, s52, 0xfff50080
	s_addc_u32 s25, s53, -1
	s_cmp_eq_u32 s67, 40
	s_cselect_b32 s57, s7, s25
	s_cselect_b32 s56, s6, s24
	s_cselect_b32 s55, s51, s66
	s_cselect_b32 s54, s50, s65
	s_add_i32 m0, s15, 0xc000
	ds_read_b128 v[176:179], v199
	ds_read_b128 v[180:183], v199 offset:1024
	ds_read_b128 v[184:187], v199 offset:2048
	ds_read_b128 v[188:191], v199 offset:3072
	ds_read_b128 v[200:203], v199 offset:4096
	ds_read_b128 v[204:207], v199 offset:5120
	ds_read_b128 v[208:211], v199 offset:6144
	ds_read_b128 v[212:215], v199 offset:7168
	global_load_lds_dwordx4 v168, s[52:53]
	s_add_i32 m0, s15, 0xe000
	s_nop 0
	global_load_lds_dwordx4 v170, s[52:53]
	s_waitcnt vmcnt(8)
	s_waitcnt lgkmcnt(0)
	s_barrier
	s_setprio 3
	s_waitcnt lgkmcnt(0)
	v_mfma_f32_16x16x128_f8f6f4 v[156:159], v[24:31], v[176:183], 0
	v_mfma_f32_16x16x128_f8f6f4 v[152:155], v[16:23], v[176:183], 0
	v_mfma_f32_16x16x128_f8f6f4 v[140:143], v[24:31], v[184:191], 0
	v_mfma_f32_16x16x128_f8f6f4 v[136:139], v[16:23], v[184:191], 0
	v_mfma_f32_16x16x128_f8f6f4 v[124:127], v[24:31], v[200:207], 0
	v_mfma_f32_16x16x128_f8f6f4 v[120:123], v[16:23], v[200:207], 0
	v_mfma_f32_16x16x128_f8f6f4 v[108:111], v[24:31], v[208:215], 0
	v_mfma_f32_16x16x128_f8f6f4 v[104:107], v[16:23], v[208:215], 0


; #define PG8_STAGE(bufoff, gbase, voff) do { _Pragma("unroll") for (int _i = 0; _i < 2; ++_i) \
;         __builtin_amdgcn_global_load_lds((const unsigned*)((const char*)(gbase) + (voff)[_i]), (PG8_LAS unsigned*)(lds + (bufoff) + ldsw + _i * 8192), 16, 0, 0); } while (0)
; #define PG8_LDA(dst, b, h) do { _Pragma("unroll") for (int m = 0; m < 4; ++m) _Pragma("unroll") for (int k = 0; k < 2; ++k) dst[m][k] = *(const PG8_LAS bf16x8*)(lds + PG8_SA(b, h) + aoff + m * 2048 + k * 1024); } while (0)
; #define PG8_WAIT_V(n) asm volatile("s_waitcnt vmcnt(" #n ")" ::: "memory")
; #define PG8_WAIT_L(n) asm volatile("s_waitcnt lgkmcnt(" #n ")" ::: "memory")
; #define PG8_BAR __builtin_amdgcn_s_barrier()
; #define PG8_SCHED __builtin_amdgcn_sched_barrier(0)
; template <class Epi, class Sched, bool ALIGN_EPI = false, bool SP2 = false, bool F8 = false>
; __device__ __forceinline__ void gemm_phase(PG8_LAS unsigned char* lds, const Gemm g, const Sched& S, const Epi& E) {
;     ...
;             PG8_WAIT_V(8); PG8_WAIT_L(0); PG8_BAR; PG8_MMA(0, 0, At, B0); PG8_MMA(0, 1, At, B1); PG8_BAR; PG8_SCHED;
;             PG8_LDA(At, 0, 1); PG8_STAGE(PG8_SB(0, 0), b2, voffB); PG8_STAGE(PG8_SB(0, 1), b2 + hstep, voffB); PG8_STAGE(PG8_SA(0, 0), a2, voffA);
;             PG8_WAIT_V(8); PG8_WAIT_L(0); PG8_BAR; PG8_MMA(1, 0, At, B0); PG8_MMA(1, 1, At, B1); PG8_BAR; PG8_SCHED;
	v_mfma_f32_16x16x128_f8f6f4 v[148:151], v[8:15], v[176:183], 0
	v_mfma_f32_16x16x128_f8f6f4 v[144:147], v[0:7], v[176:183], 0
	v_mfma_f32_16x16x128_f8f6f4 v[132:135], v[8:15], v[184:191], 0
	v_mfma_f32_16x16x128_f8f6f4 v[128:131], v[0:7], v[184:191], 0
	v_mfma_f32_16x16x128_f8f6f4 v[116:119], v[8:15], v[200:207], 0
	v_mfma_f32_16x16x128_f8f6f4 v[112:115], v[0:7], v[200:207], 0
	v_mfma_f32_16x16x128_f8f6f4 v[100:103], v[8:15], v[208:215], 0
	v_mfma_f32_16x16x128_f8f6f4 v[96:99], v[0:7], v[208:215], 0
	s_setprio 0
	s_add_i32 s24, s59, s14
	s_mov_b32 m0, s24
	ds_read_b128 v[184:187], v199 offset:16384
	ds_read_b128 v[188:191], v199 offset:17408
	ds_read_b128 v[200:203], v199 offset:18432
	ds_read_b128 v[204:207], v199 offset:19456
	ds_read_b128 v[208:211], v199 offset:20480
	ds_read_b128 v[212:215], v199 offset:21504
	ds_read_b128 v[218:221], v199 offset:22528
	ds_read_b128 v[222:225], v199 offset:23552
	global_load_lds_dwordx4 v162, s[54:55]
	s_add_i32 m0, s24, 0x2000
	s_add_u32 s24, s54, 0xb0000
	s_addc_u32 s25, s55, 0
	s_add_i32 s36, s60, s14
	global_load_lds_dwordx4 v166, s[54:55]
	s_mov_b32 m0, s36
	s_nop 0
	global_load_lds_dwordx4 v162, s[24:25]
	s_add_i32 m0, s36, 0x2000
	s_nop 0
	global_load_lds_dwordx4 v166, s[24:25]
	s_mov_b32 m0, s15
	s_nop 0
	global_load_lds_dwordx4 v160, s[56:57]
	s_mov_b32 m0, s21
	s_nop 0
	global_load_lds_dwordx4 v164, s[56:57]
	s_waitcnt vmcnt(8)
	s_waitcnt lgkmcnt(0)
	s_barrier
	s_setprio 3
	s_waitcnt lgkmcnt(0)
	v_mfma_f32_16x16x128_f8f6f4 v[92:95], v[24:31], v[184:191], 0
	v_mfma_f32_16x16x128_f8f6f4 v[88:91], v[16:23], v[184:191], 0
	v_mfma_f32_16x16x128_f8f6f4 v[76:79], v[24:31], v[200:207], 0
	v_mfma_f32_16x16x128_f8f6f4 v[72:75], v[16:23], v[200:207], 0
	v_mfma_f32_16x16x128_f8f6f4 v[60:63], v[24:31], v[208:215], 0
	v_mfma_f32_16x16x128_f8f6f4 v[56:59], v[16:23], v[208:215], 0
	v_mfma_f32_16x16x128_f8f6f4 v[44:47], v[24:31], v[218:225], 0
	v_mfma_f32_16x16x128_f8f6f4 v[40:43], v[16:23], v[218:225], 0


; #define PG8_STAGE(bufoff, gbase, voff) do { _Pragma("unroll") for (int _i = 0; _i < 2; ++_i) \
;         __builtin_amdgcn_global_load_lds((const unsigned*)((const char*)(gbase) + (voff)[_i]), (PG8_LAS unsigned*)(lds + (bufoff) + ldsw + _i * 8192), 16, 0, 0); } while (0)
; #define PG8_LDA(dst, b, h) do { _Pragma("unroll") for (int m = 0; m < 4; ++m) _Pragma("unroll") for (int k = 0; k < 2; ++k) dst[m][k] = *(const PG8_LAS bf16x8*)(lds + PG8_SA(b, h) + aoff + m * 2048 + k * 1024); } while (0)
; #define PG8_LDB(dst, b, h) do { _Pragma("unroll") for (int n = 0; n < 2; ++n) _Pragma("unroll") for (int k = 0; k < 2; ++k) dst[n][k] = *(const PG8_LAS bf16x8*)(lds + PG8_SB(b, h) + boff + n * 2048 + k * 1024); } while (0)
; #define PG8_WAIT_V(n) asm volatile("s_waitcnt vmcnt(" #n ")" ::: "memory")
; #define PG8_WAIT_L(n) asm volatile("s_waitcnt lgkmcnt(" #n ")" ::: "memory")
; #define PG8_BAR __builtin_amdgcn_s_barrier()
; #define PG8_SCHED __builtin_amdgcn_sched_barrier(0)
; template <class Epi, class Sched, bool ALIGN_EPI = false, bool SP2 = false, bool F8 = false>
; __device__ __forceinline__ void gemm_phase(PG8_LAS unsigned char* lds, const Gemm g, const Sched& S, const Epi& E) {
;     ...
;             PG8_WAIT_V(8); PG8_WAIT_L(0); PG8_BAR; PG8_MMA(1, 0, At, B0); PG8_MMA(1, 1, At, B1); PG8_BAR; PG8_SCHED;
;             PG8_LDB(B0, 1, 0); PG8_LDB(B1, 1, 1); PG8_SCHED; PG8_LDA(At, 1, 0); PG8_STAGE(PG8_SA(0, 1), a2 + hstepA, voffA);
;             PG8_WAIT_V(8); PG8_WAIT_L(0); PG8_BAR; PG8_MMA(0, 0, At, B0); PG8_MMA(0, 1, At, B1); PG8_BAR; PG8_SCHED;
	v_mfma_f32_16x16x128_f8f6f4 v[84:87], v[8:15], v[184:191], 0
	v_mfma_f32_16x16x128_f8f6f4 v[80:83], v[0:7], v[184:191], 0
	v_mfma_f32_16x16x128_f8f6f4 v[68:71], v[8:15], v[200:207], 0
	v_mfma_f32_16x16x128_f8f6f4 v[64:67], v[0:7], v[200:207], 0
	v_mfma_f32_16x16x128_f8f6f4 v[52:55], v[8:15], v[208:215], 0
	v_mfma_f32_16x16x128_f8f6f4 v[48:51], v[0:7], v[208:215], 0
	v_mfma_f32_16x16x128_f8f6f4 v[36:39], v[8:15], v[218:225], 0
	v_mfma_f32_16x16x128_f8f6f4 v[32:35], v[0:7], v[218:225], 0
	s_setprio 0
	s_add_i32 s36, 0, 0x18000
	s_add_i32 s37, 0, 0x1c000
	v_add_u32_e32 v12, s36, v195
	v_add_u32_e32 v28, s37, v195
	ds_read_b128 v[0:3], v12
	ds_read_b128 v[4:7], v12 offset:1024
	ds_read_b128 v[8:11], v12 offset:2048
	ds_read_b128 v[12:15], v12 offset:3072
	ds_read_b128 v[16:19], v28
	ds_read_b128 v[20:23], v28 offset:1024
	ds_read_b128 v[24:27], v28 offset:2048
	ds_read_b128 v[28:31], v28 offset:3072
	s_add_u32 s24, s56, 0xb0000
	s_addc_u32 s25, s57, 0
	s_mov_b32 m0, s23
	ds_read_b128 v[184:187], v199 offset:32768
	ds_read_b128 v[188:191], v199 offset:33792
	ds_read_b128 v[200:203], v199 offset:34816
	ds_read_b128 v[204:207], v199 offset:35840
	ds_read_b128 v[208:211], v199 offset:36864
	ds_read_b128 v[212:215], v199 offset:37888
	ds_read_b128 v[218:221], v199 offset:38912
	ds_read_b128 v[222:225], v199 offset:39936
	global_load_lds_dwordx4 v160, s[24:25]
	s_mov_b32 m0, s26
	s_nop 0
	global_load_lds_dwordx4 v164, s[24:25]
	s_waitcnt vmcnt(8)
	s_waitcnt lgkmcnt(0)
	s_barrier
	s_setprio 3
	s_waitcnt lgkmcnt(0)
	v_mfma_f32_16x16x128_f8f6f4 v[156:159], v[0:7], v[184:191], v[156:159]
	v_mfma_f32_16x16x128_f8f6f4 v[152:155], v[8:15], v[184:191], v[152:155]
	v_mfma_f32_16x16x128_f8f6f4 v[140:143], v[0:7], v[200:207], v[140:143]
	v_mfma_f32_16x16x128_f8f6f4 v[136:139], v[8:15], v[200:207], v[136:139]
	v_mfma_f32_16x16x128_f8f6f4 v[124:127], v[0:7], v[208:215], v[124:127]
	v_mfma_f32_16x16x128_f8f6f4 v[120:123], v[8:15], v[208:215], v[120:123]
	v_mfma_f32_16x16x128_f8f6f4 v[108:111], v[0:7], v[218:225], v[108:111]
	v_mfma_f32_16x16x128_f8f6f4 v[104:107], v[8:15], v[218:225], v[104:107]


; #define PG8_STAGE(bufoff, gbase, voff) do { _Pragma("unroll") for (int _i = 0; _i < 2; ++_i) \
;         __builtin_amdgcn_global_load_lds((const unsigned*)((const char*)(gbase) + (voff)[_i]), (PG8_LAS unsigned*)(lds + (bufoff) + ldsw + _i * 8192), 16, 0, 0); } while (0)
; #define PG8_LDA(dst, b, h) do { _Pragma("unroll") for (int m = 0; m < 4; ++m) _Pragma("unroll") for (int k = 0; k < 2; ++k) dst[m][k] = *(const PG8_LAS bf16x8*)(lds + PG8_SA(b, h) + aoff + m * 2048 + k * 1024); } while (0)
; #define PG8_WAIT_V(n) asm volatile("s_waitcnt vmcnt(" #n ")" ::: "memory")
; #define PG8_WAIT_L(n) asm volatile("s_waitcnt lgkmcnt(" #n ")" ::: "memory")
; #define PG8_BAR __builtin_amdgcn_s_barrier()
; #define PG8_SCHED __builtin_amdgcn_sched_barrier(0)
; template <class Epi, class Sched, bool ALIGN_EPI = false, bool SP2 = false, bool F8 = false>
; __device__ __forceinline__ void gemm_phase(PG8_LAS unsigned char* lds, const Gemm g, const Sched& S, const Epi& E) {
;     ...
;             PG8_WAIT_V(8); PG8_WAIT_L(0); PG8_BAR; PG8_MMA(0, 0, At, B0); PG8_MMA(0, 1, At, B1); PG8_BAR; PG8_SCHED;
;             PG8_LDA(At, 1, 1); PG8_STAGE(PG8_SB(1, 0), b3, voffB); PG8_STAGE(PG8_SB(1, 1), b3 + hstep, voffB); PG8_STAGE(PG8_SA(1, 0), a3, voffA);
;             PG8_WAIT_V(8); PG8_WAIT_L(0); PG8_BAR; PG8_MMA(1, 0, At, B0); PG8_MMA(1, 1, At, B1); PG8_BAR; PG8_SCHED;
	v_mfma_f32_16x16x128_f8f6f4 v[148:151], v[16:23], v[184:191], v[148:151]
	v_mfma_f32_16x16x128_f8f6f4 v[144:147], v[24:31], v[184:191], v[144:147]
	v_mfma_f32_16x16x128_f8f6f4 v[132:135], v[16:23], v[200:207], v[132:135]
	v_mfma_f32_16x16x128_f8f6f4 v[128:131], v[24:31], v[200:207], v[128:131]
	v_mfma_f32_16x16x128_f8f6f4 v[116:119], v[16:23], v[208:215], v[116:119]
	v_mfma_f32_16x16x128_f8f6f4 v[112:115], v[24:31], v[208:215], v[112:115]
	v_mfma_f32_16x16x128_f8f6f4 v[100:103], v[16:23], v[218:225], v[100:103]
	v_mfma_f32_16x16x128_f8f6f4 v[96:99], v[24:31], v[218:225], v[96:99]
	s_setprio 0
	s_add_i32 s24, s36, s14
	s_mov_b32 m0, s24
	ds_read_b128 v[184:187], v199 offset:49152
	ds_read_b128 v[188:191], v199 offset:50176
	ds_read_b128 v[200:203], v199 offset:51200
	ds_read_b128 v[204:207], v199 offset:52224
	ds_read_b128 v[208:211], v199 offset:53248
	ds_read_b128 v[212:215], v199 offset:54272
	ds_read_b128 v[218:221], v199 offset:55296
	ds_read_b128 v[222:225], v199 offset:56320
	s_add_u32 s98, s54, 0x80
	s_addc_u32 s99, s55, 0
	global_load_lds_dwordx4 v162, s[98:99]
	s_add_i32 m0, s24, 0x2000
	s_add_u32 s24, s54, 0xb0080
	s_addc_u32 s25, s55, 0
	s_add_i32 s36, s37, s14
	s_add_u32 s100, s54, 0x80
	s_addc_u32 s101, s55, 0
	global_load_lds_dwordx4 v166, s[100:101]
	s_mov_b32 m0, s36
	s_nop 0
	global_load_lds_dwordx4 v162, s[24:25]
	s_add_i32 m0, s36, 0x2000
	s_nop 0
	global_load_lds_dwordx4 v166, s[24:25]
	s_mov_b32 m0, s33
	s_nop 0
	s_add_u32 s98, s56, 0x80
	s_addc_u32 s99, s57, 0
	global_load_lds_dwordx4 v160, s[98:99]
	s_mov_b32 m0, s43
	s_nop 0
	s_add_u32 s100, s56, 0x80
	s_addc_u32 s101, s57, 0
	global_load_lds_dwordx4 v164, s[100:101]
	s_waitcnt vmcnt(8)
	s_waitcnt lgkmcnt(0)
	s_barrier
	s_setprio 3
	s_waitcnt lgkmcnt(0)
	v_mfma_f32_16x16x128_f8f6f4 v[92:95], v[0:7], v[184:191], v[92:95]
	v_mfma_f32_16x16x128_f8f6f4 v[88:91], v[8:15], v[184:191], v[88:91]
	v_mfma_f32_16x16x128_f8f6f4 v[76:79], v[0:7], v[200:207], v[76:79]
	v_mfma_f32_16x16x128_f8f6f4 v[72:75], v[8:15], v[200:207], v[72:75]
	v_mfma_f32_16x16x128_f8f6f4 v[60:63], v[0:7], v[208:215], v[60:63]
	v_mfma_f32_16x16x128_f8f6f4 v[56:59], v[8:15], v[208:215], v[56:59]
	v_mfma_f32_16x16x128_f8f6f4 v[44:47], v[0:7], v[218:225], v[44:47]
	v_mfma_f32_16x16x128_f8f6f4 v[40:43], v[8:15], v[218:225], v[40:43]


; #define PG8_WAIT_V(n) asm volatile("s_waitcnt vmcnt(" #n ")" ::: "memory")
; #define PG8_WAIT_L(n) asm volatile("s_waitcnt lgkmcnt(" #n ")" ::: "memory")
; #define PG8_BAR __builtin_amdgcn_s_barrier()
; #define PG8_SCHED __builtin_amdgcn_sched_barrier(0)
; template <class Epi, class Sched, bool ALIGN_EPI = false, bool SP2 = false, bool F8 = false>
; __device__ __forceinline__ void gemm_phase(PG8_LAS unsigned char* lds, const Gemm g, const Sched& S, const Epi& E) {
;     ...
;         for (int t = 0; t < nt; t += 2) {
;             const bool last = (t == nt - 2);
;             const char* a1 = cA + (size_t)(t + 1) * kstep;
;             const char* a2 = last ? nA : cA + (size_t)(t + 2) * kstep; const char* b2 = last ? nB : cB + (size_t)(t + 2) * kstep;
;     ...
;             PG8_WAIT_V(8); PG8_WAIT_L(0); PG8_BAR; PG8_MMA(1, 0, At, B0); PG8_MMA(1, 1, At, B1); PG8_BAR; PG8_SCHED;
	v_mfma_f32_16x16x128_f8f6f4 v[84:87], v[16:23], v[184:191], v[84:87]
	v_mfma_f32_16x16x128_f8f6f4 v[80:83], v[24:31], v[184:191], v[80:83]
	v_mfma_f32_16x16x128_f8f6f4 v[68:71], v[16:23], v[200:207], v[68:71]
	v_mfma_f32_16x16x128_f8f6f4 v[64:67], v[24:31], v[200:207], v[64:67]
	v_mfma_f32_16x16x128_f8f6f4 v[52:55], v[16:23], v[208:215], v[52:55]
	v_mfma_f32_16x16x128_f8f6f4 v[48:51], v[24:31], v[208:215], v[48:51]
	v_mfma_f32_16x16x128_f8f6f4 v[36:39], v[16:23], v[218:225], v[36:39]
	v_mfma_f32_16x16x128_f8f6f4 v[32:35], v[24:31], v[218:225], v[32:35]
	s_setprio 0
	s_add_i32 s67, s67, 2
	s_add_u32 s52, s52, 0x100
	s_addc_u32 s53, s53, 0
	s_add_u32 s65, s65, 0x100
	s_addc_u32 s66, s66, 0
	s_cmp_gt_u32 s67, 41
	s_branch .Lk4_Y
